# loop-edge rotation: diff-attention stage loop computes the next stage's DMA addresses and counters before the barrier and issues K reads first after it; GEMM K-loop pointer/counter updates moved above
# baseline (speedup 1.0000x reference)
; #define PG8_STAGE(bufoff, gbase, voff) do { _Pragma("unroll") for (int _i = 0; _i < 2; ++_i) \
;         __builtin_amdgcn_global_load_lds((const unsigned*)((const char*)(gbase) + (voff)[_i]), (PG8_LAS unsigned*)(lds + (bufoff) + ldsw + _i * 8192), 16, 0, 0); } while (0)
; #define PG8_LDA(dst, b, h) do { _Pragma("unroll") for (int m = 0; m < 4; ++m) _Pragma("unroll") for (int k = 0; k < 2; ++k) dst[m][k] = *(const PG8_LAS bf16x8*)(lds + PG8_SA(b, h) + aoff + m * 2048 + k * 1024); } while (0)
; #define PG8_LDB(dst, b, h) do { _Pragma("unroll") for (int n = 0; n < 2; ++n) _Pragma("unroll") for (int k = 0; k < 2; ++k) dst[n][k] = *(const PG8_LAS bf16x8*)(lds + PG8_SB(b, h) + boff + n * 2048 + k * 1024); } while (0)
; #define PG8_MMA(ai, bj, At, Bt) do { __builtin_amdgcn_s_setprio(1); _Pragma("unroll") for (int m = 0; m < 4; ++m) _Pragma("unroll") for (int n = 0; n < 2; ++n) _Pragma("unroll") for (int k = 0; k < 2; ++k) \
;         acc[ai][bj][m][n] = __builtin_amdgcn_mfma_f32_16x16x32_bf16(Bt[n][k], At[m][k], acc[ai][bj][m][n], 0, 0, 0); __builtin_amdgcn_s_setprio(0); } while (0)
; #define PG8_WAIT_V(n) asm volatile("s_waitcnt vmcnt(" #n ")" ::: "memory")
; #define PG8_WAIT_L(n) asm volatile("s_waitcnt lgkmcnt(" #n ")" ::: "memory")
; #define PG8_BAR __builtin_amdgcn_s_barrier()
; #define PG8_SCHED __builtin_amdgcn_sched_barrier(0)
; template <class Epi, class Sched, bool ALIGN_EPI = false, bool SP2 = false>
; __device__ __forceinline__ void gemm_phase(PG8_LAS unsigned char* lds, const Gemm g, const Sched& S, const Epi& E) {
;     ...
;             PG8_LDB(B0, 0, 0); PG8_LDB(B1, 0, 1); PG8_SCHED; PG8_LDA(At, 0, 0); PG8_STAGE(PG8_SA(1, 1), a1 + hstep, voffA);
;             PG8_WAIT_V(8); PG8_WAIT_L(0); PG8_BAR; PG8_MMA(0, 0, At, B0); PG8_MMA(0, 1, At, B1); PG8_BAR; PG8_SCHED;
;             PG8_LDA(At, 0, 1); PG8_STAGE(PG8_SB(0, 0), b2, voffB); PG8_STAGE(PG8_SB(0, 1), b2 + hstep, voffB); PG8_STAGE(PG8_SA(0, 0), a2, voffA);
;             PG8_WAIT_V(8); PG8_WAIT_L(0); PG8_BAR; PG8_MMA(1, 0, At, B0); PG8_MMA(1, 1, At, B1); PG8_BAR; PG8_SCHED;
.LBB0_163:
	ds_read_b128 v[128:131], v188
	ds_read_b128 v[132:135], v189
	ds_read_b128 v[136:139], v190
	ds_read_b128 v[140:143], v191
	ds_read_b128 v[144:147], v192
	ds_read_b128 v[148:151], v193
	ds_read_b128 v[172:175], v194
	ds_read_b128 v[176:179], v195
	s_add_u32 s44, s42, 0xfffc0080
	s_addc_u32 s45, s43, -1
	s_cmp_eq_u32 s74, 12
	s_cselect_b32 s47, s9, s45
	s_cselect_b32 s46, s11, s44
	s_cselect_b32 s45, s29, s73
	s_cselect_b32 s44, s31, s72
	s_mov_b32 m0, s68
	v_lshl_add_u64 v[236:237], s[42:43], 0, v[166:167]
	ds_read_b128 v[180:183], v186
	ds_read_b128 v[208:211], v186 offset:1024
	ds_read_b128 v[212:215], v186 offset:2048
	ds_read_b128 v[216:219], v186 offset:3072
	ds_read_b128 v[220:223], v186 offset:4096
	ds_read_b128 v[224:227], v186 offset:5120
	ds_read_b128 v[228:231], v186 offset:6144
	ds_read_b128 v[232:235], v186 offset:7168
	global_load_lds_dwordx4 v[236:237], off
	v_lshl_add_u64 v[236:237], s[42:43], 0, v[164:165]
	s_mov_b32 m0, s69
	s_nop 0
	global_load_lds_dwordx4 v[236:237], off
	s_waitcnt vmcnt(8)
	s_waitcnt lgkmcnt(0)
	s_barrier
	s_waitcnt lgkmcnt(0)
	v_mfma_f32_16x16x32_bf16 v[124:127], v[128:131], v[180:183], v[124:127]
	v_mfma_f32_16x16x32_bf16 v[120:123], v[136:139], v[180:183], v[120:123]
	v_mfma_f32_16x16x32_bf16 v[108:111], v[128:131], v[212:215], v[108:111]
	v_mfma_f32_16x16x32_bf16 v[104:107], v[136:139], v[212:215], v[104:107]
	v_mfma_f32_16x16x32_bf16 v[92:95], v[128:131], v[220:223], v[92:95]
	v_mfma_f32_16x16x32_bf16 v[88:91], v[136:139], v[220:223], v[88:91]
	v_mfma_f32_16x16x32_bf16 v[76:79], v[128:131], v[228:231], v[76:79]
	v_mfma_f32_16x16x32_bf16 v[72:75], v[136:139], v[228:231], v[72:75]
	v_mfma_f32_16x16x32_bf16 v[124:127], v[132:135], v[208:211], v[124:127]
	v_mfma_f32_16x16x32_bf16 v[120:123], v[140:143], v[208:211], v[120:123]
	v_mfma_f32_16x16x32_bf16 v[108:111], v[132:135], v[216:219], v[108:111]
	v_mfma_f32_16x16x32_bf16 v[104:107], v[140:143], v[216:219], v[104:107]
	v_mfma_f32_16x16x32_bf16 v[92:95], v[132:135], v[224:227], v[92:95]
	v_mfma_f32_16x16x32_bf16 v[88:91], v[140:143], v[224:227], v[88:91]
	v_mfma_f32_16x16x32_bf16 v[76:79], v[132:135], v[232:235], v[76:79]
	v_mfma_f32_16x16x32_bf16 v[72:75], v[140:143], v[232:235], v[72:75]
	v_mfma_f32_16x16x32_bf16 v[116:119], v[144:147], v[180:183], v[116:119]
	v_mfma_f32_16x16x32_bf16 v[112:115], v[172:175], v[180:183], v[112:115]
	v_mfma_f32_16x16x32_bf16 v[100:103], v[144:147], v[212:215], v[100:103]
	v_mfma_f32_16x16x32_bf16 v[96:99], v[172:175], v[212:215], v[96:99]
	v_mfma_f32_16x16x32_bf16 v[84:87], v[144:147], v[220:223], v[84:87]
	v_mfma_f32_16x16x32_bf16 v[80:83], v[172:175], v[220:223], v[80:83]
	v_mfma_f32_16x16x32_bf16 v[68:71], v[144:147], v[228:231], v[68:71]
	v_mfma_f32_16x16x32_bf16 v[64:67], v[172:175], v[228:231], v[64:67]
	v_mfma_f32_16x16x32_bf16 v[116:119], v[148:151], v[208:211], v[116:119]
	v_mfma_f32_16x16x32_bf16 v[112:115], v[176:179], v[208:211], v[112:115]
	v_mfma_f32_16x16x32_bf16 v[100:103], v[148:151], v[216:219], v[100:103]
	v_mfma_f32_16x16x32_bf16 v[96:99], v[176:179], v[216:219], v[96:99]
	v_mfma_f32_16x16x32_bf16 v[84:87], v[148:151], v[224:227], v[84:87]
	v_mfma_f32_16x16x32_bf16 v[80:83], v[176:179], v[224:227], v[80:83]
	v_mfma_f32_16x16x32_bf16 v[68:71], v[148:151], v[232:235], v[68:71]
	v_mfma_f32_16x16x32_bf16 v[64:67], v[176:179], v[232:235], v[64:67]
	s_barrier
	s_mov_b32 m0, s51
	v_lshl_add_u64 v[236:237], s[44:45], 0, v[154:155]
	s_add_u32 s76, s44, 0x40000
	ds_read_b128 v[180:183], v186 offset:16384
	ds_read_b128 v[208:211], v186 offset:17408
	ds_read_b128 v[212:215], v186 offset:18432
	ds_read_b128 v[216:219], v186 offset:19456
	ds_read_b128 v[220:223], v186 offset:20480
	ds_read_b128 v[224:227], v186 offset:21504
	ds_read_b128 v[228:231], v186 offset:22528
	ds_read_b128 v[232:235], v186 offset:23552
	global_load_lds_dwordx4 v[236:237], off
	v_lshl_add_u64 v[238:239], s[44:45], 0, v[158:159]
	s_mov_b32 m0, s52
	s_addc_u32 s77, s45, 0
	global_load_lds_dwordx4 v[238:239], off
	v_lshl_add_u64 v[240:241], s[76:77], 0, v[154:155]
	s_mov_b32 m0, s53
	v_lshl_add_u64 v[242:243], s[46:47], 0, v[156:157]
	global_load_lds_dwordx4 v[240:241], off
	v_lshl_add_u64 v[240:241], s[76:77], 0, v[158:159]
	s_mov_b32 m0, s54
	s_nop 0
	global_load_lds_dwordx4 v[240:241], off
	v_lshl_add_u64 v[240:241], s[46:47], 0, v[152:153]
	s_mov_b32 m0, s50
	s_nop 0
	global_load_lds_dwordx4 v[240:241], off
	s_mov_b32 m0, s55
	s_nop 0
	global_load_lds_dwordx4 v[242:243], off
	s_waitcnt vmcnt(8)
	s_waitcnt lgkmcnt(0)
	s_barrier
	s_waitcnt lgkmcnt(0)
	v_mfma_f32_16x16x32_bf16 v[60:63], v[128:131], v[180:183], v[60:63]
	v_mfma_f32_16x16x32_bf16 v[56:59], v[136:139], v[180:183], v[56:59]
	v_mfma_f32_16x16x32_bf16 v[44:47], v[128:131], v[212:215], v[44:47]
	v_mfma_f32_16x16x32_bf16 v[40:43], v[136:139], v[212:215], v[40:43]
	v_mfma_f32_16x16x32_bf16 v[28:31], v[128:131], v[220:223], v[28:31]
	v_mfma_f32_16x16x32_bf16 v[24:27], v[136:139], v[220:223], v[24:27]
	v_mfma_f32_16x16x32_bf16 v[12:15], v[128:131], v[228:231], v[12:15]
	v_mfma_f32_16x16x32_bf16 v[8:11], v[136:139], v[228:231], v[8:11]
	v_mfma_f32_16x16x32_bf16 v[60:63], v[132:135], v[208:211], v[60:63]
	v_mfma_f32_16x16x32_bf16 v[56:59], v[140:143], v[208:211], v[56:59]
	v_mfma_f32_16x16x32_bf16 v[44:47], v[132:135], v[216:219], v[44:47]
	v_mfma_f32_16x16x32_bf16 v[40:43], v[140:143], v[216:219], v[40:43]
	v_mfma_f32_16x16x32_bf16 v[28:31], v[132:135], v[224:227], v[28:31]
	v_mfma_f32_16x16x32_bf16 v[24:27], v[140:143], v[224:227], v[24:27]
	v_mfma_f32_16x16x32_bf16 v[12:15], v[132:135], v[232:235], v[12:15]
	v_mfma_f32_16x16x32_bf16 v[8:11], v[140:143], v[232:235], v[8:11]
	v_mfma_f32_16x16x32_bf16 v[52:55], v[144:147], v[180:183], v[52:55]
	v_mfma_f32_16x16x32_bf16 v[48:51], v[172:175], v[180:183], v[48:51]
	v_mfma_f32_16x16x32_bf16 v[36:39], v[144:147], v[212:215], v[36:39]
	v_mfma_f32_16x16x32_bf16 v[32:35], v[172:175], v[212:215], v[32:35]
	v_mfma_f32_16x16x32_bf16 v[20:23], v[144:147], v[220:223], v[20:23]
	v_mfma_f32_16x16x32_bf16 v[16:19], v[172:175], v[220:223], v[16:19]
	v_mfma_f32_16x16x32_bf16 v[4:7], v[144:147], v[228:231], v[4:7]
	v_mfma_f32_16x16x32_bf16 v[0:3], v[172:175], v[228:231], v[0:3]
	v_mfma_f32_16x16x32_bf16 v[52:55], v[148:151], v[208:211], v[52:55]
	v_mfma_f32_16x16x32_bf16 v[48:51], v[176:179], v[208:211], v[48:51]
	v_mfma_f32_16x16x32_bf16 v[36:39], v[148:151], v[216:219], v[36:39]
	v_mfma_f32_16x16x32_bf16 v[32:35], v[176:179], v[216:219], v[32:35]
	v_mfma_f32_16x16x32_bf16 v[20:23], v[148:151], v[224:227], v[20:23]
	v_mfma_f32_16x16x32_bf16 v[16:19], v[176:179], v[224:227], v[16:19]
	v_mfma_f32_16x16x32_bf16 v[4:7], v[148:151], v[232:235], v[4:7]
	v_mfma_f32_16x16x32_bf16 v[0:3], v[176:179], v[232:235], v[0:3]
	s_barrier
; #define PG8_STAGE(bufoff, gbase, voff) do { _Pragma("unroll") for (int _i = 0; _i < 2; ++_i) \
;         __builtin_amdgcn_global_load_lds((const unsigned*)((const char*)(gbase) + (voff)[_i]), (PG8_LAS unsigned*)(lds + (bufoff) + ldsw + _i * 8192), 16, 0, 0); } while (0)
; #define PG8_LDA(dst, b, h) do { _Pragma("unroll") for (int m = 0; m < 4; ++m) _Pragma("unroll") for (int k = 0; k < 2; ++k) dst[m][k] = *(const PG8_LAS bf16x8*)(lds + PG8_SA(b, h) + aoff + m * 2048 + k * 1024); } while (0)
; #define PG8_LDB(dst, b, h) do { _Pragma("unroll") for (int n = 0; n < 2; ++n) _Pragma("unroll") for (int k = 0; k < 2; ++k) dst[n][k] = *(const PG8_LAS bf16x8*)(lds + PG8_SB(b, h) + boff + n * 2048 + k * 1024); } while (0)
; #define PG8_MMA(ai, bj, At, Bt) do { __builtin_amdgcn_s_setprio(1); _Pragma("unroll") for (int m = 0; m < 4; ++m) _Pragma("unroll") for (int n = 0; n < 2; ++n) _Pragma("unroll") for (int k = 0; k < 2; ++k) \
;         acc[ai][bj][m][n] = __builtin_amdgcn_mfma_f32_16x16x32_bf16(Bt[n][k], At[m][k], acc[ai][bj][m][n], 0, 0, 0); __builtin_amdgcn_s_setprio(0); } while (0)
; #define PG8_WAIT_V(n) asm volatile("s_waitcnt vmcnt(" #n ")" ::: "memory")
; #define PG8_WAIT_L(n) asm volatile("s_waitcnt lgkmcnt(" #n ")" ::: "memory")
; #define PG8_BAR __builtin_amdgcn_s_barrier()
; #define PG8_SCHED __builtin_amdgcn_sched_barrier(0)
; template <class Epi, class Sched, bool ALIGN_EPI = false, bool SP2 = false>
; __device__ __forceinline__ void gemm_phase(PG8_LAS unsigned char* lds, const Gemm g, const Sched& S, const Epi& E) {
;     ...
;         for (int t = 0; t < nt; t += 2) {
;     ...
;             PG8_LDB(B0, 1, 0); PG8_LDB(B1, 1, 1); PG8_SCHED; PG8_LDA(At, 1, 0); PG8_STAGE(PG8_SA(0, 1), a2 + hstep, voffA);
;             PG8_WAIT_V(8); PG8_WAIT_L(0); PG8_BAR; PG8_MMA(0, 0, At, B0); PG8_MMA(0, 1, At, B1); PG8_BAR; PG8_SCHED;
;             PG8_LDA(At, 1, 1); PG8_STAGE(PG8_SB(1, 0), b3, voffB); PG8_STAGE(PG8_SB(1, 1), b3 + hstep, voffB); PG8_STAGE(PG8_SA(1, 0), a3, voffA);
;             PG8_WAIT_V(8); PG8_WAIT_L(0); PG8_BAR; PG8_MMA(1, 0, At, B0); PG8_MMA(1, 1, At, B1); PG8_BAR; PG8_SCHED;
	ds_read_b128 v[128:131], v196
	ds_read_b128 v[132:135], v197
	ds_read_b128 v[136:139], v198
	ds_read_b128 v[140:143], v199
	ds_read_b128 v[144:147], v200
	ds_read_b128 v[148:151], v201
	ds_read_b128 v[172:175], v202
	ds_read_b128 v[176:179], v203
	s_add_u32 s46, s46, 0x40000
	s_addc_u32 s47, s47, 0
	s_mov_b32 m0, s56
	v_lshl_add_u64 v[244:245], s[46:47], 0, v[152:153]
	ds_read_b128 v[180:183], v186 offset:32768
	ds_read_b128 v[208:211], v186 offset:33792
	ds_read_b128 v[212:215], v186 offset:34816
	ds_read_b128 v[216:219], v186 offset:35840
	ds_read_b128 v[220:223], v186 offset:36864
	ds_read_b128 v[224:227], v186 offset:37888
	ds_read_b128 v[228:231], v186 offset:38912
	ds_read_b128 v[232:235], v186 offset:39936
	global_load_lds_dwordx4 v[244:245], off
	v_lshl_add_u64 v[244:245], s[46:47], 0, v[156:157]
	s_mov_b32 m0, s57
	s_nop 0
	global_load_lds_dwordx4 v[244:245], off
	s_waitcnt vmcnt(8)
	s_waitcnt lgkmcnt(0)
	s_barrier
	s_waitcnt lgkmcnt(0)
	v_mfma_f32_16x16x32_bf16 v[124:127], v[128:131], v[180:183], v[124:127]
	v_mfma_f32_16x16x32_bf16 v[120:123], v[136:139], v[180:183], v[120:123]
	v_mfma_f32_16x16x32_bf16 v[108:111], v[128:131], v[212:215], v[108:111]
	v_mfma_f32_16x16x32_bf16 v[104:107], v[136:139], v[212:215], v[104:107]
	v_mfma_f32_16x16x32_bf16 v[92:95], v[128:131], v[220:223], v[92:95]
	v_mfma_f32_16x16x32_bf16 v[88:91], v[136:139], v[220:223], v[88:91]
	v_mfma_f32_16x16x32_bf16 v[76:79], v[128:131], v[228:231], v[76:79]
	v_mfma_f32_16x16x32_bf16 v[72:75], v[136:139], v[228:231], v[72:75]
	v_mfma_f32_16x16x32_bf16 v[124:127], v[132:135], v[208:211], v[124:127]
	v_mfma_f32_16x16x32_bf16 v[120:123], v[140:143], v[208:211], v[120:123]
	v_mfma_f32_16x16x32_bf16 v[108:111], v[132:135], v[216:219], v[108:111]
	v_mfma_f32_16x16x32_bf16 v[104:107], v[140:143], v[216:219], v[104:107]
	v_mfma_f32_16x16x32_bf16 v[92:95], v[132:135], v[224:227], v[92:95]
	v_mfma_f32_16x16x32_bf16 v[88:91], v[140:143], v[224:227], v[88:91]
	v_mfma_f32_16x16x32_bf16 v[76:79], v[132:135], v[232:235], v[76:79]
	v_mfma_f32_16x16x32_bf16 v[72:75], v[140:143], v[232:235], v[72:75]
	v_mfma_f32_16x16x32_bf16 v[116:119], v[144:147], v[180:183], v[116:119]
	v_mfma_f32_16x16x32_bf16 v[112:115], v[172:175], v[180:183], v[112:115]
	v_mfma_f32_16x16x32_bf16 v[100:103], v[144:147], v[212:215], v[100:103]
	v_mfma_f32_16x16x32_bf16 v[96:99], v[172:175], v[212:215], v[96:99]
	v_mfma_f32_16x16x32_bf16 v[84:87], v[144:147], v[220:223], v[84:87]
	v_mfma_f32_16x16x32_bf16 v[80:83], v[172:175], v[220:223], v[80:83]
	v_mfma_f32_16x16x32_bf16 v[68:71], v[144:147], v[228:231], v[68:71]
	v_mfma_f32_16x16x32_bf16 v[64:67], v[172:175], v[228:231], v[64:67]
	v_mfma_f32_16x16x32_bf16 v[116:119], v[148:151], v[208:211], v[116:119]
	v_mfma_f32_16x16x32_bf16 v[112:115], v[176:179], v[208:211], v[112:115]
	v_mfma_f32_16x16x32_bf16 v[100:103], v[148:151], v[216:219], v[100:103]
	v_mfma_f32_16x16x32_bf16 v[96:99], v[176:179], v[216:219], v[96:99]
	v_mfma_f32_16x16x32_bf16 v[84:87], v[148:151], v[224:227], v[84:87]
	v_mfma_f32_16x16x32_bf16 v[80:83], v[176:179], v[224:227], v[80:83]
	v_mfma_f32_16x16x32_bf16 v[68:71], v[148:151], v[232:235], v[68:71]
	v_mfma_f32_16x16x32_bf16 v[64:67], v[176:179], v[232:235], v[64:67]
	s_barrier
	s_mov_b32 m0, s59
	v_lshl_add_u64 v[236:237], v[236:237], 0, s[22:23]
	s_add_u32 s44, s44, 0x40080
	ds_read_b128 v[180:183], v186 offset:49152
	ds_read_b128 v[208:211], v186 offset:50176
	ds_read_b128 v[212:215], v186 offset:51200
	ds_read_b128 v[216:219], v186 offset:52224
	ds_read_b128 v[220:223], v186 offset:53248
	ds_read_b128 v[224:227], v186 offset:54272
	ds_read_b128 v[228:231], v186 offset:55296
	ds_read_b128 v[232:235], v186 offset:56320
	global_load_lds_dwordx4 v[236:237], off
	v_lshl_add_u64 v[236:237], v[238:239], 0, s[22:23]
	s_mov_b32 m0, s60
	s_addc_u32 s45, s45, 0
	global_load_lds_dwordx4 v[236:237], off
	v_lshl_add_u64 v[236:237], s[44:45], 0, v[154:155]
	s_mov_b32 m0, s63
	s_nop 0
	global_load_lds_dwordx4 v[236:237], off
	v_lshl_add_u64 v[236:237], s[44:45], 0, v[158:159]
	s_mov_b32 m0, s64
	s_nop 0
	global_load_lds_dwordx4 v[236:237], off
	v_lshl_add_u64 v[236:237], v[240:241], 0, s[22:23]
	s_mov_b32 m0, s61
	s_nop 0
	global_load_lds_dwordx4 v[236:237], off
	v_lshl_add_u64 v[236:237], v[242:243], 0, s[22:23]
	s_mov_b32 m0, s62
	s_nop 0
	global_load_lds_dwordx4 v[236:237], off
	s_waitcnt vmcnt(8)
	s_waitcnt lgkmcnt(0)
	s_barrier
	s_waitcnt lgkmcnt(0)
	v_mfma_f32_16x16x32_bf16 v[60:63], v[128:131], v[180:183], v[60:63]
	v_mfma_f32_16x16x32_bf16 v[56:59], v[136:139], v[180:183], v[56:59]
	v_mfma_f32_16x16x32_bf16 v[44:47], v[128:131], v[212:215], v[44:47]
	v_mfma_f32_16x16x32_bf16 v[40:43], v[136:139], v[212:215], v[40:43]
	v_mfma_f32_16x16x32_bf16 v[28:31], v[128:131], v[220:223], v[28:31]
	v_mfma_f32_16x16x32_bf16 v[24:27], v[136:139], v[220:223], v[24:27]
	v_mfma_f32_16x16x32_bf16 v[12:15], v[128:131], v[228:231], v[12:15]
	v_mfma_f32_16x16x32_bf16 v[8:11], v[136:139], v[228:231], v[8:11]
	v_mfma_f32_16x16x32_bf16 v[60:63], v[132:135], v[208:211], v[60:63]
	v_mfma_f32_16x16x32_bf16 v[56:59], v[140:143], v[208:211], v[56:59]
	v_mfma_f32_16x16x32_bf16 v[44:47], v[132:135], v[216:219], v[44:47]
	v_mfma_f32_16x16x32_bf16 v[40:43], v[140:143], v[216:219], v[40:43]
	v_mfma_f32_16x16x32_bf16 v[28:31], v[132:135], v[224:227], v[28:31]
	v_mfma_f32_16x16x32_bf16 v[24:27], v[140:143], v[224:227], v[24:27]
	v_mfma_f32_16x16x32_bf16 v[12:15], v[132:135], v[232:235], v[12:15]
	v_mfma_f32_16x16x32_bf16 v[8:11], v[140:143], v[232:235], v[8:11]
	v_mfma_f32_16x16x32_bf16 v[52:55], v[144:147], v[180:183], v[52:55]
	v_mfma_f32_16x16x32_bf16 v[48:51], v[172:175], v[180:183], v[48:51]
	v_mfma_f32_16x16x32_bf16 v[36:39], v[144:147], v[212:215], v[36:39]
	v_mfma_f32_16x16x32_bf16 v[32:35], v[172:175], v[212:215], v[32:35]
	v_mfma_f32_16x16x32_bf16 v[20:23], v[144:147], v[220:223], v[20:23]
	v_mfma_f32_16x16x32_bf16 v[16:19], v[172:175], v[220:223], v[16:19]
	v_mfma_f32_16x16x32_bf16 v[4:7], v[144:147], v[228:231], v[4:7]
	v_mfma_f32_16x16x32_bf16 v[0:3], v[172:175], v[228:231], v[0:3]
	v_mfma_f32_16x16x32_bf16 v[52:55], v[148:151], v[208:211], v[52:55]
	v_mfma_f32_16x16x32_bf16 v[48:51], v[176:179], v[208:211], v[48:51]
	v_mfma_f32_16x16x32_bf16 v[36:39], v[148:151], v[216:219], v[36:39]
	v_mfma_f32_16x16x32_bf16 v[32:35], v[176:179], v[216:219], v[32:35]
	v_mfma_f32_16x16x32_bf16 v[20:23], v[148:151], v[224:227], v[20:23]
	v_mfma_f32_16x16x32_bf16 v[16:19], v[176:179], v[224:227], v[16:19]
	v_mfma_f32_16x16x32_bf16 v[4:7], v[148:151], v[232:235], v[4:7]
	v_mfma_f32_16x16x32_bf16 v[0:3], v[176:179], v[232:235], v[0:3]
	s_add_i32 s74, s74, 2
	s_add_u32 s72, s72, 0x100
	s_addc_u32 s73, s73, 0
	s_add_u32 s42, s42, 0x100
	s_addc_u32 s43, s43, 0
	s_cmp_gt_u32 s74, 13
	s_barrier
	s_cbranch_scc0 .LBB0_163
	s_and_b64 vcc, exec, s[24:25]
	s_cbranch_vccz .LBB0_166
	s_barrier

; #define LAS __attribute__((address_space(3)))
; #define DF_WAITBAR(N) asm volatile("s_waitcnt vmcnt(" #N ") lgkmcnt(0)\n\ts_barrier" ::: "memory")
; DI void diff_unit(const Args& A, const bf16_t* QKV, bf16_t* ATT, unsigned char* lds, LAS unsigned char* lds3, int b, int head, int qb, int tid, int wid, int lane) {
;     const int r32 = lane & 31, hi = lane >> 5, comp = wid >> 2, wq = wid & 3;
;     const size_t rowbase = (size_t)b * SEQ;
;     const int q0 = qb * 128 + wq * 32;
;     const int qcol = 1536 + head * 128 + comp * 64;
;     bf16x8 qf[4];
; #pragma unroll
;     for (int c = 0; c < 4; ++c) qf[c] = *(const bf16x8*)(QKV + (rowbase + q0 + r32) * QKVW + qcol + 16 * c + 8 * hi);
;     f32x16 o[4];
; #pragma unroll
;     for (int t = 0; t < 4; ++t)
; #pragma unroll
;         for (int i = 0; i < 16; ++i) o[t][i] = 0.f;
;     float m = -INFINITY, l = 0.f;
;     const int nst = 2 * (qb + 1);
;     const unsigned ldsb = (unsigned)(uintptr_t)lds3;
;     const int kkey = 8 * wid + (lane >> 3), kch = (lane & 7) ^ ((kkey >> 1) & 7);
;     const int vi0 = 2 * wid, vi1 = 2 * wid + 1;
;     const bf16_t* sbase = QKV + rowbase * QKVW + head * 128;
;     const unsigned oK = (unsigned)((kkey * QKVW + 2048 + kch * 8) * 2);
;     const unsigned oV0 = (unsigned)(((16 * (vi0 & 3) + (lane >> 2)) * QKVW + 2560 + ((vi0 >> 2) * 4 + (lane & 3)) * 8) * 2);
;     const unsigned oV1 = (unsigned)(((16 * (vi1 & 3) + (lane >> 2)) * QKVW + 2560 + ((vi1 >> 2) * 4 + (lane & 3)) * 8) * 2);
;     const unsigned dK = (unsigned)__builtin_amdgcn_readfirstlane(wid * 1024);
;     const unsigned dV0 = (unsigned)__builtin_amdgcn_readfirstlane(DF_V + (vi0 >> 2) * 4096 + (vi0 & 3) * 1024), dV1 = (unsigned)__builtin_amdgcn_readfirstlane(DF_V + (vi1 >> 2) * 4096 + (vi1 & 3) * 1024);
;     ...
;     DF_DMA(0, 0); DF_DMA(1, 1);
;     asm volatile("" : "+v"(qf[0]), "+v"(qf[1]), "+v"(qf[2]), "+v"(qf[3]));
;     DF_WAITBAR(4);
;     const int vlane = (4 * hi + ((lane & 15) >> 2)) * 64 + ((lane >> 4) & 1) * 32 + (lane & 3) * 8;
;     const bool skew = false;
;     bf16x8 pp[4]; { const bf16x8 z8 = {0, 0, 0, 0, 0, 0, 0, 0}; pp[0] = z8; pp[1] = z8; pp[2] = z8; pp[3] = z8; } int pvo = vlane; bool have_prev = false;
;     for (int t = 0; t < nst; ++t) {
;         { const int tl = (t + 2 < nst) ? t + 2 : nst - 1; DF_DMA(tl, (t + 2) & 3); }
.LBB0_278:
	s_and_b32 s49, s7, 63
	s_ashr_i32 s6, s7, 8
	s_xor_b32 s24, s49, 0x7f
	s_bfe_u32 s22, s7, 0x20006
	s_ashr_i32 s7, s6, 31
	s_lshl_b32 s25, s24, 7
	s_lshl_b64 s[26:27], s[6:7], 14
	s_or_b32 s7, s25, s34
	v_or_b32_e32 v1, s7, v129
	s_lshl_b32 s48, s22, 7
	v_or_b32_e32 v154, s26, v1
	v_mad_u64_u32 v[2:3], s[8:9], v154, s43, v[140:141]
	s_add_u32 s28, s35, s48
	v_mad_i32_i24 v3, s27, v169, v3
	s_addc_u32 s29, s42, 0
	v_lshl_add_u64 v[2:3], s[28:29], 1, v[2:3]
	v_lshl_add_u64 v[2:3], v[2:3], 0, v[144:145]
	global_load_dwordx4 v[112:115], v[2:3], off offset:3168
	global_load_dwordx4 v[116:119], v[2:3], off offset:3136
	global_load_dwordx4 v[120:123], v[2:3], off offset:3104
	global_load_dwordx4 v[124:127], v[2:3], off offset:3072
	s_mul_hi_i32 s31, s6, 0x6000000
	s_mul_i32 s50, s6, 0x6000000
	s_lshl_b32 s6, s24, 1
	s_add_u32 s24, s12, s50
	v_add_u32_e32 v146, s25, v168
	s_addc_u32 s25, s13, s31
	s_lshl_b32 s22, s22, 8
	v_readfirstlane_b32 s30, v170
	s_add_u32 s24, s24, s22
	s_addc_u32 s25, s25, 0
	s_lshl_b32 s50, s30, 10
	s_mov_b32 s30, m0
	s_mov_b32 m0, s50
	s_nop 0
	global_load_lds_dwordx4 v156, s[24:25]
	s_mov_b32 m0, s30
	s_add_i32 s51, s50, 0x2000
	s_mov_b32 s30, m0
	s_mov_b32 m0, s51
	s_nop 0
	global_load_lds_dwordx4 v159, s[24:25]
	s_mov_b32 m0, s30
	v_readfirstlane_b32 s9, v171
	s_mov_b32 s31, m0
	s_mov_b32 m0, s9
	s_nop 0
	global_load_lds_dwordx4 v157, s[24:25]
	s_mov_b32 m0, s31
	v_readfirstlane_b32 s10, v172
	s_add_u32 s30, s24, 0x60000
	s_mov_b32 s58, m0
	s_mov_b32 m0, s10
	s_nop 0
	global_load_lds_dwordx4 v158, s[24:25]
	s_mov_b32 m0, s58
	s_addc_u32 s31, s25, 0
	s_add_i32 s54, s50, 0x8000
	s_mov_b32 s58, m0
	s_mov_b32 m0, s54
	s_nop 0
	global_load_lds_dwordx4 v156, s[30:31]
	s_mov_b32 m0, s58
	s_add_i32 s55, s50, 0xa000
	s_mov_b32 s54, m0
	s_mov_b32 m0, s55
	s_nop 0
	global_load_lds_dwordx4 v159, s[30:31]
	s_mov_b32 m0, s54
	s_add_i32 s56, s9, 0x8000
	s_mov_b32 s54, m0
	s_mov_b32 m0, s56
	s_nop 0
	global_load_lds_dwordx4 v157, s[30:31]
	s_mov_b32 m0, s54
	v_mov_b32_e32 v14, v0
	v_mov_b32_e32 v15, v0
	s_add_i32 s57, s10, 0x8000
	s_mov_b32 s54, m0
	s_mov_b32 m0, s57
	s_nop 0
	global_load_lds_dwordx4 v158, s[30:31]
	s_mov_b32 m0, s54
	v_mov_b32_e32 v1, v0
	v_mov_b32_e32 v2, v0
	v_mov_b32_e32 v3, v0
	v_mov_b32_e32 v4, v0
	v_mov_b32_e32 v5, v0
	v_mov_b32_e32 v6, v0
	v_mov_b32_e32 v7, v0
	v_mov_b32_e32 v8, v0
	v_mov_b32_e32 v9, v0
	v_mov_b32_e32 v10, v0
	v_mov_b32_e32 v11, v0
	v_mov_b32_e32 v12, v0
	v_mov_b32_e32 v13, v0
	v_mov_b64_e32 v[30:31], v[14:15]
	v_mov_b64_e32 v[46:47], v[14:15]
	v_mov_b64_e32 v[62:63], v[14:15]
	v_mov_b64_e32 v[78:79], v[14:15]
	s_mov_b32 s8, 63
	s_mov_b32 s11, 0
	v_mov_b32_e32 v143, 0
	v_mov_b32_e32 v147, 0xff800000
	v_mov_b64_e32 v[28:29], v[12:13]
	v_mov_b64_e32 v[26:27], v[10:11]
	v_mov_b64_e32 v[24:25], v[8:9]
	v_mov_b64_e32 v[22:23], v[6:7]
	v_mov_b64_e32 v[20:21], v[4:5]
	v_mov_b64_e32 v[18:19], v[2:3]
	v_mov_b64_e32 v[16:17], v[0:1]
	v_mov_b32_e32 v155, s27
	s_or_b32 s52, s6, 1
	s_or_b32 s53, s7, 31
	v_mov_b64_e32 v[44:45], v[12:13]
	v_mov_b64_e32 v[42:43], v[10:11]
	v_mov_b64_e32 v[40:41], v[8:9]
	v_mov_b64_e32 v[38:39], v[6:7]
	v_mov_b64_e32 v[36:37], v[4:5]
	v_mov_b64_e32 v[34:35], v[2:3]
	v_mov_b64_e32 v[32:33], v[0:1]
	v_mov_b64_e32 v[60:61], v[12:13]
	v_mov_b64_e32 v[58:59], v[10:11]
	v_mov_b64_e32 v[56:57], v[8:9]
	s_waitcnt vmcnt(0)
	s_waitcnt vmcnt(4) lgkmcnt(0)
	s_barrier
	v_mov_b64_e32 v[54:55], v[6:7]
	v_mov_b64_e32 v[52:53], v[4:5]
	v_mov_b64_e32 v[50:51], v[2:3]
	v_mov_b64_e32 v[48:49], v[0:1]
	s_mov_b32 s54, 0
	v_mov_b64_e32 v[76:77], v[12:13]
	v_mov_b64_e32 v[74:75], v[10:11]
	v_mov_b64_e32 v[72:73], v[8:9]
	v_mov_b64_e32 v[70:71], v[6:7]
	v_mov_b64_e32 v[68:69], v[4:5]
	v_mov_b64_e32 v[66:67], v[2:3]
	v_mov_b64_e32 v[64:65], v[0:1]
	s_mov_b32 s60, 0
	s_mov_b32 s61, 0
	s_mov_b32 s62, m0
	v_mov_b32_e32 v240, 0
	v_mov_b32_e32 v241, 0
	v_mov_b32_e32 v242, 0
	v_mov_b32_e32 v243, 0
	v_mov_b32_e32 v244, 0
	v_mov_b32_e32 v245, 0
	v_mov_b32_e32 v246, 0
	v_mov_b32_e32 v247, 0
	v_mov_b32_e32 v248, 0
	v_mov_b32_e32 v249, 0
	v_mov_b32_e32 v250, 0
	v_mov_b32_e32 v251, 0
	v_mov_b32_e32 v252, 0
	v_mov_b32_e32 v253, 0
	v_mov_b32_e32 v254, 0
	v_mov_b32_e32 v255, 0
	s_add_i32 s66, s54, 2
	s_cmp_lt_u32 s54, s6
	s_cselect_b32 s64, s66, s52
	s_lshl_b32 s65, s64, 6
	s_mul_i32 s64, s64, 0x60000
	s_mul_hi_u32 s65, s65, 0x1800
	s_add_u32 s64, s24, s64
	s_addc_u32 s65, s25, s65
	s_lshl_b32 s66, s66, 15
	s_and_b32 s66, s66, 0x18000
	s_add_i32 s67, s66, s50
	s_add_i32 s68, s66, s51
	s_add_i32 s69, s66, s9
	s_add_i32 s70, s66, s10
; DI f32x16 mfma32(bf16x8 a, bf16x8 b, f32x16 c) { return __builtin_amdgcn_mfma_f32_32x32x16_bf16(a, b, c, 0, 0, 0); }
; #define DF_VLD(VF, VOFF, H) do { _Pragma("unroll") for (int d2 = 0; d2 < 2; ++d2) { LAS unsigned char* vb_ = lds3 + (VOFF) + (2 * (H) + d2) * 4096; VF[2 * d2] = vfrag(vb_); VF[2 * d2 + 1] = vfrag(vb_ + 1024); } } while (0)
; #define DF_PVM(VF, P0, P1, H) do { _Pragma("unroll") for (int d2 = 0; d2 < 2; ++d2) { o[2 * (H) + d2] = mfma32(VF[2 * d2], P0, o[2 * (H) + d2]); o[2 * (H) + d2] = mfma32(VF[2 * d2 + 1], P1, o[2 * (H) + d2]); } } while (0)
; DI void diff_stage(const unsigned char* lds, LAS unsigned char* lds3, int buf, int t, int comp, int q0, int r32, int hi, int vlane, bool skew,
;                    const bf16x8 (&qf)[4], f32x16 (&o)[4], float& m, float& l, bf16x8 (&pp)[4], int& pvo, bool& have_prev) {
;     const int k0 = 64 * t;
;     if (k0 > q0 + 31) return;
;     const unsigned char* sb = lds + buf * DF_STAGE + comp * DF_K2 + r32 * 128; const int ke16 = (hi ^ ((r32 >> 1) & 7)) * 16;
;     bf16x8 vf[4];
;     if (skew && have_prev) {
; #pragma unroll
;         for (int sub = 0; sub < 2; ++sub) { DF_VLD(vf, pvo + sub * 2048, 0); DF_PVM(vf, pp[2 * sub], pp[2 * sub + 1], 0); DF_VLD(vf, pvo + sub * 2048, 1); DF_PVM(vf, pp[2 * sub], pp[2 * sub + 1], 1); }
;     }
;     f32x16 s0, s1;
; #pragma unroll
;     for (int i = 0; i < 16; ++i) { s0[i] = 0.f; s1[i] = 0.f; }
;     {
;         bf16x8 k0f[4], k1f[4];
; #pragma unroll
;         for (int c = 0; c < 4; ++c) { k0f[c] = *(const bf16x8*)(sb + ((32 * c) ^ ke16)); k1f[c] = *(const bf16x8*)(sb + 32 * 128 + ((32 * c) ^ ke16)); }
; #pragma unroll
;         for (int c = 0; c < 4; ++c) { s0 = mfma32(k0f[c], qf[c], s0); s1 = mfma32(k1f[c], qf[c], s1); }
;     }
; DI void diff_unit(const Args& A, const bf16_t* QKV, bf16_t* ATT, unsigned char* lds, LAS unsigned char* lds3, int b, int head, int qb, int tid, int wid, int lane) {
;     ...
;     for (int t = 0; t < nst; ++t) {
;         { const int tl = (t + 2 < nst) ? t + 2 : nst - 1; DF_DMA(tl, (t + 2) & 3); }
;         diff_stage(lds, lds3, t & 3, t, comp, q0, r32, hi, vlane, skew, qf, o, m, l, pp, pvo, have_prev);
.Ldf1_loop:
	s_sub_i32 s71, s8, 63
	s_cmp_gt_u32 s71, s53
	s_cbranch_scc1 .Ldf1_skip
	s_and_b32 s55, s11, 0x18000
	v_add_u32_e32 v2, s55, v160
	v_add_u32_e32 v3, v2, v161
	v_add_u32_e32 v4, v2, v162
	v_add_u32_e32 v5, v2, v163
	v_add_u32_e32 v2, v2, v164
	ds_read_b128 v[208:211], v3
	ds_read_b128 v[212:215], v3 offset:4096
	ds_read_b128 v[216:219], v4
	ds_read_b128 v[220:223], v4 offset:4096
	ds_read_b128 v[224:227], v5
	ds_read_b128 v[228:231], v5 offset:4096
	ds_read_b128 v[232:235], v2
	ds_read_b128 v[236:239], v2 offset:4096
	s_mov_b32 m0, s67
	s_nop 0
	global_load_lds_dwordx4 v156, s[64:65]
	s_mov_b32 m0, s68
	s_nop 0
	global_load_lds_dwordx4 v159, s[64:65]
	s_mov_b32 m0, s69
	s_nop 0
	global_load_lds_dwordx4 v157, s[64:65]
	s_mov_b32 m0, s70
	s_nop 0
	global_load_lds_dwordx4 v158, s[64:65]
	s_add_i32 s56, s11, 0x18000
	s_cmp_eq_u32 s61, 0
	s_cselect_b32 s56, s11, s56
	s_and_b32 s56, s56, 0x18000
	v_add_u32_e32 v6, s56, v165
	s_cmp_eq_u32 s60, 0
	s_cbranch_scc1 .Ldf1s_noresc
	v_pk_mul_f32 v[78:79], v[78:79], v[206:207] op_sel_hi:[1,0]
	v_pk_mul_f32 v[76:77], v[76:77], v[206:207] op_sel_hi:[1,0]
	v_pk_mul_f32 v[74:75], v[74:75], v[206:207] op_sel_hi:[1,0]
	v_pk_mul_f32 v[72:73], v[72:73], v[206:207] op_sel_hi:[1,0]
	v_pk_mul_f32 v[70:71], v[70:71], v[206:207] op_sel_hi:[1,0]
	v_pk_mul_f32 v[68:69], v[68:69], v[206:207] op_sel_hi:[1,0]
	v_pk_mul_f32 v[66:67], v[66:67], v[206:207] op_sel_hi:[1,0]
	v_pk_mul_f32 v[64:65], v[64:65], v[206:207] op_sel_hi:[1,0]
	v_pk_mul_f32 v[62:63], v[62:63], v[206:207] op_sel_hi:[1,0]
	v_pk_mul_f32 v[60:61], v[60:61], v[206:207] op_sel_hi:[1,0]
	v_pk_mul_f32 v[58:59], v[58:59], v[206:207] op_sel_hi:[1,0]
	v_pk_mul_f32 v[56:57], v[56:57], v[206:207] op_sel_hi:[1,0]
	v_pk_mul_f32 v[54:55], v[54:55], v[206:207] op_sel_hi:[1,0]
	v_pk_mul_f32 v[52:53], v[52:53], v[206:207] op_sel_hi:[1,0]
	v_pk_mul_f32 v[50:51], v[50:51], v[206:207] op_sel_hi:[1,0]
	v_pk_mul_f32 v[48:49], v[48:49], v[206:207] op_sel_hi:[1,0]
	v_pk_mul_f32 v[46:47], v[46:47], v[206:207] op_sel_hi:[1,0]
	v_pk_mul_f32 v[44:45], v[44:45], v[206:207] op_sel_hi:[1,0]
	v_pk_mul_f32 v[42:43], v[42:43], v[206:207] op_sel_hi:[1,0]
	v_pk_mul_f32 v[40:41], v[40:41], v[206:207] op_sel_hi:[1,0]
	v_pk_mul_f32 v[38:39], v[38:39], v[206:207] op_sel_hi:[1,0]
	v_pk_mul_f32 v[36:37], v[36:37], v[206:207] op_sel_hi:[1,0]
	v_pk_mul_f32 v[34:35], v[34:35], v[206:207] op_sel_hi:[1,0]
	v_pk_mul_f32 v[32:33], v[32:33], v[206:207] op_sel_hi:[1,0]
	v_pk_mul_f32 v[30:31], v[30:31], v[206:207] op_sel_hi:[1,0]
	v_pk_mul_f32 v[28:29], v[28:29], v[206:207] op_sel_hi:[1,0]
	v_pk_mul_f32 v[26:27], v[26:27], v[206:207] op_sel_hi:[1,0]
	v_pk_mul_f32 v[24:25], v[24:25], v[206:207] op_sel_hi:[1,0]
	v_pk_mul_f32 v[22:23], v[22:23], v[206:207] op_sel_hi:[1,0]
	v_pk_mul_f32 v[20:21], v[20:21], v[206:207] op_sel_hi:[1,0]
	v_pk_mul_f32 v[18:19], v[18:19], v[206:207] op_sel_hi:[1,0]
	v_pk_mul_f32 v[16:17], v[16:17], v[206:207] op_sel_hi:[1,0]
	s_mov_b32 s60, 0

; DI float fexp2(float x) { return __builtin_amdgcn_exp2f(x); }
; #define DF_DMA(t, bufi) do { const bf16_t* sb_ = sbase + (size_t)(64 * (t)) * QKVW; const unsigned base_ = (unsigned)__builtin_amdgcn_readfirstlane(ldsb + (bufi) * DF_STAGE); \
;         glds16s(sb_, oK, base_ + dK); glds16s(sb_, oK + 128u, base_ + DF_K2 + dK); glds16s(sb_, oV0, base_ + dV0); glds16s(sb_, oV1, base_ + dV1); } while (0)
; DI void diff_stage(const unsigned char* lds, LAS unsigned char* lds3, int buf, int t, int comp, int q0, int r32, int hi, int vlane, bool skew,
;                    const bf16x8 (&qf)[4], f32x16 (&o)[4], float& m, float& l, bf16x8 (&pp)[4], int& pvo, bool& have_prev) {
;     ...
;     if (__any(mx > m + 8.f)) {
;         const float mn = fmaxf(m, mx), al = fexp2(m - mn); l *= al; m = mn;
; #pragma unroll
;         for (int dt = 0; dt < 4; ++dt)
; #pragma unroll
;             for (int i = 0; i < 16; ++i) o[dt][i] *= al;
;     }
; DI void diff_unit(const Args& A, const bf16_t* QKV, bf16_t* ATT, unsigned char* lds, LAS unsigned char* lds3, int b, int head, int qb, int tid, int wid, int lane) {
;     ...
;         { const int tl = (t + 2 < nst) ? t + 2 : nst - 1; DF_DMA(tl, (t + 2) & 3); }
.Ldf1_skip:
	s_mov_b32 m0, s67
	s_nop 0
	global_load_lds_dwordx4 v156, s[64:65]
	s_mov_b32 m0, s68
	s_nop 0
	global_load_lds_dwordx4 v159, s[64:65]
	s_mov_b32 m0, s69
	s_nop 0
	global_load_lds_dwordx4 v157, s[64:65]
	s_mov_b32 m0, s70
	s_nop 0
	global_load_lds_dwordx4 v158, s[64:65]
	s_cmp_eq_u32 s61, 0
	s_cbranch_scc1 .Ldf1_bar
	s_add_i32 s56, s11, 0x18000
	s_and_b32 s56, s56, 0x18000
	v_add_u32_e32 v6, s56, v165
	s_cmp_eq_u32 s60, 0
	s_cbranch_scc1 .Ldf1k_noresc
	v_pk_mul_f32 v[78:79], v[78:79], v[206:207] op_sel_hi:[1,0]
	v_pk_mul_f32 v[76:77], v[76:77], v[206:207] op_sel_hi:[1,0]
	v_pk_mul_f32 v[74:75], v[74:75], v[206:207] op_sel_hi:[1,0]
	v_pk_mul_f32 v[72:73], v[72:73], v[206:207] op_sel_hi:[1,0]
	v_pk_mul_f32 v[70:71], v[70:71], v[206:207] op_sel_hi:[1,0]
	v_pk_mul_f32 v[68:69], v[68:69], v[206:207] op_sel_hi:[1,0]
	v_pk_mul_f32 v[66:67], v[66:67], v[206:207] op_sel_hi:[1,0]
	v_pk_mul_f32 v[64:65], v[64:65], v[206:207] op_sel_hi:[1,0]
	v_pk_mul_f32 v[62:63], v[62:63], v[206:207] op_sel_hi:[1,0]
	v_pk_mul_f32 v[60:61], v[60:61], v[206:207] op_sel_hi:[1,0]
	v_pk_mul_f32 v[58:59], v[58:59], v[206:207] op_sel_hi:[1,0]
	v_pk_mul_f32 v[56:57], v[56:57], v[206:207] op_sel_hi:[1,0]
	v_pk_mul_f32 v[54:55], v[54:55], v[206:207] op_sel_hi:[1,0]
	v_pk_mul_f32 v[52:53], v[52:53], v[206:207] op_sel_hi:[1,0]
	v_pk_mul_f32 v[50:51], v[50:51], v[206:207] op_sel_hi:[1,0]
	v_pk_mul_f32 v[48:49], v[48:49], v[206:207] op_sel_hi:[1,0]
	v_pk_mul_f32 v[46:47], v[46:47], v[206:207] op_sel_hi:[1,0]
	v_pk_mul_f32 v[44:45], v[44:45], v[206:207] op_sel_hi:[1,0]
	v_pk_mul_f32 v[42:43], v[42:43], v[206:207] op_sel_hi:[1,0]
	v_pk_mul_f32 v[40:41], v[40:41], v[206:207] op_sel_hi:[1,0]
	v_pk_mul_f32 v[38:39], v[38:39], v[206:207] op_sel_hi:[1,0]
	v_pk_mul_f32 v[36:37], v[36:37], v[206:207] op_sel_hi:[1,0]
	v_pk_mul_f32 v[34:35], v[34:35], v[206:207] op_sel_hi:[1,0]
	v_pk_mul_f32 v[32:33], v[32:33], v[206:207] op_sel_hi:[1,0]
	v_pk_mul_f32 v[30:31], v[30:31], v[206:207] op_sel_hi:[1,0]
	v_pk_mul_f32 v[28:29], v[28:29], v[206:207] op_sel_hi:[1,0]
	v_pk_mul_f32 v[26:27], v[26:27], v[206:207] op_sel_hi:[1,0]
	v_pk_mul_f32 v[24:25], v[24:25], v[206:207] op_sel_hi:[1,0]
	v_pk_mul_f32 v[22:23], v[22:23], v[206:207] op_sel_hi:[1,0]
	v_pk_mul_f32 v[20:21], v[20:21], v[206:207] op_sel_hi:[1,0]
	v_pk_mul_f32 v[18:19], v[18:19], v[206:207] op_sel_hi:[1,0]
	v_pk_mul_f32 v[16:17], v[16:17], v[206:207] op_sel_hi:[1,0]
	s_mov_b32 s60, 0

; #define DF_DMA(t, bufi) do { const bf16_t* sb_ = sbase + (size_t)(64 * (t)) * QKVW; const unsigned base_ = (unsigned)__builtin_amdgcn_readfirstlane(ldsb + (bufi) * DF_STAGE); \
;         glds16s(sb_, oK, base_ + dK); glds16s(sb_, oK + 128u, base_ + DF_K2 + dK); glds16s(sb_, oV0, base_ + dV0); glds16s(sb_, oV1, base_ + dV1); } while (0)
; #define DF_WAITBAR(N) asm volatile("s_waitcnt vmcnt(" #N ") lgkmcnt(0)\n\ts_barrier" ::: "memory")
; DI void diff_unit(const Args& A, const bf16_t* QKV, bf16_t* ATT, unsigned char* lds, LAS unsigned char* lds3, int b, int head, int qb, int tid, int wid, int lane) {
;     ...
;     for (int t = 0; t < nst; ++t) {
;         { const int tl = (t + 2 < nst) ? t + 2 : nst - 1; DF_DMA(tl, (t + 2) & 3); }
;         diff_stage(lds, lds3, t & 3, t, comp, q0, r32, hi, vlane, skew, qf, o, m, l, pp, pvo, have_prev);
;         DF_WAITBAR(4);
;     }
.Ldf1_bar:
	s_waitcnt vmcnt(4) lgkmcnt(0)
	s_add_i32 s11, s11, 0x8000
	s_add_i32 s8, s8, 64
	v_subrev_u32_e32 v146, 64, v146
	s_add_i32 s55, s54, 1
	s_add_i32 s66, s55, 2
	s_cmp_lt_u32 s55, s6
	s_cselect_b32 s64, s66, s52
	s_lshl_b32 s65, s64, 6
	s_mul_i32 s64, s64, 0x60000
	s_mul_hi_u32 s65, s65, 0x1800
	s_add_u32 s64, s24, s64
	s_addc_u32 s65, s25, s65
	s_lshl_b32 s66, s66, 15
	s_and_b32 s66, s66, 0x18000
	s_add_i32 s67, s66, s50
	s_add_i32 s68, s66, s51
	s_add_i32 s69, s66, s9
	s_add_i32 s70, s66, s10
	s_cmp_eq_u32 s54, s52
	s_barrier
	s_cbranch_scc1 .Ldf1_exit
	s_mov_b32 s54, s55
	s_branch .Ldf1_loop

; DI void diff_stage(const unsigned char* lds, LAS unsigned char* lds3, int buf, int t, int comp, int q0, int r32, int hi, int vlane, bool skew,
;                    const bf16x8 (&qf)[4], f32x16 (&o)[4], float& m, float& l, bf16x8 (&pp)[4], int& pvo, bool& have_prev) {
;     ...
;     if (k0 > q0 + 31) return;
;     const unsigned char* sb = lds + buf * DF_STAGE + comp * DF_K2 + r32 * 128; const int ke16 = (hi ^ ((r32 >> 1) & 7)) * 16;
;     bf16x8 vf[4];
;     if (skew && have_prev) {
; DI void diff_unit(const Args& A, const bf16_t* QKV, bf16_t* ATT, unsigned char* lds, LAS unsigned char* lds3, int b, int head, int qb, int tid, int wid, int lane) {
;     ...
;     for (int c = 0; c < 4; ++c) qf[c] = *(const bf16x8*)(QKV + (rowbase + q0 + r32) * QKVW + qcol + 16 * c + 8 * hi);
;     f32x16 o[4];
; #pragma unroll
;     for (int t = 0; t < 4; ++t)
; #pragma unroll
;         for (int i = 0; i < 16; ++i) o[t][i] = 0.f;
;     float m = -INFINITY, l = 0.f;
;     const int nst = 2 * (qb + 1);
;     const unsigned ldsb = (unsigned)(uintptr_t)lds3;
;     const int kkey = 8 * wid + (lane >> 3), kch = (lane & 7) ^ ((kkey >> 1) & 7);
;     const int vi0 = 2 * wid, vi1 = 2 * wid + 1;
;     const bf16_t* sbase = QKV + rowbase * QKVW + head * 128;
;     const unsigned oK = (unsigned)((kkey * QKVW + 2048 + kch * 8) * 2);
;     const unsigned oV0 = (unsigned)(((16 * (vi0 & 3) + (lane >> 2)) * QKVW + 2560 + ((vi0 >> 2) * 4 + (lane & 3)) * 8) * 2);
;     const unsigned oV1 = (unsigned)(((16 * (vi1 & 3) + (lane >> 2)) * QKVW + 2560 + ((vi1 >> 2) * 4 + (lane & 3)) * 8) * 2);
;     const unsigned dK = (unsigned)__builtin_amdgcn_readfirstlane(wid * 1024);
;     const unsigned dV0 = (unsigned)__builtin_amdgcn_readfirstlane(DF_V + (vi0 >> 2) * 4096 + (vi0 & 3) * 1024), dV1 = (unsigned)__builtin_amdgcn_readfirstlane(DF_V + (vi1 >> 2) * 4096 + (vi1 & 3) * 1024);
;     ...
;     DF_DMA(0, 0); DF_DMA(1, 1);
;     asm volatile("" : "+v"(qf[0]), "+v"(qf[1]), "+v"(qf[2]), "+v"(qf[3]));
;     DF_WAITBAR(4);
;     const int vlane = (4 * hi + ((lane & 15) >> 2)) * 64 + ((lane >> 4) & 1) * 32 + (lane & 3) * 8;
;     const bool skew = false;
;     bf16x8 pp[4]; { const bf16x8 z8 = {0, 0, 0, 0, 0, 0, 0, 0}; pp[0] = z8; pp[1] = z8; pp[2] = z8; pp[3] = z8; } int pvo = vlane; bool have_prev = false;
;     for (int t = 0; t < nst; ++t) {
;         { const int tl = (t + 2 < nst) ? t + 2 : nst - 1; DF_DMA(tl, (t + 2) & 3); }
.LBB0_291:
	s_lshl_b32 s52, s49, 7
	s_or_b32 s10, s52, s34
	v_or_b32_e32 v1, s10, v129
	v_or_b32_e32 v154, s26, v1
	v_mov_b64_e32 v[2:3], s[12:13]
	v_mad_u64_u32 v[2:3], s[50:51], v154, s43, v[2:3]
	v_mad_i32_i24 v3, s27, v169, v3
	v_lshl_add_u64 v[2:3], s[28:29], 1, v[2:3]
	v_mov_b32_e32 v143, v0
	v_lshl_add_u64 v[2:3], v[2:3], 0, v[142:143]
	s_barrier
	global_load_dwordx4 v[112:115], v[2:3], off offset:3168
	global_load_dwordx4 v[116:119], v[2:3], off offset:3136
	global_load_dwordx4 v[120:123], v[2:3], off offset:3104
	global_load_dwordx4 v[124:127], v[2:3], off offset:3072
	s_lshl_b32 s22, s33, 10
	v_add_u32_e32 v183, s52, v168
	s_mov_b32 s52, m0
	s_mov_b32 m0, s22
	s_nop 0
	global_load_lds_dwordx4 v156, s[24:25]
	s_mov_b32 m0, s52
	s_add_i32 s28, s22, 0x2000
	s_mov_b32 s52, m0
	s_mov_b32 m0, s28
	s_nop 0
	global_load_lds_dwordx4 v159, s[24:25]
	s_mov_b32 m0, s52
	s_add_i32 s53, s22, 0x8000
	s_mov_b32 s52, m0
	s_mov_b32 m0, s36
	s_nop 0
	global_load_lds_dwordx4 v157, s[24:25]
	s_mov_b32 m0, s52
	s_add_i32 s54, s22, 0xa000
	s_mov_b32 s52, m0
	s_mov_b32 m0, s37
	s_nop 0
	global_load_lds_dwordx4 v158, s[24:25]
	s_mov_b32 m0, s52
	s_add_i32 s50, s36, 0x8000
	s_mov_b32 s52, m0
	s_mov_b32 m0, s53
	s_nop 0
	global_load_lds_dwordx4 v156, s[30:31]
	s_mov_b32 m0, s52
	s_add_i32 s51, s37, 0x8000
	s_mov_b32 s52, m0
	s_mov_b32 m0, s54
	s_nop 0
	global_load_lds_dwordx4 v159, s[30:31]
	s_mov_b32 m0, s52
	v_mov_b32_e32 v14, v0
	s_mov_b32 s52, m0
	s_mov_b32 m0, s50
	s_nop 0
	global_load_lds_dwordx4 v157, s[30:31]
	s_mov_b32 m0, s52
	v_mov_b32_e32 v15, v0
	s_mov_b32 s50, m0
	s_mov_b32 m0, s51
	s_nop 0
	global_load_lds_dwordx4 v158, s[30:31]
	s_mov_b32 m0, s50
	s_lshl_b32 s11, s49, 1
	v_mov_b32_e32 v1, v0
	v_mov_b32_e32 v2, v0
	v_mov_b32_e32 v3, v0
	v_mov_b32_e32 v4, v0
	v_mov_b32_e32 v5, v0
	v_mov_b32_e32 v6, v0
	v_mov_b32_e32 v7, v0
	v_mov_b32_e32 v8, v0
	v_mov_b32_e32 v9, v0
	v_mov_b32_e32 v10, v0
	v_mov_b32_e32 v11, v0
	v_mov_b32_e32 v12, v0
	v_mov_b32_e32 v13, v0
	v_mov_b64_e32 v[30:31], v[14:15]
	v_mov_b64_e32 v[46:47], v[14:15]
	v_mov_b64_e32 v[62:63], v[14:15]
	v_mov_b64_e32 v[78:79], v[14:15]
	v_mov_b32_e32 v155, s27
	s_mov_b32 s26, 0
	v_mov_b32_e32 v143, 0
	v_mov_b32_e32 v185, 0xff800000
	s_mov_b32 s27, 63
	s_or_b32 s29, s11, 1
	v_mov_b64_e32 v[28:29], v[12:13]
	v_mov_b64_e32 v[26:27], v[10:11]
	v_mov_b64_e32 v[24:25], v[8:9]
	v_mov_b64_e32 v[22:23], v[6:7]
	v_mov_b64_e32 v[20:21], v[4:5]
	v_mov_b64_e32 v[18:19], v[2:3]
	v_mov_b64_e32 v[16:17], v[0:1]
	s_or_b32 s49, s10, 31
	v_mov_b64_e32 v[44:45], v[12:13]
	v_mov_b64_e32 v[42:43], v[10:11]
	v_mov_b64_e32 v[40:41], v[8:9]
	v_mov_b64_e32 v[38:39], v[6:7]
	v_mov_b64_e32 v[36:37], v[4:5]
	v_mov_b64_e32 v[34:35], v[2:3]
	v_mov_b64_e32 v[32:33], v[0:1]
	v_mov_b64_e32 v[60:61], v[12:13]
	v_mov_b64_e32 v[58:59], v[10:11]
	v_mov_b64_e32 v[56:57], v[8:9]
	v_mov_b64_e32 v[54:55], v[6:7]
	v_mov_b64_e32 v[52:53], v[4:5]
	v_mov_b64_e32 v[50:51], v[2:3]
	v_mov_b64_e32 v[48:49], v[0:1]
	s_mov_b32 s30, 0
	v_mov_b64_e32 v[76:77], v[12:13]
	v_mov_b64_e32 v[74:75], v[10:11]
	v_mov_b64_e32 v[72:73], v[8:9]
	v_mov_b64_e32 v[70:71], v[6:7]
	v_mov_b64_e32 v[68:69], v[4:5]
	v_mov_b64_e32 v[66:67], v[2:3]
	v_mov_b64_e32 v[64:65], v[0:1]
	s_waitcnt vmcnt(0)
	s_waitcnt vmcnt(4) lgkmcnt(0)
	s_barrier
	s_mov_b32 s60, 0
	s_mov_b32 s61, 0
	s_mov_b32 s62, m0
	v_mov_b32_e32 v240, 0
	v_mov_b32_e32 v241, 0
	v_mov_b32_e32 v242, 0
	v_mov_b32_e32 v243, 0
	v_mov_b32_e32 v244, 0
	v_mov_b32_e32 v245, 0
	v_mov_b32_e32 v246, 0
	v_mov_b32_e32 v247, 0
	v_mov_b32_e32 v248, 0
	v_mov_b32_e32 v249, 0
	v_mov_b32_e32 v250, 0
	v_mov_b32_e32 v251, 0
	v_mov_b32_e32 v252, 0
	v_mov_b32_e32 v253, 0
	v_mov_b32_e32 v254, 0
	v_mov_b32_e32 v255, 0
	s_add_i32 s66, s30, 2
	s_cmp_lt_u32 s30, s11
	s_cselect_b32 s64, s66, s29
	s_lshl_b32 s65, s64, 6
	s_mul_i32 s64, s64, 0x60000
	s_mul_hi_u32 s65, s65, 0x1800
	s_add_u32 s64, s24, s64
	s_addc_u32 s65, s25, s65
	s_lshl_b32 s66, s66, 15
	s_and_b32 s66, s66, 0x18000
	s_add_i32 s67, s66, s22
	s_add_i32 s68, s66, s28
	s_add_i32 s69, s66, s36
	s_add_i32 s70, s66, s37
.Ldf2_loop:
	s_sub_i32 s71, s27, 63
	s_cmp_gt_u32 s71, s49
	s_cbranch_scc1 .Ldf2_skip
	s_and_b32 s31, s26, 0x18000
	v_add_u32_e32 v2, s31, v160
	v_add_u32_e32 v3, v2, v161
	v_add_u32_e32 v4, v2, v162
	v_add_u32_e32 v5, v2, v163
	v_add_u32_e32 v2, v2, v164
	ds_read_b128 v[208:211], v3
	ds_read_b128 v[212:215], v3 offset:4096
	ds_read_b128 v[216:219], v4
	ds_read_b128 v[220:223], v4 offset:4096
	ds_read_b128 v[224:227], v5
	ds_read_b128 v[228:231], v5 offset:4096
	ds_read_b128 v[232:235], v2
	ds_read_b128 v[236:239], v2 offset:4096
	s_mov_b32 m0, s67
	s_nop 0
	global_load_lds_dwordx4 v156, s[64:65]
	s_mov_b32 m0, s68
	s_nop 0
	global_load_lds_dwordx4 v159, s[64:65]
	s_mov_b32 m0, s69
	s_nop 0
	global_load_lds_dwordx4 v157, s[64:65]
	s_mov_b32 m0, s70
	s_nop 0
	global_load_lds_dwordx4 v158, s[64:65]
	s_add_i32 s50, s26, 0x18000
	s_cmp_eq_u32 s61, 0
	s_cselect_b32 s50, s26, s50
	s_and_b32 s50, s50, 0x18000
	v_add_u32_e32 v6, s50, v165
	s_cmp_eq_u32 s60, 0
	s_cbranch_scc1 .Ldf2s_noresc
	v_pk_mul_f32 v[78:79], v[78:79], v[206:207] op_sel_hi:[1,0]
	v_pk_mul_f32 v[76:77], v[76:77], v[206:207] op_sel_hi:[1,0]
	v_pk_mul_f32 v[74:75], v[74:75], v[206:207] op_sel_hi:[1,0]
	v_pk_mul_f32 v[72:73], v[72:73], v[206:207] op_sel_hi:[1,0]
	v_pk_mul_f32 v[70:71], v[70:71], v[206:207] op_sel_hi:[1,0]
	v_pk_mul_f32 v[68:69], v[68:69], v[206:207] op_sel_hi:[1,0]
	v_pk_mul_f32 v[66:67], v[66:67], v[206:207] op_sel_hi:[1,0]
	v_pk_mul_f32 v[64:65], v[64:65], v[206:207] op_sel_hi:[1,0]
	v_pk_mul_f32 v[62:63], v[62:63], v[206:207] op_sel_hi:[1,0]
	v_pk_mul_f32 v[60:61], v[60:61], v[206:207] op_sel_hi:[1,0]
	v_pk_mul_f32 v[58:59], v[58:59], v[206:207] op_sel_hi:[1,0]
	v_pk_mul_f32 v[56:57], v[56:57], v[206:207] op_sel_hi:[1,0]
	v_pk_mul_f32 v[54:55], v[54:55], v[206:207] op_sel_hi:[1,0]
	v_pk_mul_f32 v[52:53], v[52:53], v[206:207] op_sel_hi:[1,0]
	v_pk_mul_f32 v[50:51], v[50:51], v[206:207] op_sel_hi:[1,0]
	v_pk_mul_f32 v[48:49], v[48:49], v[206:207] op_sel_hi:[1,0]
	v_pk_mul_f32 v[46:47], v[46:47], v[206:207] op_sel_hi:[1,0]
	v_pk_mul_f32 v[44:45], v[44:45], v[206:207] op_sel_hi:[1,0]
	v_pk_mul_f32 v[42:43], v[42:43], v[206:207] op_sel_hi:[1,0]
	v_pk_mul_f32 v[40:41], v[40:41], v[206:207] op_sel_hi:[1,0]
	v_pk_mul_f32 v[38:39], v[38:39], v[206:207] op_sel_hi:[1,0]
	v_pk_mul_f32 v[36:37], v[36:37], v[206:207] op_sel_hi:[1,0]
	v_pk_mul_f32 v[34:35], v[34:35], v[206:207] op_sel_hi:[1,0]
	v_pk_mul_f32 v[32:33], v[32:33], v[206:207] op_sel_hi:[1,0]
	v_pk_mul_f32 v[30:31], v[30:31], v[206:207] op_sel_hi:[1,0]
	v_pk_mul_f32 v[28:29], v[28:29], v[206:207] op_sel_hi:[1,0]
	v_pk_mul_f32 v[26:27], v[26:27], v[206:207] op_sel_hi:[1,0]
	v_pk_mul_f32 v[24:25], v[24:25], v[206:207] op_sel_hi:[1,0]
	v_pk_mul_f32 v[22:23], v[22:23], v[206:207] op_sel_hi:[1,0]
	v_pk_mul_f32 v[20:21], v[20:21], v[206:207] op_sel_hi:[1,0]
	v_pk_mul_f32 v[18:19], v[18:19], v[206:207] op_sel_hi:[1,0]
	v_pk_mul_f32 v[16:17], v[16:17], v[206:207] op_sel_hi:[1,0]
	s_mov_b32 s60, 0

; #define DF_VLD(VF, VOFF, H) do { _Pragma("unroll") for (int d2 = 0; d2 < 2; ++d2) { LAS unsigned char* vb_ = lds3 + (VOFF) + (2 * (H) + d2) * 4096; VF[2 * d2] = vfrag(vb_); VF[2 * d2 + 1] = vfrag(vb_ + 1024); } } while (0)
; #define DF_PVM(VF, P0, P1, H) do { _Pragma("unroll") for (int d2 = 0; d2 < 2; ++d2) { o[2 * (H) + d2] = mfma32(VF[2 * d2], P0, o[2 * (H) + d2]); o[2 * (H) + d2] = mfma32(VF[2 * d2 + 1], P1, o[2 * (H) + d2]); } } while (0)
; #define DF_DMA(t, bufi) do { const bf16_t* sb_ = sbase + (size_t)(64 * (t)) * QKVW; const unsigned base_ = (unsigned)__builtin_amdgcn_readfirstlane(ldsb + (bufi) * DF_STAGE); \
;         glds16s(sb_, oK, base_ + dK); glds16s(sb_, oK + 128u, base_ + DF_K2 + dK); glds16s(sb_, oV0, base_ + dV0); glds16s(sb_, oV1, base_ + dV1); } while (0)
; DI void diff_stage(const unsigned char* lds, LAS unsigned char* lds3, int buf, int t, int comp, int q0, int r32, int hi, int vlane, bool skew,
;                    const bf16x8 (&qf)[4], f32x16 (&o)[4], float& m, float& l, bf16x8 (&pp)[4], int& pvo, bool& have_prev) {
;     ...
;     if (skew && have_prev) {
; #pragma unroll
;         for (int sub = 0; sub < 2; ++sub) { DF_VLD(vf, pvo + sub * 2048, 0); DF_PVM(vf, pp[2 * sub], pp[2 * sub + 1], 0); DF_VLD(vf, pvo + sub * 2048, 1); DF_PVM(vf, pp[2 * sub], pp[2 * sub + 1], 1); }
;     }
; DI void diff_unit(const Args& A, const bf16_t* QKV, bf16_t* ATT, unsigned char* lds, LAS unsigned char* lds3, int b, int head, int qb, int tid, int wid, int lane) {
;     ...
;     for (int t = 0; t < nst; ++t) {
;         { const int tl = (t + 2 < nst) ? t + 2 : nst - 1; DF_DMA(tl, (t + 2) & 3); }
.Ldf2_skip:
	s_mov_b32 m0, s67
	s_nop 0
	global_load_lds_dwordx4 v156, s[64:65]
	s_mov_b32 m0, s68
	s_nop 0
	global_load_lds_dwordx4 v159, s[64:65]
	s_mov_b32 m0, s69
	s_nop 0
	global_load_lds_dwordx4 v157, s[64:65]
	s_mov_b32 m0, s70
	s_nop 0
	global_load_lds_dwordx4 v158, s[64:65]
	s_cmp_eq_u32 s61, 0
	s_cbranch_scc1 .Ldf2_bar
	s_add_i32 s50, s26, 0x18000
	s_and_b32 s50, s50, 0x18000
	v_add_u32_e32 v6, s50, v165
	s_cmp_eq_u32 s60, 0
	s_cbranch_scc1 .Ldf2k_noresc
	v_pk_mul_f32 v[78:79], v[78:79], v[206:207] op_sel_hi:[1,0]
	v_pk_mul_f32 v[76:77], v[76:77], v[206:207] op_sel_hi:[1,0]
	v_pk_mul_f32 v[74:75], v[74:75], v[206:207] op_sel_hi:[1,0]
	v_pk_mul_f32 v[72:73], v[72:73], v[206:207] op_sel_hi:[1,0]
	v_pk_mul_f32 v[70:71], v[70:71], v[206:207] op_sel_hi:[1,0]
	v_pk_mul_f32 v[68:69], v[68:69], v[206:207] op_sel_hi:[1,0]
	v_pk_mul_f32 v[66:67], v[66:67], v[206:207] op_sel_hi:[1,0]
	v_pk_mul_f32 v[64:65], v[64:65], v[206:207] op_sel_hi:[1,0]
	v_pk_mul_f32 v[62:63], v[62:63], v[206:207] op_sel_hi:[1,0]
	v_pk_mul_f32 v[60:61], v[60:61], v[206:207] op_sel_hi:[1,0]
	v_pk_mul_f32 v[58:59], v[58:59], v[206:207] op_sel_hi:[1,0]
	v_pk_mul_f32 v[56:57], v[56:57], v[206:207] op_sel_hi:[1,0]
	v_pk_mul_f32 v[54:55], v[54:55], v[206:207] op_sel_hi:[1,0]
	v_pk_mul_f32 v[52:53], v[52:53], v[206:207] op_sel_hi:[1,0]
	v_pk_mul_f32 v[50:51], v[50:51], v[206:207] op_sel_hi:[1,0]
	v_pk_mul_f32 v[48:49], v[48:49], v[206:207] op_sel_hi:[1,0]
	v_pk_mul_f32 v[46:47], v[46:47], v[206:207] op_sel_hi:[1,0]
	v_pk_mul_f32 v[44:45], v[44:45], v[206:207] op_sel_hi:[1,0]
	v_pk_mul_f32 v[42:43], v[42:43], v[206:207] op_sel_hi:[1,0]
	v_pk_mul_f32 v[40:41], v[40:41], v[206:207] op_sel_hi:[1,0]
	v_pk_mul_f32 v[38:39], v[38:39], v[206:207] op_sel_hi:[1,0]
	v_pk_mul_f32 v[36:37], v[36:37], v[206:207] op_sel_hi:[1,0]
	v_pk_mul_f32 v[34:35], v[34:35], v[206:207] op_sel_hi:[1,0]
	v_pk_mul_f32 v[32:33], v[32:33], v[206:207] op_sel_hi:[1,0]
	v_pk_mul_f32 v[30:31], v[30:31], v[206:207] op_sel_hi:[1,0]
	v_pk_mul_f32 v[28:29], v[28:29], v[206:207] op_sel_hi:[1,0]
	v_pk_mul_f32 v[26:27], v[26:27], v[206:207] op_sel_hi:[1,0]
	v_pk_mul_f32 v[24:25], v[24:25], v[206:207] op_sel_hi:[1,0]
	v_pk_mul_f32 v[22:23], v[22:23], v[206:207] op_sel_hi:[1,0]
	v_pk_mul_f32 v[20:21], v[20:21], v[206:207] op_sel_hi:[1,0]
	v_pk_mul_f32 v[18:19], v[18:19], v[206:207] op_sel_hi:[1,0]
	v_pk_mul_f32 v[16:17], v[16:17], v[206:207] op_sel_hi:[1,0]
	s_mov_b32 s60, 0

; #define DF_DMA(t, bufi) do { const bf16_t* sb_ = sbase + (size_t)(64 * (t)) * QKVW; const unsigned base_ = (unsigned)__builtin_amdgcn_readfirstlane(ldsb + (bufi) * DF_STAGE); \
;         glds16s(sb_, oK, base_ + dK); glds16s(sb_, oK + 128u, base_ + DF_K2 + dK); glds16s(sb_, oV0, base_ + dV0); glds16s(sb_, oV1, base_ + dV1); } while (0)
; #define DF_WAITBAR(N) asm volatile("s_waitcnt vmcnt(" #N ") lgkmcnt(0)\n\ts_barrier" ::: "memory")
; DI void diff_unit(const Args& A, const bf16_t* QKV, bf16_t* ATT, unsigned char* lds, LAS unsigned char* lds3, int b, int head, int qb, int tid, int wid, int lane) {
;     ...
;     for (int t = 0; t < nst; ++t) {
;         { const int tl = (t + 2 < nst) ? t + 2 : nst - 1; DF_DMA(tl, (t + 2) & 3); }
;         diff_stage(lds, lds3, t & 3, t, comp, q0, r32, hi, vlane, skew, qf, o, m, l, pp, pvo, have_prev);
;         DF_WAITBAR(4);
;     }
.Ldf2_bar:
	s_waitcnt vmcnt(4) lgkmcnt(0)
	s_add_i32 s26, s26, 0x8000
	s_add_i32 s27, s27, 64
	v_subrev_u32_e32 v183, 64, v183
	s_add_i32 s31, s30, 1
	s_add_i32 s66, s31, 2
	s_cmp_lt_u32 s31, s11
	s_cselect_b32 s64, s66, s29
	s_lshl_b32 s65, s64, 6
	s_mul_i32 s64, s64, 0x60000
	s_mul_hi_u32 s65, s65, 0x1800
	s_add_u32 s64, s24, s64
	s_addc_u32 s65, s25, s65
	s_lshl_b32 s66, s66, 15
	s_and_b32 s66, s66, 0x18000
	s_add_i32 s67, s66, s22
	s_add_i32 s68, s66, s28
	s_add_i32 s69, s66, s36
	s_add_i32 s70, s66, s37
	s_cmp_eq_u32 s30, s29
	s_barrier
	s_cbranch_scc1 .Ldf2_exit
	s_mov_b32 s30, s31
	s_branch .Ldf2_loop

; #define PG8_STAGE(bufoff, gbase, voff) do { _Pragma("unroll") for (int _i = 0; _i < 2; ++_i) \
;         __builtin_amdgcn_global_load_lds((const unsigned*)((const char*)(gbase) + (voff)[_i]), (PG8_LAS unsigned*)(lds + (bufoff) + ldsw + _i * 8192), 16, 0, 0); } while (0)
; #define PG8_LDA(dst, b, h) do { _Pragma("unroll") for (int m = 0; m < 4; ++m) _Pragma("unroll") for (int k = 0; k < 2; ++k) dst[m][k] = *(const PG8_LAS bf16x8*)(lds + PG8_SA(b, h) + aoff + m * 2048 + k * 1024); } while (0)
; #define PG8_LDB(dst, b, h) do { _Pragma("unroll") for (int n = 0; n < 2; ++n) _Pragma("unroll") for (int k = 0; k < 2; ++k) dst[n][k] = *(const PG8_LAS bf16x8*)(lds + PG8_SB(b, h) + boff + n * 2048 + k * 1024); } while (0)
; #define PG8_MMA(ai, bj, At, Bt) do { __builtin_amdgcn_s_setprio(1); _Pragma("unroll") for (int m = 0; m < 4; ++m) _Pragma("unroll") for (int n = 0; n < 2; ++n) _Pragma("unroll") for (int k = 0; k < 2; ++k) \
;         acc[ai][bj][m][n] = __builtin_amdgcn_mfma_f32_16x16x32_bf16(Bt[n][k], At[m][k], acc[ai][bj][m][n], 0, 0, 0); __builtin_amdgcn_s_setprio(0); } while (0)
; #define PG8_WAIT_V(n) asm volatile("s_waitcnt vmcnt(" #n ")" ::: "memory")
; #define PG8_WAIT_L(n) asm volatile("s_waitcnt lgkmcnt(" #n ")" ::: "memory")
; #define PG8_BAR __builtin_amdgcn_s_barrier()
; #define PG8_SCHED __builtin_amdgcn_sched_barrier(0)
; template <class Epi, class Sched, bool ALIGN_EPI = false, bool SP2 = false>
; __device__ __forceinline__ void gemm_phase(PG8_LAS unsigned char* lds, const Gemm g, const Sched& S, const Epi& E) {
;     ...
;             PG8_LDB(B0, 0, 0); PG8_LDB(B1, 0, 1); PG8_SCHED; PG8_LDA(At, 0, 0); PG8_STAGE(PG8_SA(1, 1), a1 + hstep, voffA);
;             PG8_WAIT_V(8); PG8_WAIT_L(0); PG8_BAR; PG8_MMA(0, 0, At, B0); PG8_MMA(0, 1, At, B1); PG8_BAR; PG8_SCHED;
;             PG8_LDA(At, 0, 1); PG8_STAGE(PG8_SB(0, 0), b2, voffB); PG8_STAGE(PG8_SB(0, 1), b2 + hstep, voffB); PG8_STAGE(PG8_SA(0, 0), a2, voffA);
;             PG8_WAIT_V(8); PG8_WAIT_L(0); PG8_BAR; PG8_MMA(1, 0, At, B0); PG8_MMA(1, 1, At, B1); PG8_BAR; PG8_SCHED;
.LBB0_390:
	ds_read_b128 v[144:147], v151
	ds_read_b128 v[168:171], v152
	ds_read_b128 v[172:175], v153
	ds_read_b128 v[176:179], v154
	ds_read_b128 v[180:183], v155
	ds_read_b128 v[186:189], v156
	ds_read_b128 v[190:193], v157
	ds_read_b128 v[194:197], v158
	s_add_u32 s36, s34, 0xfffc0080
	s_addc_u32 s37, s35, -1
	s_cmp_eq_u32 s70, 12
	s_cselect_b32 s43, s25, s37
	s_cselect_b32 s42, s31, s36
	s_cselect_b32 s37, s23, s69
	s_cselect_b32 s36, s67, s68
	s_mov_b32 m0, s64
	v_lshl_add_u64 v[230:231], s[34:35], 0, v[138:139]
	ds_read_b128 v[198:201], v149
	ds_read_b128 v[202:205], v149 offset:1024
	ds_read_b128 v[206:209], v149 offset:2048
	ds_read_b128 v[210:213], v149 offset:3072
	ds_read_b128 v[214:217], v149 offset:4096
	ds_read_b128 v[218:221], v149 offset:5120
	ds_read_b128 v[222:225], v149 offset:6144
	ds_read_b128 v[226:229], v149 offset:7168
	global_load_lds_dwordx4 v[230:231], off
	v_lshl_add_u64 v[230:231], s[34:35], 0, v[136:137]
	s_mov_b32 m0, s65
	s_nop 0
	global_load_lds_dwordx4 v[230:231], off
	s_waitcnt vmcnt(8)
	s_waitcnt lgkmcnt(0)
	s_barrier
	s_waitcnt lgkmcnt(0)
	v_mfma_f32_16x16x32_bf16 v[124:127], v[144:147], v[198:201], v[124:127]
	v_mfma_f32_16x16x32_bf16 v[120:123], v[172:175], v[198:201], v[120:123]
	v_mfma_f32_16x16x32_bf16 v[108:111], v[144:147], v[206:209], v[108:111]
	v_mfma_f32_16x16x32_bf16 v[104:107], v[172:175], v[206:209], v[104:107]
	v_mfma_f32_16x16x32_bf16 v[92:95], v[144:147], v[214:217], v[92:95]
	v_mfma_f32_16x16x32_bf16 v[88:91], v[172:175], v[214:217], v[88:91]
	v_mfma_f32_16x16x32_bf16 v[76:79], v[144:147], v[222:225], v[76:79]
	v_mfma_f32_16x16x32_bf16 v[72:75], v[172:175], v[222:225], v[72:75]
	v_mfma_f32_16x16x32_bf16 v[124:127], v[168:171], v[202:205], v[124:127]
	v_mfma_f32_16x16x32_bf16 v[120:123], v[176:179], v[202:205], v[120:123]
	v_mfma_f32_16x16x32_bf16 v[108:111], v[168:171], v[210:213], v[108:111]
	v_mfma_f32_16x16x32_bf16 v[104:107], v[176:179], v[210:213], v[104:107]
	v_mfma_f32_16x16x32_bf16 v[92:95], v[168:171], v[218:221], v[92:95]
	v_mfma_f32_16x16x32_bf16 v[88:91], v[176:179], v[218:221], v[88:91]
	v_mfma_f32_16x16x32_bf16 v[76:79], v[168:171], v[226:229], v[76:79]
	v_mfma_f32_16x16x32_bf16 v[72:75], v[176:179], v[226:229], v[72:75]
	v_mfma_f32_16x16x32_bf16 v[116:119], v[180:183], v[198:201], v[116:119]
	v_mfma_f32_16x16x32_bf16 v[112:115], v[190:193], v[198:201], v[112:115]
	v_mfma_f32_16x16x32_bf16 v[100:103], v[180:183], v[206:209], v[100:103]
	v_mfma_f32_16x16x32_bf16 v[96:99], v[190:193], v[206:209], v[96:99]
	v_mfma_f32_16x16x32_bf16 v[84:87], v[180:183], v[214:217], v[84:87]
	v_mfma_f32_16x16x32_bf16 v[80:83], v[190:193], v[214:217], v[80:83]
	v_mfma_f32_16x16x32_bf16 v[68:71], v[180:183], v[222:225], v[68:71]
	v_mfma_f32_16x16x32_bf16 v[64:67], v[190:193], v[222:225], v[64:67]
	v_mfma_f32_16x16x32_bf16 v[116:119], v[186:189], v[202:205], v[116:119]
	v_mfma_f32_16x16x32_bf16 v[112:115], v[194:197], v[202:205], v[112:115]
	v_mfma_f32_16x16x32_bf16 v[100:103], v[186:189], v[210:213], v[100:103]
	v_mfma_f32_16x16x32_bf16 v[96:99], v[194:197], v[210:213], v[96:99]
	v_mfma_f32_16x16x32_bf16 v[84:87], v[186:189], v[218:221], v[84:87]
	v_mfma_f32_16x16x32_bf16 v[80:83], v[194:197], v[218:221], v[80:83]
	v_mfma_f32_16x16x32_bf16 v[68:71], v[186:189], v[226:229], v[68:71]
	v_mfma_f32_16x16x32_bf16 v[64:67], v[194:197], v[226:229], v[64:67]
	s_barrier
	s_mov_b32 m0, s48
	v_lshl_add_u64 v[230:231], s[36:37], 0, v[130:131]
	s_add_u32 s72, s36, 0x40000
	ds_read_b128 v[198:201], v149 offset:16384
	ds_read_b128 v[202:205], v149 offset:17408
	ds_read_b128 v[206:209], v149 offset:18432
	ds_read_b128 v[210:213], v149 offset:19456
	ds_read_b128 v[214:217], v149 offset:20480
	ds_read_b128 v[218:221], v149 offset:21504
	ds_read_b128 v[222:225], v149 offset:22528
	ds_read_b128 v[226:229], v149 offset:23552
	global_load_lds_dwordx4 v[230:231], off
	v_lshl_add_u64 v[232:233], s[36:37], 0, v[134:135]
	s_mov_b32 m0, s49
	s_addc_u32 s73, s37, 0
	global_load_lds_dwordx4 v[232:233], off
	v_lshl_add_u64 v[234:235], s[72:73], 0, v[130:131]
	s_mov_b32 m0, s50
	v_lshl_add_u64 v[236:237], s[42:43], 0, v[132:133]
	global_load_lds_dwordx4 v[234:235], off
	v_lshl_add_u64 v[234:235], s[72:73], 0, v[134:135]
	s_mov_b32 m0, s51
	s_nop 0
	global_load_lds_dwordx4 v[234:235], off
	v_lshl_add_u64 v[234:235], s[42:43], 0, v[128:129]
	s_mov_b32 m0, s47
	s_nop 0
	global_load_lds_dwordx4 v[234:235], off
	s_mov_b32 m0, s52
	s_nop 0
	global_load_lds_dwordx4 v[236:237], off
	s_waitcnt vmcnt(8)
	s_waitcnt lgkmcnt(0)
	s_barrier
	s_waitcnt lgkmcnt(0)
	v_mfma_f32_16x16x32_bf16 v[60:63], v[144:147], v[198:201], v[60:63]
	v_mfma_f32_16x16x32_bf16 v[56:59], v[172:175], v[198:201], v[56:59]
	v_mfma_f32_16x16x32_bf16 v[44:47], v[144:147], v[206:209], v[44:47]
	v_mfma_f32_16x16x32_bf16 v[40:43], v[172:175], v[206:209], v[40:43]
	v_mfma_f32_16x16x32_bf16 v[28:31], v[144:147], v[214:217], v[28:31]
	v_mfma_f32_16x16x32_bf16 v[24:27], v[172:175], v[214:217], v[24:27]
	v_mfma_f32_16x16x32_bf16 v[12:15], v[144:147], v[222:225], v[12:15]
	v_mfma_f32_16x16x32_bf16 v[8:11], v[172:175], v[222:225], v[8:11]
	v_mfma_f32_16x16x32_bf16 v[60:63], v[168:171], v[202:205], v[60:63]
	v_mfma_f32_16x16x32_bf16 v[56:59], v[176:179], v[202:205], v[56:59]
	v_mfma_f32_16x16x32_bf16 v[44:47], v[168:171], v[210:213], v[44:47]
	v_mfma_f32_16x16x32_bf16 v[40:43], v[176:179], v[210:213], v[40:43]
	v_mfma_f32_16x16x32_bf16 v[28:31], v[168:171], v[218:221], v[28:31]
	v_mfma_f32_16x16x32_bf16 v[24:27], v[176:179], v[218:221], v[24:27]
	v_mfma_f32_16x16x32_bf16 v[12:15], v[168:171], v[226:229], v[12:15]
	v_mfma_f32_16x16x32_bf16 v[8:11], v[176:179], v[226:229], v[8:11]
	v_mfma_f32_16x16x32_bf16 v[52:55], v[180:183], v[198:201], v[52:55]
	v_mfma_f32_16x16x32_bf16 v[48:51], v[190:193], v[198:201], v[48:51]
	v_mfma_f32_16x16x32_bf16 v[36:39], v[180:183], v[206:209], v[36:39]
	v_mfma_f32_16x16x32_bf16 v[32:35], v[190:193], v[206:209], v[32:35]
	v_mfma_f32_16x16x32_bf16 v[20:23], v[180:183], v[214:217], v[20:23]
	v_mfma_f32_16x16x32_bf16 v[16:19], v[190:193], v[214:217], v[16:19]
	v_mfma_f32_16x16x32_bf16 v[4:7], v[180:183], v[222:225], v[4:7]
	v_mfma_f32_16x16x32_bf16 v[0:3], v[190:193], v[222:225], v[0:3]
	v_mfma_f32_16x16x32_bf16 v[52:55], v[186:189], v[202:205], v[52:55]
	v_mfma_f32_16x16x32_bf16 v[48:51], v[194:197], v[202:205], v[48:51]
	v_mfma_f32_16x16x32_bf16 v[36:39], v[186:189], v[210:213], v[36:39]
	v_mfma_f32_16x16x32_bf16 v[32:35], v[194:197], v[210:213], v[32:35]
	v_mfma_f32_16x16x32_bf16 v[20:23], v[186:189], v[218:221], v[20:23]
	v_mfma_f32_16x16x32_bf16 v[16:19], v[194:197], v[218:221], v[16:19]
	v_mfma_f32_16x16x32_bf16 v[4:7], v[186:189], v[226:229], v[4:7]
	v_mfma_f32_16x16x32_bf16 v[0:3], v[194:197], v[226:229], v[0:3]
	s_barrier
; #define PG8_STAGE(bufoff, gbase, voff) do { _Pragma("unroll") for (int _i = 0; _i < 2; ++_i) \
;         __builtin_amdgcn_global_load_lds((const unsigned*)((const char*)(gbase) + (voff)[_i]), (PG8_LAS unsigned*)(lds + (bufoff) + ldsw + _i * 8192), 16, 0, 0); } while (0)
; #define PG8_LDA(dst, b, h) do { _Pragma("unroll") for (int m = 0; m < 4; ++m) _Pragma("unroll") for (int k = 0; k < 2; ++k) dst[m][k] = *(const PG8_LAS bf16x8*)(lds + PG8_SA(b, h) + aoff + m * 2048 + k * 1024); } while (0)
; #define PG8_LDB(dst, b, h) do { _Pragma("unroll") for (int n = 0; n < 2; ++n) _Pragma("unroll") for (int k = 0; k < 2; ++k) dst[n][k] = *(const PG8_LAS bf16x8*)(lds + PG8_SB(b, h) + boff + n * 2048 + k * 1024); } while (0)
; #define PG8_MMA(ai, bj, At, Bt) do { __builtin_amdgcn_s_setprio(1); _Pragma("unroll") for (int m = 0; m < 4; ++m) _Pragma("unroll") for (int n = 0; n < 2; ++n) _Pragma("unroll") for (int k = 0; k < 2; ++k) \
;         acc[ai][bj][m][n] = __builtin_amdgcn_mfma_f32_16x16x32_bf16(Bt[n][k], At[m][k], acc[ai][bj][m][n], 0, 0, 0); __builtin_amdgcn_s_setprio(0); } while (0)
; #define PG8_WAIT_V(n) asm volatile("s_waitcnt vmcnt(" #n ")" ::: "memory")
; #define PG8_WAIT_L(n) asm volatile("s_waitcnt lgkmcnt(" #n ")" ::: "memory")
; #define PG8_BAR __builtin_amdgcn_s_barrier()
; #define PG8_SCHED __builtin_amdgcn_sched_barrier(0)
; template <class Epi, class Sched, bool ALIGN_EPI = false, bool SP2 = false>
; __device__ __forceinline__ void gemm_phase(PG8_LAS unsigned char* lds, const Gemm g, const Sched& S, const Epi& E) {
;     ...
;         for (int t = 0; t < nt; t += 2) {
;             const bool last = (t == nt - 2);
;             const char* a1 = cA + (size_t)(t + 1) * kstep;
;             const char* a2 = last ? nA : cA + (size_t)(t + 2) * kstep; const char* b2 = last ? nB : cB + (size_t)(t + 2) * kstep;
;     ...
;             PG8_LDB(B0, 1, 0); PG8_LDB(B1, 1, 1); PG8_SCHED; PG8_LDA(At, 1, 0); PG8_STAGE(PG8_SA(0, 1), a2 + hstep, voffA);
;             PG8_WAIT_V(8); PG8_WAIT_L(0); PG8_BAR; PG8_MMA(0, 0, At, B0); PG8_MMA(0, 1, At, B1); PG8_BAR; PG8_SCHED;
;             PG8_LDA(At, 1, 1); PG8_STAGE(PG8_SB(1, 0), b3, voffB); PG8_STAGE(PG8_SB(1, 1), b3 + hstep, voffB); PG8_STAGE(PG8_SA(1, 0), a3, voffA);
;             PG8_WAIT_V(8); PG8_WAIT_L(0); PG8_BAR; PG8_MMA(1, 0, At, B0); PG8_MMA(1, 1, At, B1); PG8_BAR; PG8_SCHED;
	ds_read_b128 v[144:147], v159
	ds_read_b128 v[168:171], v160
	ds_read_b128 v[172:175], v161
	ds_read_b128 v[176:179], v162
	ds_read_b128 v[180:183], v163
	ds_read_b128 v[186:189], v164
	ds_read_b128 v[190:193], v165
	ds_read_b128 v[194:197], v166
	s_add_u32 s42, s42, 0x40000
	s_addc_u32 s43, s43, 0
	s_mov_b32 m0, s53
	v_lshl_add_u64 v[238:239], s[42:43], 0, v[128:129]
	ds_read_b128 v[198:201], v149 offset:32768
	ds_read_b128 v[202:205], v149 offset:33792
	ds_read_b128 v[206:209], v149 offset:34816
	ds_read_b128 v[210:213], v149 offset:35840
	ds_read_b128 v[214:217], v149 offset:36864
	ds_read_b128 v[218:221], v149 offset:37888
	ds_read_b128 v[222:225], v149 offset:38912
	ds_read_b128 v[226:229], v149 offset:39936
	global_load_lds_dwordx4 v[238:239], off
	v_lshl_add_u64 v[238:239], s[42:43], 0, v[132:133]
	s_mov_b32 m0, s54
	s_nop 0
	global_load_lds_dwordx4 v[238:239], off
	s_waitcnt vmcnt(8)
	s_waitcnt lgkmcnt(0)
	s_barrier
	s_waitcnt lgkmcnt(0)
	v_mfma_f32_16x16x32_bf16 v[124:127], v[144:147], v[198:201], v[124:127]
	v_mfma_f32_16x16x32_bf16 v[120:123], v[172:175], v[198:201], v[120:123]
	v_mfma_f32_16x16x32_bf16 v[108:111], v[144:147], v[206:209], v[108:111]
	v_mfma_f32_16x16x32_bf16 v[104:107], v[172:175], v[206:209], v[104:107]
	v_mfma_f32_16x16x32_bf16 v[92:95], v[144:147], v[214:217], v[92:95]
	v_mfma_f32_16x16x32_bf16 v[88:91], v[172:175], v[214:217], v[88:91]
	v_mfma_f32_16x16x32_bf16 v[76:79], v[144:147], v[222:225], v[76:79]
	v_mfma_f32_16x16x32_bf16 v[72:75], v[172:175], v[222:225], v[72:75]
	v_mfma_f32_16x16x32_bf16 v[124:127], v[168:171], v[202:205], v[124:127]
	v_mfma_f32_16x16x32_bf16 v[120:123], v[176:179], v[202:205], v[120:123]
	v_mfma_f32_16x16x32_bf16 v[108:111], v[168:171], v[210:213], v[108:111]
	v_mfma_f32_16x16x32_bf16 v[104:107], v[176:179], v[210:213], v[104:107]
	v_mfma_f32_16x16x32_bf16 v[92:95], v[168:171], v[218:221], v[92:95]
	v_mfma_f32_16x16x32_bf16 v[88:91], v[176:179], v[218:221], v[88:91]
	v_mfma_f32_16x16x32_bf16 v[76:79], v[168:171], v[226:229], v[76:79]
	v_mfma_f32_16x16x32_bf16 v[72:75], v[176:179], v[226:229], v[72:75]
	v_mfma_f32_16x16x32_bf16 v[116:119], v[180:183], v[198:201], v[116:119]
	v_mfma_f32_16x16x32_bf16 v[112:115], v[190:193], v[198:201], v[112:115]
	v_mfma_f32_16x16x32_bf16 v[100:103], v[180:183], v[206:209], v[100:103]
	v_mfma_f32_16x16x32_bf16 v[96:99], v[190:193], v[206:209], v[96:99]
	v_mfma_f32_16x16x32_bf16 v[84:87], v[180:183], v[214:217], v[84:87]
	v_mfma_f32_16x16x32_bf16 v[80:83], v[190:193], v[214:217], v[80:83]
	v_mfma_f32_16x16x32_bf16 v[68:71], v[180:183], v[222:225], v[68:71]
	v_mfma_f32_16x16x32_bf16 v[64:67], v[190:193], v[222:225], v[64:67]
	v_mfma_f32_16x16x32_bf16 v[116:119], v[186:189], v[202:205], v[116:119]
	v_mfma_f32_16x16x32_bf16 v[112:115], v[194:197], v[202:205], v[112:115]
	v_mfma_f32_16x16x32_bf16 v[100:103], v[186:189], v[210:213], v[100:103]
	v_mfma_f32_16x16x32_bf16 v[96:99], v[194:197], v[210:213], v[96:99]
	v_mfma_f32_16x16x32_bf16 v[84:87], v[186:189], v[218:221], v[84:87]
	v_mfma_f32_16x16x32_bf16 v[80:83], v[194:197], v[218:221], v[80:83]
	v_mfma_f32_16x16x32_bf16 v[68:71], v[186:189], v[226:229], v[68:71]
	v_mfma_f32_16x16x32_bf16 v[64:67], v[194:197], v[226:229], v[64:67]
	s_barrier
	s_mov_b32 m0, s56
	v_lshl_add_u64 v[230:231], v[230:231], 0, s[16:17]
	s_add_u32 s36, s36, 0x40080
	ds_read_b128 v[198:201], v149 offset:49152
	ds_read_b128 v[202:205], v149 offset:50176
	ds_read_b128 v[206:209], v149 offset:51200
	ds_read_b128 v[210:213], v149 offset:52224
	ds_read_b128 v[214:217], v149 offset:53248
	ds_read_b128 v[218:221], v149 offset:54272
	ds_read_b128 v[222:225], v149 offset:55296
	ds_read_b128 v[226:229], v149 offset:56320
	global_load_lds_dwordx4 v[230:231], off
	v_lshl_add_u64 v[230:231], v[232:233], 0, s[16:17]
	s_mov_b32 m0, s57
	s_addc_u32 s37, s37, 0
	global_load_lds_dwordx4 v[230:231], off
	v_lshl_add_u64 v[230:231], s[36:37], 0, v[130:131]
	s_mov_b32 m0, s60
	s_nop 0
	global_load_lds_dwordx4 v[230:231], off
	v_lshl_add_u64 v[230:231], s[36:37], 0, v[134:135]
	s_mov_b32 m0, s61
	s_nop 0
	global_load_lds_dwordx4 v[230:231], off
	v_lshl_add_u64 v[230:231], v[234:235], 0, s[16:17]
	s_mov_b32 m0, s58
	s_nop 0
	global_load_lds_dwordx4 v[230:231], off
	v_lshl_add_u64 v[230:231], v[236:237], 0, s[16:17]
	s_mov_b32 m0, s59
	s_nop 0
	global_load_lds_dwordx4 v[230:231], off
	s_waitcnt vmcnt(8)
	s_waitcnt lgkmcnt(0)
	s_barrier
	s_waitcnt lgkmcnt(0)
	v_mfma_f32_16x16x32_bf16 v[60:63], v[144:147], v[198:201], v[60:63]
	v_mfma_f32_16x16x32_bf16 v[56:59], v[172:175], v[198:201], v[56:59]
	v_mfma_f32_16x16x32_bf16 v[44:47], v[144:147], v[206:209], v[44:47]
	v_mfma_f32_16x16x32_bf16 v[40:43], v[172:175], v[206:209], v[40:43]
	v_mfma_f32_16x16x32_bf16 v[28:31], v[144:147], v[214:217], v[28:31]
	v_mfma_f32_16x16x32_bf16 v[24:27], v[172:175], v[214:217], v[24:27]
	v_mfma_f32_16x16x32_bf16 v[12:15], v[144:147], v[222:225], v[12:15]
	v_mfma_f32_16x16x32_bf16 v[8:11], v[172:175], v[222:225], v[8:11]
	v_mfma_f32_16x16x32_bf16 v[60:63], v[168:171], v[202:205], v[60:63]
	v_mfma_f32_16x16x32_bf16 v[56:59], v[176:179], v[202:205], v[56:59]
	v_mfma_f32_16x16x32_bf16 v[44:47], v[168:171], v[210:213], v[44:47]
	v_mfma_f32_16x16x32_bf16 v[40:43], v[176:179], v[210:213], v[40:43]
	v_mfma_f32_16x16x32_bf16 v[28:31], v[168:171], v[218:221], v[28:31]
	v_mfma_f32_16x16x32_bf16 v[24:27], v[176:179], v[218:221], v[24:27]
	v_mfma_f32_16x16x32_bf16 v[12:15], v[168:171], v[226:229], v[12:15]
	v_mfma_f32_16x16x32_bf16 v[8:11], v[176:179], v[226:229], v[8:11]
	v_mfma_f32_16x16x32_bf16 v[52:55], v[180:183], v[198:201], v[52:55]
	v_mfma_f32_16x16x32_bf16 v[48:51], v[190:193], v[198:201], v[48:51]
	v_mfma_f32_16x16x32_bf16 v[36:39], v[180:183], v[206:209], v[36:39]
	v_mfma_f32_16x16x32_bf16 v[32:35], v[190:193], v[206:209], v[32:35]
	v_mfma_f32_16x16x32_bf16 v[20:23], v[180:183], v[214:217], v[20:23]
	v_mfma_f32_16x16x32_bf16 v[16:19], v[190:193], v[214:217], v[16:19]
	v_mfma_f32_16x16x32_bf16 v[4:7], v[180:183], v[222:225], v[4:7]
	v_mfma_f32_16x16x32_bf16 v[0:3], v[190:193], v[222:225], v[0:3]
	v_mfma_f32_16x16x32_bf16 v[52:55], v[186:189], v[202:205], v[52:55]
	v_mfma_f32_16x16x32_bf16 v[48:51], v[194:197], v[202:205], v[48:51]
	v_mfma_f32_16x16x32_bf16 v[36:39], v[186:189], v[210:213], v[36:39]
	v_mfma_f32_16x16x32_bf16 v[32:35], v[194:197], v[210:213], v[32:35]
	v_mfma_f32_16x16x32_bf16 v[20:23], v[186:189], v[218:221], v[20:23]
	v_mfma_f32_16x16x32_bf16 v[16:19], v[194:197], v[218:221], v[16:19]
	v_mfma_f32_16x16x32_bf16 v[4:7], v[186:189], v[226:229], v[4:7]
	v_mfma_f32_16x16x32_bf16 v[0:3], v[194:197], v[226:229], v[0:3]
	s_add_i32 s70, s70, 2
	s_add_u32 s68, s68, 0x100
	s_addc_u32 s69, s69, 0
	s_add_u32 s34, s34, 0x100
	s_addc_u32 s35, s35, 0
	s_cmp_gt_u32 s70, 13
	s_barrier
	s_cbranch_scc0 .LBB0_390
	s_and_b64 vcc, exec, s[18:19]
	s_cbranch_vccz .LBB0_393
	s_barrier

; #define PG8_STAGE(bufoff, gbase, voff) do { _Pragma("unroll") for (int _i = 0; _i < 2; ++_i) \
;         __builtin_amdgcn_global_load_lds((const unsigned*)((const char*)(gbase) + (voff)[_i]), (PG8_LAS unsigned*)(lds + (bufoff) + ldsw + _i * 8192), 16, 0, 0); } while (0)
; #define PG8_LDA(dst, b, h) do { _Pragma("unroll") for (int m = 0; m < 4; ++m) _Pragma("unroll") for (int k = 0; k < 2; ++k) dst[m][k] = *(const PG8_LAS bf16x8*)(lds + PG8_SA(b, h) + aoff + m * 2048 + k * 1024); } while (0)
; #define PG8_LDB(dst, b, h) do { _Pragma("unroll") for (int n = 0; n < 2; ++n) _Pragma("unroll") for (int k = 0; k < 2; ++k) dst[n][k] = *(const PG8_LAS bf16x8*)(lds + PG8_SB(b, h) + boff + n * 2048 + k * 1024); } while (0)
; #define PG8_MMA(ai, bj, At, Bt) do { __builtin_amdgcn_s_setprio(1); _Pragma("unroll") for (int m = 0; m < 4; ++m) _Pragma("unroll") for (int n = 0; n < 2; ++n) _Pragma("unroll") for (int k = 0; k < 2; ++k) \
;         acc[ai][bj][m][n] = __builtin_amdgcn_mfma_f32_16x16x32_bf16(Bt[n][k], At[m][k], acc[ai][bj][m][n], 0, 0, 0); __builtin_amdgcn_s_setprio(0); } while (0)
; #define PG8_WAIT_V(n) asm volatile("s_waitcnt vmcnt(" #n ")" ::: "memory")
; #define PG8_WAIT_L(n) asm volatile("s_waitcnt lgkmcnt(" #n ")" ::: "memory")
; #define PG8_BAR __builtin_amdgcn_s_barrier()
; #define PG8_SCHED __builtin_amdgcn_sched_barrier(0)
; template <class Epi, class Sched, bool ALIGN_EPI = false, bool SP2 = false>
; __device__ __forceinline__ void gemm_phase(PG8_LAS unsigned char* lds, const Gemm g, const Sched& S, const Epi& E) {
;     ...
;             PG8_LDB(B0, 0, 0); PG8_LDB(B1, 0, 1); PG8_SCHED; PG8_LDA(At, 0, 0); PG8_STAGE(PG8_SA(1, 1), a1 + hstep, voffA);
;             PG8_WAIT_V(8); PG8_WAIT_L(0); PG8_BAR; PG8_MMA(0, 0, At, B0); PG8_MMA(0, 1, At, B1); PG8_BAR; PG8_SCHED;
;             PG8_LDA(At, 0, 1); PG8_STAGE(PG8_SB(0, 0), b2, voffB); PG8_STAGE(PG8_SB(0, 1), b2 + hstep, voffB); PG8_STAGE(PG8_SA(0, 0), a2, voffA);
;             PG8_WAIT_V(8); PG8_WAIT_L(0); PG8_BAR; PG8_MMA(1, 0, At, B0); PG8_MMA(1, 1, At, B1); PG8_BAR; PG8_SCHED;
.LBB0_477:
	ds_read_b128 v[144:147], v151
	ds_read_b128 v[170:173], v152
	ds_read_b128 v[174:177], v153
	ds_read_b128 v[178:181], v154
	ds_read_b128 v[186:189], v155
	ds_read_b128 v[190:193], v156
	ds_read_b128 v[194:197], v157
	ds_read_b128 v[198:201], v158
	s_add_u32 s30, s28, 0xfffc0080
	s_addc_u32 s31, s29, -1
	s_cmp_eq_u32 s67, 12
	s_cselect_b32 s35, s23, s31
	s_cselect_b32 s34, s63, s30
	s_cselect_b32 s31, s21, s66
	s_cselect_b32 s30, s64, s65
	s_mov_b32 m0, s60
	v_lshl_add_u64 v[182:183], s[28:29], 0, v[138:139]
	ds_read_b128 v[202:205], v149
	ds_read_b128 v[206:209], v149 offset:1024
	ds_read_b128 v[210:213], v149 offset:2048
	ds_read_b128 v[214:217], v149 offset:3072
	ds_read_b128 v[218:221], v149 offset:4096
	ds_read_b128 v[222:225], v149 offset:5120
	ds_read_b128 v[226:229], v149 offset:6144
	ds_read_b128 v[230:233], v149 offset:7168
	global_load_lds_dwordx4 v[182:183], off
	v_lshl_add_u64 v[182:183], s[28:29], 0, v[136:137]
	s_mov_b32 m0, s61
	s_nop 0
	global_load_lds_dwordx4 v[182:183], off
	s_waitcnt vmcnt(8)
	s_waitcnt lgkmcnt(0)
	s_barrier
	s_waitcnt lgkmcnt(0)
	v_mfma_f32_16x16x32_bf16 v[124:127], v[144:147], v[202:205], v[124:127]
	v_mfma_f32_16x16x32_bf16 v[120:123], v[174:177], v[202:205], v[120:123]
	v_mfma_f32_16x16x32_bf16 v[108:111], v[144:147], v[210:213], v[108:111]
	v_mfma_f32_16x16x32_bf16 v[104:107], v[174:177], v[210:213], v[104:107]
	v_mfma_f32_16x16x32_bf16 v[92:95], v[144:147], v[218:221], v[92:95]
	v_mfma_f32_16x16x32_bf16 v[88:91], v[174:177], v[218:221], v[88:91]
	v_mfma_f32_16x16x32_bf16 v[76:79], v[144:147], v[226:229], v[76:79]
	v_mfma_f32_16x16x32_bf16 v[72:75], v[174:177], v[226:229], v[72:75]
	v_mfma_f32_16x16x32_bf16 v[124:127], v[170:173], v[206:209], v[124:127]
	v_mfma_f32_16x16x32_bf16 v[120:123], v[178:181], v[206:209], v[120:123]
	v_mfma_f32_16x16x32_bf16 v[108:111], v[170:173], v[214:217], v[108:111]
	v_mfma_f32_16x16x32_bf16 v[104:107], v[178:181], v[214:217], v[104:107]
	v_mfma_f32_16x16x32_bf16 v[92:95], v[170:173], v[222:225], v[92:95]
	v_mfma_f32_16x16x32_bf16 v[88:91], v[178:181], v[222:225], v[88:91]
	v_mfma_f32_16x16x32_bf16 v[76:79], v[170:173], v[230:233], v[76:79]
	v_mfma_f32_16x16x32_bf16 v[72:75], v[178:181], v[230:233], v[72:75]
	v_mfma_f32_16x16x32_bf16 v[116:119], v[186:189], v[202:205], v[116:119]
	v_mfma_f32_16x16x32_bf16 v[112:115], v[194:197], v[202:205], v[112:115]
	v_mfma_f32_16x16x32_bf16 v[100:103], v[186:189], v[210:213], v[100:103]
	v_mfma_f32_16x16x32_bf16 v[96:99], v[194:197], v[210:213], v[96:99]
	v_mfma_f32_16x16x32_bf16 v[84:87], v[186:189], v[218:221], v[84:87]
	v_mfma_f32_16x16x32_bf16 v[80:83], v[194:197], v[218:221], v[80:83]
	v_mfma_f32_16x16x32_bf16 v[68:71], v[186:189], v[226:229], v[68:71]
	v_mfma_f32_16x16x32_bf16 v[64:67], v[194:197], v[226:229], v[64:67]
	v_mfma_f32_16x16x32_bf16 v[116:119], v[190:193], v[206:209], v[116:119]
	v_mfma_f32_16x16x32_bf16 v[112:115], v[198:201], v[206:209], v[112:115]
	v_mfma_f32_16x16x32_bf16 v[100:103], v[190:193], v[214:217], v[100:103]
	v_mfma_f32_16x16x32_bf16 v[96:99], v[198:201], v[214:217], v[96:99]
	v_mfma_f32_16x16x32_bf16 v[84:87], v[190:193], v[222:225], v[84:87]
	v_mfma_f32_16x16x32_bf16 v[80:83], v[198:201], v[222:225], v[80:83]
	v_mfma_f32_16x16x32_bf16 v[68:71], v[190:193], v[230:233], v[68:71]
	v_mfma_f32_16x16x32_bf16 v[64:67], v[198:201], v[230:233], v[64:67]
	s_barrier
	s_mov_b32 m0, s44
	v_lshl_add_u64 v[182:183], s[30:31], 0, v[132:133]
	s_add_u32 s68, s30, 0x40000
	ds_read_b128 v[202:205], v149 offset:16384
	ds_read_b128 v[206:209], v149 offset:17408
	ds_read_b128 v[210:213], v149 offset:18432
	ds_read_b128 v[214:217], v149 offset:19456
	ds_read_b128 v[218:221], v149 offset:20480
	ds_read_b128 v[222:225], v149 offset:21504
	ds_read_b128 v[226:229], v149 offset:22528
	ds_read_b128 v[230:233], v149 offset:23552
	global_load_lds_dwordx4 v[182:183], off
	v_lshl_add_u64 v[234:235], s[30:31], 0, v[128:129]
	s_mov_b32 m0, s45
	s_addc_u32 s69, s31, 0
	global_load_lds_dwordx4 v[234:235], off
	v_lshl_add_u64 v[236:237], s[68:69], 0, v[132:133]
	s_mov_b32 m0, s46
	v_lshl_add_u64 v[238:239], s[34:35], 0, v[130:131]
	global_load_lds_dwordx4 v[236:237], off
	v_lshl_add_u64 v[236:237], s[68:69], 0, v[128:129]
	s_mov_b32 m0, s47
	s_nop 0
	global_load_lds_dwordx4 v[236:237], off
	v_lshl_add_u64 v[236:237], s[34:35], 0, v[134:135]
	s_mov_b32 m0, s42
	s_nop 0
	global_load_lds_dwordx4 v[236:237], off
	s_mov_b32 m0, s48
	s_nop 0
	global_load_lds_dwordx4 v[238:239], off
	s_waitcnt vmcnt(8)
	s_waitcnt lgkmcnt(0)
	s_barrier
	s_waitcnt lgkmcnt(0)
	v_mfma_f32_16x16x32_bf16 v[60:63], v[144:147], v[202:205], v[60:63]
	v_mfma_f32_16x16x32_bf16 v[56:59], v[174:177], v[202:205], v[56:59]
	v_mfma_f32_16x16x32_bf16 v[44:47], v[144:147], v[210:213], v[44:47]
	v_mfma_f32_16x16x32_bf16 v[40:43], v[174:177], v[210:213], v[40:43]
	v_mfma_f32_16x16x32_bf16 v[28:31], v[144:147], v[218:221], v[28:31]
	v_mfma_f32_16x16x32_bf16 v[24:27], v[174:177], v[218:221], v[24:27]
	v_mfma_f32_16x16x32_bf16 v[12:15], v[144:147], v[226:229], v[12:15]
	v_mfma_f32_16x16x32_bf16 v[8:11], v[174:177], v[226:229], v[8:11]
	v_mfma_f32_16x16x32_bf16 v[60:63], v[170:173], v[206:209], v[60:63]
	v_mfma_f32_16x16x32_bf16 v[56:59], v[178:181], v[206:209], v[56:59]
	v_mfma_f32_16x16x32_bf16 v[44:47], v[170:173], v[214:217], v[44:47]
	v_mfma_f32_16x16x32_bf16 v[40:43], v[178:181], v[214:217], v[40:43]
	v_mfma_f32_16x16x32_bf16 v[28:31], v[170:173], v[222:225], v[28:31]
	v_mfma_f32_16x16x32_bf16 v[24:27], v[178:181], v[222:225], v[24:27]
	v_mfma_f32_16x16x32_bf16 v[12:15], v[170:173], v[230:233], v[12:15]
	v_mfma_f32_16x16x32_bf16 v[8:11], v[178:181], v[230:233], v[8:11]
	v_mfma_f32_16x16x32_bf16 v[52:55], v[186:189], v[202:205], v[52:55]
	v_mfma_f32_16x16x32_bf16 v[48:51], v[194:197], v[202:205], v[48:51]
	v_mfma_f32_16x16x32_bf16 v[36:39], v[186:189], v[210:213], v[36:39]
	v_mfma_f32_16x16x32_bf16 v[32:35], v[194:197], v[210:213], v[32:35]
	v_mfma_f32_16x16x32_bf16 v[20:23], v[186:189], v[218:221], v[20:23]
	v_mfma_f32_16x16x32_bf16 v[16:19], v[194:197], v[218:221], v[16:19]
	v_mfma_f32_16x16x32_bf16 v[4:7], v[186:189], v[226:229], v[4:7]
	v_mfma_f32_16x16x32_bf16 v[0:3], v[194:197], v[226:229], v[0:3]
	v_mfma_f32_16x16x32_bf16 v[52:55], v[190:193], v[206:209], v[52:55]
	v_mfma_f32_16x16x32_bf16 v[48:51], v[198:201], v[206:209], v[48:51]
	v_mfma_f32_16x16x32_bf16 v[36:39], v[190:193], v[214:217], v[36:39]
	v_mfma_f32_16x16x32_bf16 v[32:35], v[198:201], v[214:217], v[32:35]
	v_mfma_f32_16x16x32_bf16 v[20:23], v[190:193], v[222:225], v[20:23]
	v_mfma_f32_16x16x32_bf16 v[16:19], v[198:201], v[222:225], v[16:19]
	v_mfma_f32_16x16x32_bf16 v[4:7], v[190:193], v[230:233], v[4:7]
	v_mfma_f32_16x16x32_bf16 v[0:3], v[198:201], v[230:233], v[0:3]
	s_barrier
; #define PG8_STAGE(bufoff, gbase, voff) do { _Pragma("unroll") for (int _i = 0; _i < 2; ++_i) \
;         __builtin_amdgcn_global_load_lds((const unsigned*)((const char*)(gbase) + (voff)[_i]), (PG8_LAS unsigned*)(lds + (bufoff) + ldsw + _i * 8192), 16, 0, 0); } while (0)
; #define PG8_LDA(dst, b, h) do { _Pragma("unroll") for (int m = 0; m < 4; ++m) _Pragma("unroll") for (int k = 0; k < 2; ++k) dst[m][k] = *(const PG8_LAS bf16x8*)(lds + PG8_SA(b, h) + aoff + m * 2048 + k * 1024); } while (0)
; #define PG8_LDB(dst, b, h) do { _Pragma("unroll") for (int n = 0; n < 2; ++n) _Pragma("unroll") for (int k = 0; k < 2; ++k) dst[n][k] = *(const PG8_LAS bf16x8*)(lds + PG8_SB(b, h) + boff + n * 2048 + k * 1024); } while (0)
; #define PG8_MMA(ai, bj, At, Bt) do { __builtin_amdgcn_s_setprio(1); _Pragma("unroll") for (int m = 0; m < 4; ++m) _Pragma("unroll") for (int n = 0; n < 2; ++n) _Pragma("unroll") for (int k = 0; k < 2; ++k) \
;         acc[ai][bj][m][n] = __builtin_amdgcn_mfma_f32_16x16x32_bf16(Bt[n][k], At[m][k], acc[ai][bj][m][n], 0, 0, 0); __builtin_amdgcn_s_setprio(0); } while (0)
; #define PG8_WAIT_V(n) asm volatile("s_waitcnt vmcnt(" #n ")" ::: "memory")
; #define PG8_WAIT_L(n) asm volatile("s_waitcnt lgkmcnt(" #n ")" ::: "memory")
; #define PG8_BAR __builtin_amdgcn_s_barrier()
; #define PG8_SCHED __builtin_amdgcn_sched_barrier(0)
; template <class Epi, class Sched, bool ALIGN_EPI = false, bool SP2 = false>
; __device__ __forceinline__ void gemm_phase(PG8_LAS unsigned char* lds, const Gemm g, const Sched& S, const Epi& E) {
;     ...
;         for (int t = 0; t < nt; t += 2) {
;             const bool last = (t == nt - 2);
;             const char* a1 = cA + (size_t)(t + 1) * kstep;
;             const char* a2 = last ? nA : cA + (size_t)(t + 2) * kstep; const char* b2 = last ? nB : cB + (size_t)(t + 2) * kstep;
;     ...
;             PG8_LDB(B0, 1, 0); PG8_LDB(B1, 1, 1); PG8_SCHED; PG8_LDA(At, 1, 0); PG8_STAGE(PG8_SA(0, 1), a2 + hstep, voffA);
;             PG8_WAIT_V(8); PG8_WAIT_L(0); PG8_BAR; PG8_MMA(0, 0, At, B0); PG8_MMA(0, 1, At, B1); PG8_BAR; PG8_SCHED;
;             PG8_LDA(At, 1, 1); PG8_STAGE(PG8_SB(1, 0), b3, voffB); PG8_STAGE(PG8_SB(1, 1), b3 + hstep, voffB); PG8_STAGE(PG8_SA(1, 0), a3, voffA);
;             PG8_WAIT_V(8); PG8_WAIT_L(0); PG8_BAR; PG8_MMA(1, 0, At, B0); PG8_MMA(1, 1, At, B1); PG8_BAR; PG8_SCHED;
	ds_read_b128 v[144:147], v159
	ds_read_b128 v[170:173], v160
	ds_read_b128 v[174:177], v161
	ds_read_b128 v[178:181], v162
	ds_read_b128 v[186:189], v163
	ds_read_b128 v[190:193], v164
	ds_read_b128 v[194:197], v165
	ds_read_b128 v[198:201], v166
	s_add_u32 s34, s34, 0x40000
	s_addc_u32 s35, s35, 0
	s_mov_b32 m0, s49
	v_lshl_add_u64 v[240:241], s[34:35], 0, v[134:135]
	ds_read_b128 v[202:205], v149 offset:32768
	ds_read_b128 v[206:209], v149 offset:33792
	ds_read_b128 v[210:213], v149 offset:34816
	ds_read_b128 v[214:217], v149 offset:35840
	ds_read_b128 v[218:221], v149 offset:36864
	ds_read_b128 v[222:225], v149 offset:37888
	ds_read_b128 v[226:229], v149 offset:38912
	ds_read_b128 v[230:233], v149 offset:39936
	global_load_lds_dwordx4 v[240:241], off
	v_lshl_add_u64 v[240:241], s[34:35], 0, v[130:131]
	s_mov_b32 m0, s50
	s_nop 0
	global_load_lds_dwordx4 v[240:241], off
	s_waitcnt vmcnt(8)
	s_waitcnt lgkmcnt(0)
	s_barrier
	s_waitcnt lgkmcnt(0)
	v_mfma_f32_16x16x32_bf16 v[124:127], v[144:147], v[202:205], v[124:127]
	v_mfma_f32_16x16x32_bf16 v[120:123], v[174:177], v[202:205], v[120:123]
	v_mfma_f32_16x16x32_bf16 v[108:111], v[144:147], v[210:213], v[108:111]
	v_mfma_f32_16x16x32_bf16 v[104:107], v[174:177], v[210:213], v[104:107]
	v_mfma_f32_16x16x32_bf16 v[92:95], v[144:147], v[218:221], v[92:95]
	v_mfma_f32_16x16x32_bf16 v[88:91], v[174:177], v[218:221], v[88:91]
	v_mfma_f32_16x16x32_bf16 v[76:79], v[144:147], v[226:229], v[76:79]
	v_mfma_f32_16x16x32_bf16 v[72:75], v[174:177], v[226:229], v[72:75]
	v_mfma_f32_16x16x32_bf16 v[124:127], v[170:173], v[206:209], v[124:127]
	v_mfma_f32_16x16x32_bf16 v[120:123], v[178:181], v[206:209], v[120:123]
	v_mfma_f32_16x16x32_bf16 v[108:111], v[170:173], v[214:217], v[108:111]
	v_mfma_f32_16x16x32_bf16 v[104:107], v[178:181], v[214:217], v[104:107]
	v_mfma_f32_16x16x32_bf16 v[92:95], v[170:173], v[222:225], v[92:95]
	v_mfma_f32_16x16x32_bf16 v[88:91], v[178:181], v[222:225], v[88:91]
	v_mfma_f32_16x16x32_bf16 v[76:79], v[170:173], v[230:233], v[76:79]
	v_mfma_f32_16x16x32_bf16 v[72:75], v[178:181], v[230:233], v[72:75]
	v_mfma_f32_16x16x32_bf16 v[116:119], v[186:189], v[202:205], v[116:119]
	v_mfma_f32_16x16x32_bf16 v[112:115], v[194:197], v[202:205], v[112:115]
	v_mfma_f32_16x16x32_bf16 v[100:103], v[186:189], v[210:213], v[100:103]
	v_mfma_f32_16x16x32_bf16 v[96:99], v[194:197], v[210:213], v[96:99]
	v_mfma_f32_16x16x32_bf16 v[84:87], v[186:189], v[218:221], v[84:87]
	v_mfma_f32_16x16x32_bf16 v[80:83], v[194:197], v[218:221], v[80:83]
	v_mfma_f32_16x16x32_bf16 v[68:71], v[186:189], v[226:229], v[68:71]
	v_mfma_f32_16x16x32_bf16 v[64:67], v[194:197], v[226:229], v[64:67]
	v_mfma_f32_16x16x32_bf16 v[116:119], v[190:193], v[206:209], v[116:119]
	v_mfma_f32_16x16x32_bf16 v[112:115], v[198:201], v[206:209], v[112:115]
	v_mfma_f32_16x16x32_bf16 v[100:103], v[190:193], v[214:217], v[100:103]
	v_mfma_f32_16x16x32_bf16 v[96:99], v[198:201], v[214:217], v[96:99]
	v_mfma_f32_16x16x32_bf16 v[84:87], v[190:193], v[222:225], v[84:87]
	v_mfma_f32_16x16x32_bf16 v[80:83], v[198:201], v[222:225], v[80:83]
	v_mfma_f32_16x16x32_bf16 v[68:71], v[190:193], v[230:233], v[68:71]
	v_mfma_f32_16x16x32_bf16 v[64:67], v[198:201], v[230:233], v[64:67]
	s_barrier
	s_mov_b32 m0, s53
	v_lshl_add_u64 v[182:183], v[182:183], 0, s[16:17]
	s_add_u32 s30, s30, 0x40080
	ds_read_b128 v[202:205], v149 offset:49152
	ds_read_b128 v[206:209], v149 offset:50176
	ds_read_b128 v[210:213], v149 offset:51200
	ds_read_b128 v[214:217], v149 offset:52224
	ds_read_b128 v[218:221], v149 offset:53248
	ds_read_b128 v[222:225], v149 offset:54272
	ds_read_b128 v[226:229], v149 offset:55296
	ds_read_b128 v[230:233], v149 offset:56320
	global_load_lds_dwordx4 v[182:183], off
	v_lshl_add_u64 v[182:183], v[234:235], 0, s[16:17]
	s_mov_b32 m0, s54
	s_addc_u32 s31, s31, 0
	global_load_lds_dwordx4 v[182:183], off
	v_lshl_add_u64 v[182:183], s[30:31], 0, v[132:133]
	s_mov_b32 m0, s57
	s_nop 0
	global_load_lds_dwordx4 v[182:183], off
	v_lshl_add_u64 v[182:183], s[30:31], 0, v[128:129]
	s_mov_b32 m0, s58
	s_nop 0
	global_load_lds_dwordx4 v[182:183], off
	v_lshl_add_u64 v[182:183], v[236:237], 0, s[16:17]
	s_mov_b32 m0, s55
	s_nop 0
	global_load_lds_dwordx4 v[182:183], off
	v_lshl_add_u64 v[182:183], v[238:239], 0, s[16:17]
	s_mov_b32 m0, s56
	s_nop 0
	global_load_lds_dwordx4 v[182:183], off
	s_waitcnt vmcnt(8)
	s_waitcnt lgkmcnt(0)
	s_barrier
	s_waitcnt lgkmcnt(0)
	v_mfma_f32_16x16x32_bf16 v[60:63], v[144:147], v[202:205], v[60:63]
	v_mfma_f32_16x16x32_bf16 v[56:59], v[174:177], v[202:205], v[56:59]
	v_mfma_f32_16x16x32_bf16 v[44:47], v[144:147], v[210:213], v[44:47]
	v_mfma_f32_16x16x32_bf16 v[40:43], v[174:177], v[210:213], v[40:43]
	v_mfma_f32_16x16x32_bf16 v[28:31], v[144:147], v[218:221], v[28:31]
	v_mfma_f32_16x16x32_bf16 v[24:27], v[174:177], v[218:221], v[24:27]
	v_mfma_f32_16x16x32_bf16 v[12:15], v[144:147], v[226:229], v[12:15]
	v_mfma_f32_16x16x32_bf16 v[8:11], v[174:177], v[226:229], v[8:11]
	v_mfma_f32_16x16x32_bf16 v[60:63], v[170:173], v[206:209], v[60:63]
	v_mfma_f32_16x16x32_bf16 v[56:59], v[178:181], v[206:209], v[56:59]
	v_mfma_f32_16x16x32_bf16 v[44:47], v[170:173], v[214:217], v[44:47]
	v_mfma_f32_16x16x32_bf16 v[40:43], v[178:181], v[214:217], v[40:43]
	v_mfma_f32_16x16x32_bf16 v[28:31], v[170:173], v[222:225], v[28:31]
	v_mfma_f32_16x16x32_bf16 v[24:27], v[178:181], v[222:225], v[24:27]
	v_mfma_f32_16x16x32_bf16 v[12:15], v[170:173], v[230:233], v[12:15]
	v_mfma_f32_16x16x32_bf16 v[8:11], v[178:181], v[230:233], v[8:11]
	v_mfma_f32_16x16x32_bf16 v[52:55], v[186:189], v[202:205], v[52:55]
	v_mfma_f32_16x16x32_bf16 v[48:51], v[194:197], v[202:205], v[48:51]
	v_mfma_f32_16x16x32_bf16 v[36:39], v[186:189], v[210:213], v[36:39]
	v_mfma_f32_16x16x32_bf16 v[32:35], v[194:197], v[210:213], v[32:35]
	v_mfma_f32_16x16x32_bf16 v[20:23], v[186:189], v[218:221], v[20:23]
	v_mfma_f32_16x16x32_bf16 v[16:19], v[194:197], v[218:221], v[16:19]
	v_mfma_f32_16x16x32_bf16 v[4:7], v[186:189], v[226:229], v[4:7]
	v_mfma_f32_16x16x32_bf16 v[0:3], v[194:197], v[226:229], v[0:3]
	v_mfma_f32_16x16x32_bf16 v[52:55], v[190:193], v[206:209], v[52:55]
	v_mfma_f32_16x16x32_bf16 v[48:51], v[198:201], v[206:209], v[48:51]
	v_mfma_f32_16x16x32_bf16 v[36:39], v[190:193], v[214:217], v[36:39]
	v_mfma_f32_16x16x32_bf16 v[32:35], v[198:201], v[214:217], v[32:35]
	v_mfma_f32_16x16x32_bf16 v[20:23], v[190:193], v[222:225], v[20:23]
	v_mfma_f32_16x16x32_bf16 v[16:19], v[198:201], v[222:225], v[16:19]
	v_mfma_f32_16x16x32_bf16 v[4:7], v[190:193], v[230:233], v[4:7]
	v_mfma_f32_16x16x32_bf16 v[0:3], v[198:201], v[230:233], v[0:3]
	s_add_i32 s67, s67, 2
	s_add_u32 s65, s65, 0x100
	s_addc_u32 s66, s66, 0
	s_add_u32 s28, s28, 0x100
	s_addc_u32 s29, s29, 0
	s_cmp_gt_u32 s67, 13
	s_barrier
	s_cbranch_scc0 .LBB0_477
	s_and_b64 vcc, exec, s[18:19]
	s_cbranch_vccz .LBB0_480
	s_barrier

; #define PG8_STAGE(bufoff, gbase, voff) do { _Pragma("unroll") for (int _i = 0; _i < 2; ++_i) \
;         __builtin_amdgcn_global_load_lds((const unsigned*)((const char*)(gbase) + (voff)[_i]), (PG8_LAS unsigned*)(lds + (bufoff) + ldsw + _i * 8192), 16, 0, 0); } while (0)
; #define PG8_LDA(dst, b, h) do { _Pragma("unroll") for (int m = 0; m < 4; ++m) _Pragma("unroll") for (int k = 0; k < 2; ++k) dst[m][k] = *(const PG8_LAS bf16x8*)(lds + PG8_SA(b, h) + aoff + m * 2048 + k * 1024); } while (0)
; #define PG8_LDB(dst, b, h) do { _Pragma("unroll") for (int n = 0; n < 2; ++n) _Pragma("unroll") for (int k = 0; k < 2; ++k) dst[n][k] = *(const PG8_LAS bf16x8*)(lds + PG8_SB(b, h) + boff + n * 2048 + k * 1024); } while (0)
; #define PG8_MMA(ai, bj, At, Bt) do { __builtin_amdgcn_s_setprio(1); _Pragma("unroll") for (int m = 0; m < 4; ++m) _Pragma("unroll") for (int n = 0; n < 2; ++n) _Pragma("unroll") for (int k = 0; k < 2; ++k) \
;         acc[ai][bj][m][n] = __builtin_amdgcn_mfma_f32_16x16x32_bf16(Bt[n][k], At[m][k], acc[ai][bj][m][n], 0, 0, 0); __builtin_amdgcn_s_setprio(0); } while (0)
; #define PG8_WAIT_V(n) asm volatile("s_waitcnt vmcnt(" #n ")" ::: "memory")
; #define PG8_WAIT_L(n) asm volatile("s_waitcnt lgkmcnt(" #n ")" ::: "memory")
; #define PG8_BAR __builtin_amdgcn_s_barrier()
; #define PG8_SCHED __builtin_amdgcn_sched_barrier(0)
; template <class Epi, class Sched, bool ALIGN_EPI = false, bool SP2 = false>
; __device__ __forceinline__ void gemm_phase(PG8_LAS unsigned char* lds, const Gemm g, const Sched& S, const Epi& E) {
;     ...
;             PG8_LDB(B0, 0, 0); PG8_LDB(B1, 0, 1); PG8_SCHED; PG8_LDA(At, 0, 0); PG8_STAGE(PG8_SA(1, 1), a1 + hstep, voffA);
;             PG8_WAIT_V(8); PG8_WAIT_L(0); PG8_BAR; PG8_MMA(0, 0, At, B0); PG8_MMA(0, 1, At, B1); PG8_BAR; PG8_SCHED;
;             PG8_LDA(At, 0, 1); PG8_STAGE(PG8_SB(0, 0), b2, voffB); PG8_STAGE(PG8_SB(0, 1), b2 + hstep, voffB); PG8_STAGE(PG8_SA(0, 0), a2, voffA);
;             PG8_WAIT_V(8); PG8_WAIT_L(0); PG8_BAR; PG8_MMA(1, 0, At, B0); PG8_MMA(1, 1, At, B1); PG8_BAR; PG8_SCHED;
.LBB0_558:
	ds_read_b128 v[144:147], v151
	ds_read_b128 v[168:171], v152
	ds_read_b128 v[172:175], v153
	ds_read_b128 v[176:179], v154
	ds_read_b128 v[180:183], v155
	ds_read_b128 v[186:189], v156
	ds_read_b128 v[190:193], v157
	ds_read_b128 v[194:197], v158
	s_add_u32 s36, s34, 0xfff00080
	s_addc_u32 s37, s35, -1
	s_cmp_eq_u32 s70, 60
	s_cselect_b32 s43, s25, s37
	s_cselect_b32 s42, s31, s36
	s_cselect_b32 s37, s23, s69
	s_cselect_b32 s36, s67, s68
	s_mov_b32 m0, s64
	v_lshl_add_u64 v[230:231], s[34:35], 0, v[138:139]
	ds_read_b128 v[198:201], v149
	ds_read_b128 v[202:205], v149 offset:1024
	ds_read_b128 v[206:209], v149 offset:2048
	ds_read_b128 v[210:213], v149 offset:3072
	ds_read_b128 v[214:217], v149 offset:4096
	ds_read_b128 v[218:221], v149 offset:5120
	ds_read_b128 v[222:225], v149 offset:6144
	ds_read_b128 v[226:229], v149 offset:7168
	global_load_lds_dwordx4 v[230:231], off
	v_lshl_add_u64 v[230:231], s[34:35], 0, v[136:137]
	s_mov_b32 m0, s65
	s_nop 0
	global_load_lds_dwordx4 v[230:231], off
	s_waitcnt vmcnt(8)
	s_waitcnt lgkmcnt(0)
	s_barrier
	s_waitcnt lgkmcnt(0)
	v_mfma_f32_16x16x32_bf16 v[124:127], v[144:147], v[198:201], v[124:127]
	v_mfma_f32_16x16x32_bf16 v[120:123], v[172:175], v[198:201], v[120:123]
	v_mfma_f32_16x16x32_bf16 v[108:111], v[144:147], v[206:209], v[108:111]
	v_mfma_f32_16x16x32_bf16 v[104:107], v[172:175], v[206:209], v[104:107]
	v_mfma_f32_16x16x32_bf16 v[92:95], v[144:147], v[214:217], v[92:95]
	v_mfma_f32_16x16x32_bf16 v[88:91], v[172:175], v[214:217], v[88:91]
	v_mfma_f32_16x16x32_bf16 v[76:79], v[144:147], v[222:225], v[76:79]
	v_mfma_f32_16x16x32_bf16 v[72:75], v[172:175], v[222:225], v[72:75]
	v_mfma_f32_16x16x32_bf16 v[124:127], v[168:171], v[202:205], v[124:127]
	v_mfma_f32_16x16x32_bf16 v[120:123], v[176:179], v[202:205], v[120:123]
	v_mfma_f32_16x16x32_bf16 v[108:111], v[168:171], v[210:213], v[108:111]
	v_mfma_f32_16x16x32_bf16 v[104:107], v[176:179], v[210:213], v[104:107]
	v_mfma_f32_16x16x32_bf16 v[92:95], v[168:171], v[218:221], v[92:95]
	v_mfma_f32_16x16x32_bf16 v[88:91], v[176:179], v[218:221], v[88:91]
	v_mfma_f32_16x16x32_bf16 v[76:79], v[168:171], v[226:229], v[76:79]
	v_mfma_f32_16x16x32_bf16 v[72:75], v[176:179], v[226:229], v[72:75]
	v_mfma_f32_16x16x32_bf16 v[116:119], v[180:183], v[198:201], v[116:119]
	v_mfma_f32_16x16x32_bf16 v[112:115], v[190:193], v[198:201], v[112:115]
	v_mfma_f32_16x16x32_bf16 v[100:103], v[180:183], v[206:209], v[100:103]
	v_mfma_f32_16x16x32_bf16 v[96:99], v[190:193], v[206:209], v[96:99]
	v_mfma_f32_16x16x32_bf16 v[84:87], v[180:183], v[214:217], v[84:87]
	v_mfma_f32_16x16x32_bf16 v[80:83], v[190:193], v[214:217], v[80:83]
	v_mfma_f32_16x16x32_bf16 v[68:71], v[180:183], v[222:225], v[68:71]
	v_mfma_f32_16x16x32_bf16 v[64:67], v[190:193], v[222:225], v[64:67]
	v_mfma_f32_16x16x32_bf16 v[116:119], v[186:189], v[202:205], v[116:119]
	v_mfma_f32_16x16x32_bf16 v[112:115], v[194:197], v[202:205], v[112:115]
	v_mfma_f32_16x16x32_bf16 v[100:103], v[186:189], v[210:213], v[100:103]
	v_mfma_f32_16x16x32_bf16 v[96:99], v[194:197], v[210:213], v[96:99]
	v_mfma_f32_16x16x32_bf16 v[84:87], v[186:189], v[218:221], v[84:87]
	v_mfma_f32_16x16x32_bf16 v[80:83], v[194:197], v[218:221], v[80:83]
	v_mfma_f32_16x16x32_bf16 v[68:71], v[186:189], v[226:229], v[68:71]
	v_mfma_f32_16x16x32_bf16 v[64:67], v[194:197], v[226:229], v[64:67]
	s_barrier
	s_mov_b32 m0, s48
	v_lshl_add_u64 v[230:231], s[36:37], 0, v[130:131]
	s_add_u32 s72, s36, 0x100000
	ds_read_b128 v[198:201], v149 offset:16384
	ds_read_b128 v[202:205], v149 offset:17408
	ds_read_b128 v[206:209], v149 offset:18432
	ds_read_b128 v[210:213], v149 offset:19456
	ds_read_b128 v[214:217], v149 offset:20480
	ds_read_b128 v[218:221], v149 offset:21504
	ds_read_b128 v[222:225], v149 offset:22528
	ds_read_b128 v[226:229], v149 offset:23552
	global_load_lds_dwordx4 v[230:231], off
	v_lshl_add_u64 v[232:233], s[36:37], 0, v[134:135]
	s_mov_b32 m0, s49
	s_addc_u32 s73, s37, 0
	global_load_lds_dwordx4 v[232:233], off
	v_lshl_add_u64 v[234:235], s[72:73], 0, v[130:131]
	s_mov_b32 m0, s50
	v_lshl_add_u64 v[236:237], s[42:43], 0, v[132:133]
	global_load_lds_dwordx4 v[234:235], off
	v_lshl_add_u64 v[234:235], s[72:73], 0, v[134:135]
	s_mov_b32 m0, s51
	s_nop 0
	global_load_lds_dwordx4 v[234:235], off
	v_lshl_add_u64 v[234:235], s[42:43], 0, v[128:129]
	s_mov_b32 m0, s47
	s_nop 0
	global_load_lds_dwordx4 v[234:235], off
	s_mov_b32 m0, s52
	s_nop 0
	global_load_lds_dwordx4 v[236:237], off
	s_waitcnt vmcnt(8)
	s_waitcnt lgkmcnt(0)
	s_barrier
	s_waitcnt lgkmcnt(0)
	v_mfma_f32_16x16x32_bf16 v[60:63], v[144:147], v[198:201], v[60:63]
	v_mfma_f32_16x16x32_bf16 v[56:59], v[172:175], v[198:201], v[56:59]
	v_mfma_f32_16x16x32_bf16 v[44:47], v[144:147], v[206:209], v[44:47]
	v_mfma_f32_16x16x32_bf16 v[40:43], v[172:175], v[206:209], v[40:43]
	v_mfma_f32_16x16x32_bf16 v[28:31], v[144:147], v[214:217], v[28:31]
	v_mfma_f32_16x16x32_bf16 v[24:27], v[172:175], v[214:217], v[24:27]
	v_mfma_f32_16x16x32_bf16 v[12:15], v[144:147], v[222:225], v[12:15]
	v_mfma_f32_16x16x32_bf16 v[8:11], v[172:175], v[222:225], v[8:11]
	v_mfma_f32_16x16x32_bf16 v[60:63], v[168:171], v[202:205], v[60:63]
	v_mfma_f32_16x16x32_bf16 v[56:59], v[176:179], v[202:205], v[56:59]
	v_mfma_f32_16x16x32_bf16 v[44:47], v[168:171], v[210:213], v[44:47]
	v_mfma_f32_16x16x32_bf16 v[40:43], v[176:179], v[210:213], v[40:43]
	v_mfma_f32_16x16x32_bf16 v[28:31], v[168:171], v[218:221], v[28:31]
	v_mfma_f32_16x16x32_bf16 v[24:27], v[176:179], v[218:221], v[24:27]
	v_mfma_f32_16x16x32_bf16 v[12:15], v[168:171], v[226:229], v[12:15]
	v_mfma_f32_16x16x32_bf16 v[8:11], v[176:179], v[226:229], v[8:11]
	v_mfma_f32_16x16x32_bf16 v[52:55], v[180:183], v[198:201], v[52:55]
	v_mfma_f32_16x16x32_bf16 v[48:51], v[190:193], v[198:201], v[48:51]
	v_mfma_f32_16x16x32_bf16 v[36:39], v[180:183], v[206:209], v[36:39]
	v_mfma_f32_16x16x32_bf16 v[32:35], v[190:193], v[206:209], v[32:35]
	v_mfma_f32_16x16x32_bf16 v[20:23], v[180:183], v[214:217], v[20:23]
	v_mfma_f32_16x16x32_bf16 v[16:19], v[190:193], v[214:217], v[16:19]
	v_mfma_f32_16x16x32_bf16 v[4:7], v[180:183], v[222:225], v[4:7]
	v_mfma_f32_16x16x32_bf16 v[0:3], v[190:193], v[222:225], v[0:3]
	v_mfma_f32_16x16x32_bf16 v[52:55], v[186:189], v[202:205], v[52:55]
	v_mfma_f32_16x16x32_bf16 v[48:51], v[194:197], v[202:205], v[48:51]
	v_mfma_f32_16x16x32_bf16 v[36:39], v[186:189], v[210:213], v[36:39]
	v_mfma_f32_16x16x32_bf16 v[32:35], v[194:197], v[210:213], v[32:35]
	v_mfma_f32_16x16x32_bf16 v[20:23], v[186:189], v[218:221], v[20:23]
	v_mfma_f32_16x16x32_bf16 v[16:19], v[194:197], v[218:221], v[16:19]
	v_mfma_f32_16x16x32_bf16 v[4:7], v[186:189], v[226:229], v[4:7]
	v_mfma_f32_16x16x32_bf16 v[0:3], v[194:197], v[226:229], v[0:3]
	s_barrier
; #define PG8_STAGE(bufoff, gbase, voff) do { _Pragma("unroll") for (int _i = 0; _i < 2; ++_i) \
;         __builtin_amdgcn_global_load_lds((const unsigned*)((const char*)(gbase) + (voff)[_i]), (PG8_LAS unsigned*)(lds + (bufoff) + ldsw + _i * 8192), 16, 0, 0); } while (0)
; #define PG8_LDA(dst, b, h) do { _Pragma("unroll") for (int m = 0; m < 4; ++m) _Pragma("unroll") for (int k = 0; k < 2; ++k) dst[m][k] = *(const PG8_LAS bf16x8*)(lds + PG8_SA(b, h) + aoff + m * 2048 + k * 1024); } while (0)
; #define PG8_LDB(dst, b, h) do { _Pragma("unroll") for (int n = 0; n < 2; ++n) _Pragma("unroll") for (int k = 0; k < 2; ++k) dst[n][k] = *(const PG8_LAS bf16x8*)(lds + PG8_SB(b, h) + boff + n * 2048 + k * 1024); } while (0)
; #define PG8_MMA(ai, bj, At, Bt) do { __builtin_amdgcn_s_setprio(1); _Pragma("unroll") for (int m = 0; m < 4; ++m) _Pragma("unroll") for (int n = 0; n < 2; ++n) _Pragma("unroll") for (int k = 0; k < 2; ++k) \
;         acc[ai][bj][m][n] = __builtin_amdgcn_mfma_f32_16x16x32_bf16(Bt[n][k], At[m][k], acc[ai][bj][m][n], 0, 0, 0); __builtin_amdgcn_s_setprio(0); } while (0)
; #define PG8_WAIT_V(n) asm volatile("s_waitcnt vmcnt(" #n ")" ::: "memory")
; #define PG8_WAIT_L(n) asm volatile("s_waitcnt lgkmcnt(" #n ")" ::: "memory")
; #define PG8_BAR __builtin_amdgcn_s_barrier()
; #define PG8_SCHED __builtin_amdgcn_sched_barrier(0)
; template <class Epi, class Sched, bool ALIGN_EPI = false, bool SP2 = false>
; __device__ __forceinline__ void gemm_phase(PG8_LAS unsigned char* lds, const Gemm g, const Sched& S, const Epi& E) {
;     ...
;         for (int t = 0; t < nt; t += 2) {
;             const bool last = (t == nt - 2);
;             const char* a1 = cA + (size_t)(t + 1) * kstep;
;             const char* a2 = last ? nA : cA + (size_t)(t + 2) * kstep; const char* b2 = last ? nB : cB + (size_t)(t + 2) * kstep;
;     ...
;             PG8_LDB(B0, 1, 0); PG8_LDB(B1, 1, 1); PG8_SCHED; PG8_LDA(At, 1, 0); PG8_STAGE(PG8_SA(0, 1), a2 + hstep, voffA);
;             PG8_WAIT_V(8); PG8_WAIT_L(0); PG8_BAR; PG8_MMA(0, 0, At, B0); PG8_MMA(0, 1, At, B1); PG8_BAR; PG8_SCHED;
;             PG8_LDA(At, 1, 1); PG8_STAGE(PG8_SB(1, 0), b3, voffB); PG8_STAGE(PG8_SB(1, 1), b3 + hstep, voffB); PG8_STAGE(PG8_SA(1, 0), a3, voffA);
;             PG8_WAIT_V(8); PG8_WAIT_L(0); PG8_BAR; PG8_MMA(1, 0, At, B0); PG8_MMA(1, 1, At, B1); PG8_BAR; PG8_SCHED;
	ds_read_b128 v[144:147], v159
	ds_read_b128 v[168:171], v160
	ds_read_b128 v[172:175], v161
	ds_read_b128 v[176:179], v162
	ds_read_b128 v[180:183], v163
	ds_read_b128 v[186:189], v164
	ds_read_b128 v[190:193], v165
	ds_read_b128 v[194:197], v166
	s_add_u32 s42, s42, 0x100000
	s_addc_u32 s43, s43, 0
	s_mov_b32 m0, s53
	v_lshl_add_u64 v[238:239], s[42:43], 0, v[128:129]
	ds_read_b128 v[198:201], v149 offset:32768
	ds_read_b128 v[202:205], v149 offset:33792
	ds_read_b128 v[206:209], v149 offset:34816
	ds_read_b128 v[210:213], v149 offset:35840
	ds_read_b128 v[214:217], v149 offset:36864
	ds_read_b128 v[218:221], v149 offset:37888
	ds_read_b128 v[222:225], v149 offset:38912
	ds_read_b128 v[226:229], v149 offset:39936
	global_load_lds_dwordx4 v[238:239], off
	v_lshl_add_u64 v[238:239], s[42:43], 0, v[132:133]
	s_mov_b32 m0, s54
	s_nop 0
	global_load_lds_dwordx4 v[238:239], off
	s_waitcnt vmcnt(8)
	s_waitcnt lgkmcnt(0)
	s_barrier
	s_waitcnt lgkmcnt(0)
	v_mfma_f32_16x16x32_bf16 v[124:127], v[144:147], v[198:201], v[124:127]
	v_mfma_f32_16x16x32_bf16 v[120:123], v[172:175], v[198:201], v[120:123]
	v_mfma_f32_16x16x32_bf16 v[108:111], v[144:147], v[206:209], v[108:111]
	v_mfma_f32_16x16x32_bf16 v[104:107], v[172:175], v[206:209], v[104:107]
	v_mfma_f32_16x16x32_bf16 v[92:95], v[144:147], v[214:217], v[92:95]
	v_mfma_f32_16x16x32_bf16 v[88:91], v[172:175], v[214:217], v[88:91]
	v_mfma_f32_16x16x32_bf16 v[76:79], v[144:147], v[222:225], v[76:79]
	v_mfma_f32_16x16x32_bf16 v[72:75], v[172:175], v[222:225], v[72:75]
	v_mfma_f32_16x16x32_bf16 v[124:127], v[168:171], v[202:205], v[124:127]
	v_mfma_f32_16x16x32_bf16 v[120:123], v[176:179], v[202:205], v[120:123]
	v_mfma_f32_16x16x32_bf16 v[108:111], v[168:171], v[210:213], v[108:111]
	v_mfma_f32_16x16x32_bf16 v[104:107], v[176:179], v[210:213], v[104:107]
	v_mfma_f32_16x16x32_bf16 v[92:95], v[168:171], v[218:221], v[92:95]
	v_mfma_f32_16x16x32_bf16 v[88:91], v[176:179], v[218:221], v[88:91]
	v_mfma_f32_16x16x32_bf16 v[76:79], v[168:171], v[226:229], v[76:79]
	v_mfma_f32_16x16x32_bf16 v[72:75], v[176:179], v[226:229], v[72:75]
	v_mfma_f32_16x16x32_bf16 v[116:119], v[180:183], v[198:201], v[116:119]
	v_mfma_f32_16x16x32_bf16 v[112:115], v[190:193], v[198:201], v[112:115]
	v_mfma_f32_16x16x32_bf16 v[100:103], v[180:183], v[206:209], v[100:103]
	v_mfma_f32_16x16x32_bf16 v[96:99], v[190:193], v[206:209], v[96:99]
	v_mfma_f32_16x16x32_bf16 v[84:87], v[180:183], v[214:217], v[84:87]
	v_mfma_f32_16x16x32_bf16 v[80:83], v[190:193], v[214:217], v[80:83]
	v_mfma_f32_16x16x32_bf16 v[68:71], v[180:183], v[222:225], v[68:71]
	v_mfma_f32_16x16x32_bf16 v[64:67], v[190:193], v[222:225], v[64:67]
	v_mfma_f32_16x16x32_bf16 v[116:119], v[186:189], v[202:205], v[116:119]
	v_mfma_f32_16x16x32_bf16 v[112:115], v[194:197], v[202:205], v[112:115]
	v_mfma_f32_16x16x32_bf16 v[100:103], v[186:189], v[210:213], v[100:103]
	v_mfma_f32_16x16x32_bf16 v[96:99], v[194:197], v[210:213], v[96:99]
	v_mfma_f32_16x16x32_bf16 v[84:87], v[186:189], v[218:221], v[84:87]
	v_mfma_f32_16x16x32_bf16 v[80:83], v[194:197], v[218:221], v[80:83]
	v_mfma_f32_16x16x32_bf16 v[68:71], v[186:189], v[226:229], v[68:71]
	v_mfma_f32_16x16x32_bf16 v[64:67], v[194:197], v[226:229], v[64:67]
	s_barrier
	s_mov_b32 m0, s56
	v_lshl_add_u64 v[230:231], v[230:231], 0, s[16:17]
	s_add_u32 s36, s36, 0x100080
	ds_read_b128 v[198:201], v149 offset:49152
	ds_read_b128 v[202:205], v149 offset:50176
	ds_read_b128 v[206:209], v149 offset:51200
	ds_read_b128 v[210:213], v149 offset:52224
	ds_read_b128 v[214:217], v149 offset:53248
	ds_read_b128 v[218:221], v149 offset:54272
	ds_read_b128 v[222:225], v149 offset:55296
	ds_read_b128 v[226:229], v149 offset:56320
	global_load_lds_dwordx4 v[230:231], off
	v_lshl_add_u64 v[230:231], v[232:233], 0, s[16:17]
	s_mov_b32 m0, s57
	s_addc_u32 s37, s37, 0
	global_load_lds_dwordx4 v[230:231], off
	v_lshl_add_u64 v[230:231], s[36:37], 0, v[130:131]
	s_mov_b32 m0, s60
	s_nop 0
	global_load_lds_dwordx4 v[230:231], off
	v_lshl_add_u64 v[230:231], s[36:37], 0, v[134:135]
	s_mov_b32 m0, s61
	s_nop 0
	global_load_lds_dwordx4 v[230:231], off
	v_lshl_add_u64 v[230:231], v[234:235], 0, s[16:17]
	s_mov_b32 m0, s58
	s_nop 0
	global_load_lds_dwordx4 v[230:231], off
	v_lshl_add_u64 v[230:231], v[236:237], 0, s[16:17]
	s_mov_b32 m0, s59
	s_nop 0
	global_load_lds_dwordx4 v[230:231], off
	s_waitcnt vmcnt(8)
	s_waitcnt lgkmcnt(0)
	s_barrier
	s_waitcnt lgkmcnt(0)
	v_mfma_f32_16x16x32_bf16 v[60:63], v[144:147], v[198:201], v[60:63]
	v_mfma_f32_16x16x32_bf16 v[56:59], v[172:175], v[198:201], v[56:59]
	v_mfma_f32_16x16x32_bf16 v[44:47], v[144:147], v[206:209], v[44:47]
	v_mfma_f32_16x16x32_bf16 v[40:43], v[172:175], v[206:209], v[40:43]
	v_mfma_f32_16x16x32_bf16 v[28:31], v[144:147], v[214:217], v[28:31]
	v_mfma_f32_16x16x32_bf16 v[24:27], v[172:175], v[214:217], v[24:27]
	v_mfma_f32_16x16x32_bf16 v[12:15], v[144:147], v[222:225], v[12:15]
	v_mfma_f32_16x16x32_bf16 v[8:11], v[172:175], v[222:225], v[8:11]
	v_mfma_f32_16x16x32_bf16 v[60:63], v[168:171], v[202:205], v[60:63]
	v_mfma_f32_16x16x32_bf16 v[56:59], v[176:179], v[202:205], v[56:59]
	v_mfma_f32_16x16x32_bf16 v[44:47], v[168:171], v[210:213], v[44:47]
	v_mfma_f32_16x16x32_bf16 v[40:43], v[176:179], v[210:213], v[40:43]
	v_mfma_f32_16x16x32_bf16 v[28:31], v[168:171], v[218:221], v[28:31]
	v_mfma_f32_16x16x32_bf16 v[24:27], v[176:179], v[218:221], v[24:27]
	v_mfma_f32_16x16x32_bf16 v[12:15], v[168:171], v[226:229], v[12:15]
	v_mfma_f32_16x16x32_bf16 v[8:11], v[176:179], v[226:229], v[8:11]
	v_mfma_f32_16x16x32_bf16 v[52:55], v[180:183], v[198:201], v[52:55]
	v_mfma_f32_16x16x32_bf16 v[48:51], v[190:193], v[198:201], v[48:51]
	v_mfma_f32_16x16x32_bf16 v[36:39], v[180:183], v[206:209], v[36:39]
	v_mfma_f32_16x16x32_bf16 v[32:35], v[190:193], v[206:209], v[32:35]
	v_mfma_f32_16x16x32_bf16 v[20:23], v[180:183], v[214:217], v[20:23]
	v_mfma_f32_16x16x32_bf16 v[16:19], v[190:193], v[214:217], v[16:19]
	v_mfma_f32_16x16x32_bf16 v[4:7], v[180:183], v[222:225], v[4:7]
	v_mfma_f32_16x16x32_bf16 v[0:3], v[190:193], v[222:225], v[0:3]
	v_mfma_f32_16x16x32_bf16 v[52:55], v[186:189], v[202:205], v[52:55]
	v_mfma_f32_16x16x32_bf16 v[48:51], v[194:197], v[202:205], v[48:51]
	v_mfma_f32_16x16x32_bf16 v[36:39], v[186:189], v[210:213], v[36:39]
	v_mfma_f32_16x16x32_bf16 v[32:35], v[194:197], v[210:213], v[32:35]
	v_mfma_f32_16x16x32_bf16 v[20:23], v[186:189], v[218:221], v[20:23]
	v_mfma_f32_16x16x32_bf16 v[16:19], v[194:197], v[218:221], v[16:19]
	v_mfma_f32_16x16x32_bf16 v[4:7], v[186:189], v[226:229], v[4:7]
	v_mfma_f32_16x16x32_bf16 v[0:3], v[194:197], v[226:229], v[0:3]
	s_add_i32 s70, s70, 2
	s_add_u32 s68, s68, 0x100
	s_addc_u32 s69, s69, 0
	s_add_u32 s34, s34, 0x100
	s_addc_u32 s35, s35, 0
	s_cmp_gt_u32 s70, 61
	s_barrier
	s_cbranch_scc0 .LBB0_558
	s_and_b64 vcc, exec, s[18:19]
	s_cbranch_vccz .LBB0_561
	s_barrier

; #define PG8_STAGE(bufoff, gbase, voff) do { _Pragma("unroll") for (int _i = 0; _i < 2; ++_i) \
;         __builtin_amdgcn_global_load_lds((const unsigned*)((const char*)(gbase) + (voff)[_i]), (PG8_LAS unsigned*)(lds + (bufoff) + ldsw + _i * 8192), 16, 0, 0); } while (0)
; #define PG8_LDA(dst, b, h) do { _Pragma("unroll") for (int m = 0; m < 4; ++m) _Pragma("unroll") for (int k = 0; k < 2; ++k) dst[m][k] = *(const PG8_LAS bf16x8*)(lds + PG8_SA(b, h) + aoff + m * 2048 + k * 1024); } while (0)
; #define PG8_LDB(dst, b, h) do { _Pragma("unroll") for (int n = 0; n < 2; ++n) _Pragma("unroll") for (int k = 0; k < 2; ++k) dst[n][k] = *(const PG8_LAS bf16x8*)(lds + PG8_SB(b, h) + boff + n * 2048 + k * 1024); } while (0)
; #define PG8_MMA(ai, bj, At, Bt) do { __builtin_amdgcn_s_setprio(1); _Pragma("unroll") for (int m = 0; m < 4; ++m) _Pragma("unroll") for (int n = 0; n < 2; ++n) _Pragma("unroll") for (int k = 0; k < 2; ++k) \
;         acc[ai][bj][m][n] = __builtin_amdgcn_mfma_f32_16x16x32_bf16(Bt[n][k], At[m][k], acc[ai][bj][m][n], 0, 0, 0); __builtin_amdgcn_s_setprio(0); } while (0)
; #define PG8_WAIT_V(n) asm volatile("s_waitcnt vmcnt(" #n ")" ::: "memory")
; #define PG8_WAIT_L(n) asm volatile("s_waitcnt lgkmcnt(" #n ")" ::: "memory")
; #define PG8_BAR __builtin_amdgcn_s_barrier()
; #define PG8_SCHED __builtin_amdgcn_sched_barrier(0)
; template <class Epi, class Sched, bool ALIGN_EPI = false, bool SP2 = false>
; __device__ __forceinline__ void gemm_phase(PG8_LAS unsigned char* lds, const Gemm g, const Sched& S, const Epi& E) {
;     ...
;             PG8_LDB(B0, 0, 0); PG8_LDB(B1, 0, 1); PG8_SCHED; PG8_LDA(At, 0, 0); PG8_STAGE(PG8_SA(1, 1), a1 + hstep, voffA);
;             PG8_WAIT_V(8); PG8_WAIT_L(0); PG8_BAR; PG8_MMA(0, 0, At, B0); PG8_MMA(0, 1, At, B1); PG8_BAR; PG8_SCHED;
;             PG8_LDA(At, 0, 1); PG8_STAGE(PG8_SB(0, 0), b2, voffB); PG8_STAGE(PG8_SB(0, 1), b2 + hstep, voffB); PG8_STAGE(PG8_SA(0, 0), a2, voffA);
;             PG8_WAIT_V(8); PG8_WAIT_L(0); PG8_BAR; PG8_MMA(1, 0, At, B0); PG8_MMA(1, 1, At, B1); PG8_BAR; PG8_SCHED;
.LBB0_671:
	ds_read_b128 v[128:131], v161
	ds_read_b128 v[132:135], v162
	ds_read_b128 v[152:155], v163
	ds_read_b128 v[180:183], v164
	ds_read_b128 v[186:189], v165
	ds_read_b128 v[190:193], v166
	ds_read_b128 v[194:197], v167
	ds_read_b128 v[198:201], v168
	s_add_u32 s12, s10, 0xfffc0080
	s_addc_u32 s13, s11, -1
	s_cmp_eq_u32 s75, 12
	s_cselect_b32 s49, s9, s13
	s_cselect_b32 s48, s43, s12
	s_cselect_b32 s13, s37, s74
	s_cselect_b32 s12, s72, s73
	s_mov_b32 m0, s68
	v_lshl_add_u64 v[156:157], s[10:11], 0, v[146:147]
	ds_read_b128 v[202:205], v159
	ds_read_b128 v[206:209], v159 offset:1024
	ds_read_b128 v[210:213], v159 offset:2048
	ds_read_b128 v[214:217], v159 offset:3072
	ds_read_b128 v[218:221], v159 offset:4096
	ds_read_b128 v[222:225], v159 offset:5120
	ds_read_b128 v[226:229], v159 offset:6144
	ds_read_b128 v[230:233], v159 offset:7168
	global_load_lds_dwordx4 v[156:157], off
	v_lshl_add_u64 v[156:157], s[10:11], 0, v[144:145]
	s_mov_b32 m0, s69
	s_nop 0
	global_load_lds_dwordx4 v[156:157], off
	s_waitcnt vmcnt(8)
	s_waitcnt lgkmcnt(0)
	s_barrier
	s_waitcnt lgkmcnt(0)
	v_mfma_f32_16x16x32_bf16 v[124:127], v[128:131], v[202:205], v[124:127]
	v_mfma_f32_16x16x32_bf16 v[120:123], v[152:155], v[202:205], v[120:123]
	v_mfma_f32_16x16x32_bf16 v[108:111], v[128:131], v[210:213], v[108:111]
	v_mfma_f32_16x16x32_bf16 v[104:107], v[152:155], v[210:213], v[104:107]
	v_mfma_f32_16x16x32_bf16 v[92:95], v[128:131], v[218:221], v[92:95]
	v_mfma_f32_16x16x32_bf16 v[88:91], v[152:155], v[218:221], v[88:91]
	v_mfma_f32_16x16x32_bf16 v[76:79], v[128:131], v[226:229], v[76:79]
	v_mfma_f32_16x16x32_bf16 v[72:75], v[152:155], v[226:229], v[72:75]
	v_mfma_f32_16x16x32_bf16 v[124:127], v[132:135], v[206:209], v[124:127]
	v_mfma_f32_16x16x32_bf16 v[120:123], v[180:183], v[206:209], v[120:123]
	v_mfma_f32_16x16x32_bf16 v[108:111], v[132:135], v[214:217], v[108:111]
	v_mfma_f32_16x16x32_bf16 v[104:107], v[180:183], v[214:217], v[104:107]
	v_mfma_f32_16x16x32_bf16 v[92:95], v[132:135], v[222:225], v[92:95]
	v_mfma_f32_16x16x32_bf16 v[88:91], v[180:183], v[222:225], v[88:91]
	v_mfma_f32_16x16x32_bf16 v[76:79], v[132:135], v[230:233], v[76:79]
	v_mfma_f32_16x16x32_bf16 v[72:75], v[180:183], v[230:233], v[72:75]
	v_mfma_f32_16x16x32_bf16 v[116:119], v[186:189], v[202:205], v[116:119]
	v_mfma_f32_16x16x32_bf16 v[112:115], v[194:197], v[202:205], v[112:115]
	v_mfma_f32_16x16x32_bf16 v[100:103], v[186:189], v[210:213], v[100:103]
	v_mfma_f32_16x16x32_bf16 v[96:99], v[194:197], v[210:213], v[96:99]
	v_mfma_f32_16x16x32_bf16 v[84:87], v[186:189], v[218:221], v[84:87]
	v_mfma_f32_16x16x32_bf16 v[80:83], v[194:197], v[218:221], v[80:83]
	v_mfma_f32_16x16x32_bf16 v[68:71], v[186:189], v[226:229], v[68:71]
	v_mfma_f32_16x16x32_bf16 v[64:67], v[194:197], v[226:229], v[64:67]
	v_mfma_f32_16x16x32_bf16 v[116:119], v[190:193], v[206:209], v[116:119]
	v_mfma_f32_16x16x32_bf16 v[112:115], v[198:201], v[206:209], v[112:115]
	v_mfma_f32_16x16x32_bf16 v[100:103], v[190:193], v[214:217], v[100:103]
	v_mfma_f32_16x16x32_bf16 v[96:99], v[198:201], v[214:217], v[96:99]
	v_mfma_f32_16x16x32_bf16 v[84:87], v[190:193], v[222:225], v[84:87]
	v_mfma_f32_16x16x32_bf16 v[80:83], v[198:201], v[222:225], v[80:83]
	v_mfma_f32_16x16x32_bf16 v[68:71], v[190:193], v[230:233], v[68:71]
	v_mfma_f32_16x16x32_bf16 v[64:67], v[198:201], v[230:233], v[64:67]
	s_barrier
	s_mov_b32 m0, s52
	v_lshl_add_u64 v[156:157], s[12:13], 0, v[138:139]
	s_add_u32 s76, s12, 0x40000
	ds_read_b128 v[202:205], v159 offset:16384
	ds_read_b128 v[206:209], v159 offset:17408
	ds_read_b128 v[210:213], v159 offset:18432
	ds_read_b128 v[214:217], v159 offset:19456
	ds_read_b128 v[218:221], v159 offset:20480
	ds_read_b128 v[222:225], v159 offset:21504
	ds_read_b128 v[226:229], v159 offset:22528
	ds_read_b128 v[230:233], v159 offset:23552
	global_load_lds_dwordx4 v[156:157], off
	v_lshl_add_u64 v[234:235], s[12:13], 0, v[142:143]
	s_mov_b32 m0, s53
	s_addc_u32 s77, s13, 0
	global_load_lds_dwordx4 v[234:235], off
	v_lshl_add_u64 v[236:237], s[76:77], 0, v[138:139]
	s_mov_b32 m0, s54
	v_lshl_add_u64 v[238:239], s[48:49], 0, v[140:141]
	global_load_lds_dwordx4 v[236:237], off
	v_lshl_add_u64 v[236:237], s[76:77], 0, v[142:143]
	s_mov_b32 m0, s55
	s_nop 0
	global_load_lds_dwordx4 v[236:237], off
	v_lshl_add_u64 v[236:237], s[48:49], 0, v[136:137]
	s_mov_b32 m0, s51
	s_nop 0
	global_load_lds_dwordx4 v[236:237], off
	s_mov_b32 m0, s56
	s_nop 0
	global_load_lds_dwordx4 v[238:239], off
	s_waitcnt vmcnt(8)
	s_waitcnt lgkmcnt(0)
	s_barrier
	s_waitcnt lgkmcnt(0)
	v_mfma_f32_16x16x32_bf16 v[60:63], v[128:131], v[202:205], v[60:63]
	v_mfma_f32_16x16x32_bf16 v[56:59], v[152:155], v[202:205], v[56:59]
	v_mfma_f32_16x16x32_bf16 v[44:47], v[128:131], v[210:213], v[44:47]
	v_mfma_f32_16x16x32_bf16 v[40:43], v[152:155], v[210:213], v[40:43]
	v_mfma_f32_16x16x32_bf16 v[28:31], v[128:131], v[218:221], v[28:31]
	v_mfma_f32_16x16x32_bf16 v[24:27], v[152:155], v[218:221], v[24:27]
	v_mfma_f32_16x16x32_bf16 v[12:15], v[128:131], v[226:229], v[12:15]
	v_mfma_f32_16x16x32_bf16 v[8:11], v[152:155], v[226:229], v[8:11]
	v_mfma_f32_16x16x32_bf16 v[60:63], v[132:135], v[206:209], v[60:63]
	v_mfma_f32_16x16x32_bf16 v[56:59], v[180:183], v[206:209], v[56:59]
	v_mfma_f32_16x16x32_bf16 v[44:47], v[132:135], v[214:217], v[44:47]
	v_mfma_f32_16x16x32_bf16 v[40:43], v[180:183], v[214:217], v[40:43]
	v_mfma_f32_16x16x32_bf16 v[28:31], v[132:135], v[222:225], v[28:31]
	v_mfma_f32_16x16x32_bf16 v[24:27], v[180:183], v[222:225], v[24:27]
	v_mfma_f32_16x16x32_bf16 v[12:15], v[132:135], v[230:233], v[12:15]
	v_mfma_f32_16x16x32_bf16 v[8:11], v[180:183], v[230:233], v[8:11]
	v_mfma_f32_16x16x32_bf16 v[52:55], v[186:189], v[202:205], v[52:55]
	v_mfma_f32_16x16x32_bf16 v[48:51], v[194:197], v[202:205], v[48:51]
	v_mfma_f32_16x16x32_bf16 v[36:39], v[186:189], v[210:213], v[36:39]
	v_mfma_f32_16x16x32_bf16 v[32:35], v[194:197], v[210:213], v[32:35]
	v_mfma_f32_16x16x32_bf16 v[20:23], v[186:189], v[218:221], v[20:23]
	v_mfma_f32_16x16x32_bf16 v[16:19], v[194:197], v[218:221], v[16:19]
	v_mfma_f32_16x16x32_bf16 v[4:7], v[186:189], v[226:229], v[4:7]
	v_mfma_f32_16x16x32_bf16 v[0:3], v[194:197], v[226:229], v[0:3]
	v_mfma_f32_16x16x32_bf16 v[52:55], v[190:193], v[206:209], v[52:55]
	v_mfma_f32_16x16x32_bf16 v[48:51], v[198:201], v[206:209], v[48:51]
	v_mfma_f32_16x16x32_bf16 v[36:39], v[190:193], v[214:217], v[36:39]
	v_mfma_f32_16x16x32_bf16 v[32:35], v[198:201], v[214:217], v[32:35]
	v_mfma_f32_16x16x32_bf16 v[20:23], v[190:193], v[222:225], v[20:23]
	v_mfma_f32_16x16x32_bf16 v[16:19], v[198:201], v[222:225], v[16:19]
	v_mfma_f32_16x16x32_bf16 v[4:7], v[190:193], v[230:233], v[4:7]
	v_mfma_f32_16x16x32_bf16 v[0:3], v[198:201], v[230:233], v[0:3]
	s_barrier
; #define PG8_STAGE(bufoff, gbase, voff) do { _Pragma("unroll") for (int _i = 0; _i < 2; ++_i) \
;         __builtin_amdgcn_global_load_lds((const unsigned*)((const char*)(gbase) + (voff)[_i]), (PG8_LAS unsigned*)(lds + (bufoff) + ldsw + _i * 8192), 16, 0, 0); } while (0)
; #define PG8_LDA(dst, b, h) do { _Pragma("unroll") for (int m = 0; m < 4; ++m) _Pragma("unroll") for (int k = 0; k < 2; ++k) dst[m][k] = *(const PG8_LAS bf16x8*)(lds + PG8_SA(b, h) + aoff + m * 2048 + k * 1024); } while (0)
; #define PG8_LDB(dst, b, h) do { _Pragma("unroll") for (int n = 0; n < 2; ++n) _Pragma("unroll") for (int k = 0; k < 2; ++k) dst[n][k] = *(const PG8_LAS bf16x8*)(lds + PG8_SB(b, h) + boff + n * 2048 + k * 1024); } while (0)
; #define PG8_MMA(ai, bj, At, Bt) do { __builtin_amdgcn_s_setprio(1); _Pragma("unroll") for (int m = 0; m < 4; ++m) _Pragma("unroll") for (int n = 0; n < 2; ++n) _Pragma("unroll") for (int k = 0; k < 2; ++k) \
;         acc[ai][bj][m][n] = __builtin_amdgcn_mfma_f32_16x16x32_bf16(Bt[n][k], At[m][k], acc[ai][bj][m][n], 0, 0, 0); __builtin_amdgcn_s_setprio(0); } while (0)
; #define PG8_WAIT_V(n) asm volatile("s_waitcnt vmcnt(" #n ")" ::: "memory")
; #define PG8_WAIT_L(n) asm volatile("s_waitcnt lgkmcnt(" #n ")" ::: "memory")
; #define PG8_BAR __builtin_amdgcn_s_barrier()
; #define PG8_SCHED __builtin_amdgcn_sched_barrier(0)
; template <class Epi, class Sched, bool ALIGN_EPI = false, bool SP2 = false>
; __device__ __forceinline__ void gemm_phase(PG8_LAS unsigned char* lds, const Gemm g, const Sched& S, const Epi& E) {
;     ...
;         for (int t = 0; t < nt; t += 2) {
;             const bool last = (t == nt - 2);
;             const char* a1 = cA + (size_t)(t + 1) * kstep;
;             const char* a2 = last ? nA : cA + (size_t)(t + 2) * kstep; const char* b2 = last ? nB : cB + (size_t)(t + 2) * kstep;
;     ...
;             PG8_LDB(B0, 1, 0); PG8_LDB(B1, 1, 1); PG8_SCHED; PG8_LDA(At, 1, 0); PG8_STAGE(PG8_SA(0, 1), a2 + hstep, voffA);
;             PG8_WAIT_V(8); PG8_WAIT_L(0); PG8_BAR; PG8_MMA(0, 0, At, B0); PG8_MMA(0, 1, At, B1); PG8_BAR; PG8_SCHED;
;             PG8_LDA(At, 1, 1); PG8_STAGE(PG8_SB(1, 0), b3, voffB); PG8_STAGE(PG8_SB(1, 1), b3 + hstep, voffB); PG8_STAGE(PG8_SA(1, 0), a3, voffA);
;             PG8_WAIT_V(8); PG8_WAIT_L(0); PG8_BAR; PG8_MMA(1, 0, At, B0); PG8_MMA(1, 1, At, B1); PG8_BAR; PG8_SCHED;
	ds_read_b128 v[128:131], v169
	ds_read_b128 v[132:135], v170
	ds_read_b128 v[152:155], v171
	ds_read_b128 v[180:183], v172
	ds_read_b128 v[186:189], v173
	ds_read_b128 v[190:193], v174
	ds_read_b128 v[194:197], v175
	ds_read_b128 v[198:201], v176
	s_add_u32 s48, s48, 0x40000
	s_addc_u32 s49, s49, 0
	s_mov_b32 m0, s57
	v_lshl_add_u64 v[240:241], s[48:49], 0, v[136:137]
	ds_read_b128 v[202:205], v159 offset:32768
	ds_read_b128 v[206:209], v159 offset:33792
	ds_read_b128 v[210:213], v159 offset:34816
	ds_read_b128 v[214:217], v159 offset:35840
	ds_read_b128 v[218:221], v159 offset:36864
	ds_read_b128 v[222:225], v159 offset:37888
	ds_read_b128 v[226:229], v159 offset:38912
	ds_read_b128 v[230:233], v159 offset:39936
	global_load_lds_dwordx4 v[240:241], off
	v_lshl_add_u64 v[240:241], s[48:49], 0, v[140:141]
	s_mov_b32 m0, s58
	s_nop 0
	global_load_lds_dwordx4 v[240:241], off
	s_waitcnt vmcnt(8)
	s_waitcnt lgkmcnt(0)
	s_barrier
	s_waitcnt lgkmcnt(0)
	v_mfma_f32_16x16x32_bf16 v[124:127], v[128:131], v[202:205], v[124:127]
	v_mfma_f32_16x16x32_bf16 v[120:123], v[152:155], v[202:205], v[120:123]
	v_mfma_f32_16x16x32_bf16 v[108:111], v[128:131], v[210:213], v[108:111]
	v_mfma_f32_16x16x32_bf16 v[104:107], v[152:155], v[210:213], v[104:107]
	v_mfma_f32_16x16x32_bf16 v[92:95], v[128:131], v[218:221], v[92:95]
	v_mfma_f32_16x16x32_bf16 v[88:91], v[152:155], v[218:221], v[88:91]
	v_mfma_f32_16x16x32_bf16 v[76:79], v[128:131], v[226:229], v[76:79]
	v_mfma_f32_16x16x32_bf16 v[72:75], v[152:155], v[226:229], v[72:75]
	v_mfma_f32_16x16x32_bf16 v[124:127], v[132:135], v[206:209], v[124:127]
	v_mfma_f32_16x16x32_bf16 v[120:123], v[180:183], v[206:209], v[120:123]
	v_mfma_f32_16x16x32_bf16 v[108:111], v[132:135], v[214:217], v[108:111]
	v_mfma_f32_16x16x32_bf16 v[104:107], v[180:183], v[214:217], v[104:107]
	v_mfma_f32_16x16x32_bf16 v[92:95], v[132:135], v[222:225], v[92:95]
	v_mfma_f32_16x16x32_bf16 v[88:91], v[180:183], v[222:225], v[88:91]
	v_mfma_f32_16x16x32_bf16 v[76:79], v[132:135], v[230:233], v[76:79]
	v_mfma_f32_16x16x32_bf16 v[72:75], v[180:183], v[230:233], v[72:75]
	v_mfma_f32_16x16x32_bf16 v[116:119], v[186:189], v[202:205], v[116:119]
	v_mfma_f32_16x16x32_bf16 v[112:115], v[194:197], v[202:205], v[112:115]
	v_mfma_f32_16x16x32_bf16 v[100:103], v[186:189], v[210:213], v[100:103]
	v_mfma_f32_16x16x32_bf16 v[96:99], v[194:197], v[210:213], v[96:99]
	v_mfma_f32_16x16x32_bf16 v[84:87], v[186:189], v[218:221], v[84:87]
	v_mfma_f32_16x16x32_bf16 v[80:83], v[194:197], v[218:221], v[80:83]
	v_mfma_f32_16x16x32_bf16 v[68:71], v[186:189], v[226:229], v[68:71]
	v_mfma_f32_16x16x32_bf16 v[64:67], v[194:197], v[226:229], v[64:67]
	v_mfma_f32_16x16x32_bf16 v[116:119], v[190:193], v[206:209], v[116:119]
	v_mfma_f32_16x16x32_bf16 v[112:115], v[198:201], v[206:209], v[112:115]
	v_mfma_f32_16x16x32_bf16 v[100:103], v[190:193], v[214:217], v[100:103]
	v_mfma_f32_16x16x32_bf16 v[96:99], v[198:201], v[214:217], v[96:99]
	v_mfma_f32_16x16x32_bf16 v[84:87], v[190:193], v[222:225], v[84:87]
	v_mfma_f32_16x16x32_bf16 v[80:83], v[198:201], v[222:225], v[80:83]
	v_mfma_f32_16x16x32_bf16 v[68:71], v[190:193], v[230:233], v[68:71]
	v_mfma_f32_16x16x32_bf16 v[64:67], v[198:201], v[230:233], v[64:67]
	s_barrier
	s_mov_b32 m0, s60
	v_lshl_add_u64 v[156:157], v[156:157], 0, s[28:29]
	s_add_u32 s12, s12, 0x40080
	ds_read_b128 v[202:205], v159 offset:49152
	ds_read_b128 v[206:209], v159 offset:50176
	ds_read_b128 v[210:213], v159 offset:51200
	ds_read_b128 v[214:217], v159 offset:52224
	ds_read_b128 v[218:221], v159 offset:53248
	ds_read_b128 v[222:225], v159 offset:54272
	ds_read_b128 v[226:229], v159 offset:55296
	ds_read_b128 v[230:233], v159 offset:56320
	global_load_lds_dwordx4 v[156:157], off
	v_lshl_add_u64 v[156:157], v[234:235], 0, s[28:29]
	s_mov_b32 m0, s61
	s_addc_u32 s13, s13, 0
	global_load_lds_dwordx4 v[156:157], off
	v_lshl_add_u64 v[156:157], s[12:13], 0, v[138:139]
	s_mov_b32 m0, s64
	s_nop 0
	global_load_lds_dwordx4 v[156:157], off
	v_lshl_add_u64 v[156:157], s[12:13], 0, v[142:143]
	s_mov_b32 m0, s65
	s_nop 0
	global_load_lds_dwordx4 v[156:157], off
	v_lshl_add_u64 v[156:157], v[236:237], 0, s[28:29]
	s_mov_b32 m0, s62
	s_nop 0
	global_load_lds_dwordx4 v[156:157], off
	v_lshl_add_u64 v[156:157], v[238:239], 0, s[28:29]
	s_mov_b32 m0, s63
	s_nop 0
	global_load_lds_dwordx4 v[156:157], off
	s_waitcnt vmcnt(8)
	s_waitcnt lgkmcnt(0)
	s_barrier
	s_waitcnt lgkmcnt(0)
	v_mfma_f32_16x16x32_bf16 v[60:63], v[128:131], v[202:205], v[60:63]
	v_mfma_f32_16x16x32_bf16 v[56:59], v[152:155], v[202:205], v[56:59]
	v_mfma_f32_16x16x32_bf16 v[44:47], v[128:131], v[210:213], v[44:47]
	v_mfma_f32_16x16x32_bf16 v[40:43], v[152:155], v[210:213], v[40:43]
	v_mfma_f32_16x16x32_bf16 v[28:31], v[128:131], v[218:221], v[28:31]
	v_mfma_f32_16x16x32_bf16 v[24:27], v[152:155], v[218:221], v[24:27]
	v_mfma_f32_16x16x32_bf16 v[12:15], v[128:131], v[226:229], v[12:15]
	v_mfma_f32_16x16x32_bf16 v[8:11], v[152:155], v[226:229], v[8:11]
	v_mfma_f32_16x16x32_bf16 v[60:63], v[132:135], v[206:209], v[60:63]
	v_mfma_f32_16x16x32_bf16 v[56:59], v[180:183], v[206:209], v[56:59]
	v_mfma_f32_16x16x32_bf16 v[44:47], v[132:135], v[214:217], v[44:47]
	v_mfma_f32_16x16x32_bf16 v[40:43], v[180:183], v[214:217], v[40:43]
	v_mfma_f32_16x16x32_bf16 v[28:31], v[132:135], v[222:225], v[28:31]
	v_mfma_f32_16x16x32_bf16 v[24:27], v[180:183], v[222:225], v[24:27]
	v_mfma_f32_16x16x32_bf16 v[12:15], v[132:135], v[230:233], v[12:15]
	v_mfma_f32_16x16x32_bf16 v[8:11], v[180:183], v[230:233], v[8:11]
	v_mfma_f32_16x16x32_bf16 v[52:55], v[186:189], v[202:205], v[52:55]
	v_mfma_f32_16x16x32_bf16 v[48:51], v[194:197], v[202:205], v[48:51]
	v_mfma_f32_16x16x32_bf16 v[36:39], v[186:189], v[210:213], v[36:39]
	v_mfma_f32_16x16x32_bf16 v[32:35], v[194:197], v[210:213], v[32:35]
	v_mfma_f32_16x16x32_bf16 v[20:23], v[186:189], v[218:221], v[20:23]
	v_mfma_f32_16x16x32_bf16 v[16:19], v[194:197], v[218:221], v[16:19]
	v_mfma_f32_16x16x32_bf16 v[4:7], v[186:189], v[226:229], v[4:7]
	v_mfma_f32_16x16x32_bf16 v[0:3], v[194:197], v[226:229], v[0:3]
	v_mfma_f32_16x16x32_bf16 v[52:55], v[190:193], v[206:209], v[52:55]
	v_mfma_f32_16x16x32_bf16 v[48:51], v[198:201], v[206:209], v[48:51]
	v_mfma_f32_16x16x32_bf16 v[36:39], v[190:193], v[214:217], v[36:39]
	v_mfma_f32_16x16x32_bf16 v[32:35], v[198:201], v[214:217], v[32:35]
	v_mfma_f32_16x16x32_bf16 v[20:23], v[190:193], v[222:225], v[20:23]
	v_mfma_f32_16x16x32_bf16 v[16:19], v[198:201], v[222:225], v[16:19]
	v_mfma_f32_16x16x32_bf16 v[4:7], v[190:193], v[230:233], v[4:7]
	v_mfma_f32_16x16x32_bf16 v[0:3], v[198:201], v[230:233], v[0:3]
	s_add_i32 s75, s75, 2
	s_add_u32 s73, s73, 0x100
	s_addc_u32 s74, s74, 0
	s_add_u32 s10, s10, 0x100
	s_addc_u32 s11, s11, 0
	s_cmp_gt_u32 s75, 13
	s_barrier
	s_cbranch_scc0 .LBB0_671
	s_and_b64 vcc, exec, s[30:31]
	s_cbranch_vccz .LBB0_674
	s_barrier

; #define PG8_STAGE(bufoff, gbase, voff) do { _Pragma("unroll") for (int _i = 0; _i < 2; ++_i) \
;         __builtin_amdgcn_global_load_lds((const unsigned*)((const char*)(gbase) + (voff)[_i]), (PG8_LAS unsigned*)(lds + (bufoff) + ldsw + _i * 8192), 16, 0, 0); } while (0)
; #define PG8_LDA(dst, b, h) do { _Pragma("unroll") for (int m = 0; m < 4; ++m) _Pragma("unroll") for (int k = 0; k < 2; ++k) dst[m][k] = *(const PG8_LAS bf16x8*)(lds + PG8_SA(b, h) + aoff + m * 2048 + k * 1024); } while (0)
; #define PG8_LDB(dst, b, h) do { _Pragma("unroll") for (int n = 0; n < 2; ++n) _Pragma("unroll") for (int k = 0; k < 2; ++k) dst[n][k] = *(const PG8_LAS bf16x8*)(lds + PG8_SB(b, h) + boff + n * 2048 + k * 1024); } while (0)
; #define PG8_MMA(ai, bj, At, Bt) do { __builtin_amdgcn_s_setprio(1); _Pragma("unroll") for (int m = 0; m < 4; ++m) _Pragma("unroll") for (int n = 0; n < 2; ++n) _Pragma("unroll") for (int k = 0; k < 2; ++k) \
;         acc[ai][bj][m][n] = __builtin_amdgcn_mfma_f32_16x16x32_bf16(Bt[n][k], At[m][k], acc[ai][bj][m][n], 0, 0, 0); __builtin_amdgcn_s_setprio(0); } while (0)
; #define PG8_WAIT_V(n) asm volatile("s_waitcnt vmcnt(" #n ")" ::: "memory")
; #define PG8_WAIT_L(n) asm volatile("s_waitcnt lgkmcnt(" #n ")" ::: "memory")
; #define PG8_BAR __builtin_amdgcn_s_barrier()
; #define PG8_SCHED __builtin_amdgcn_sched_barrier(0)
; template <class Epi, class Sched, bool ALIGN_EPI = false, bool SP2 = false>
; __device__ __forceinline__ void gemm_phase(PG8_LAS unsigned char* lds, const Gemm g, const Sched& S, const Epi& E) {
;     ...
;             PG8_LDB(B0, 0, 0); PG8_LDB(B1, 0, 1); PG8_SCHED; PG8_LDA(At, 0, 0); PG8_STAGE(PG8_SA(1, 1), a1 + hstep, voffA);
;             PG8_WAIT_V(8); PG8_WAIT_L(0); PG8_BAR; PG8_MMA(0, 0, At, B0); PG8_MMA(0, 1, At, B1); PG8_BAR; PG8_SCHED;
;             PG8_LDA(At, 0, 1); PG8_STAGE(PG8_SB(0, 0), b2, voffB); PG8_STAGE(PG8_SB(0, 1), b2 + hstep, voffB); PG8_STAGE(PG8_SA(0, 0), a2, voffA);
;             PG8_WAIT_V(8); PG8_WAIT_L(0); PG8_BAR; PG8_MMA(1, 0, At, B0); PG8_MMA(1, 1, At, B1); PG8_BAR; PG8_SCHED;
.LBB0_760:
	ds_read_b128 v[128:131], v188
	ds_read_b128 v[132:135], v189
	ds_read_b128 v[136:139], v190
	ds_read_b128 v[140:143], v191
	ds_read_b128 v[144:147], v192
	ds_read_b128 v[148:151], v193
	ds_read_b128 v[172:175], v194
	ds_read_b128 v[176:179], v195
	s_add_u32 s46, s44, 0xfffc0080
	s_addc_u32 s47, s45, -1
	s_cmp_eq_u32 s74, 12
	s_cselect_b32 s49, s9, s47
	s_cselect_b32 s48, s11, s46
	s_cselect_b32 s47, s31, s73
	s_cselect_b32 s46, s35, s72
	s_mov_b32 m0, s68
	v_lshl_add_u64 v[236:237], s[44:45], 0, v[166:167]
	ds_read_b128 v[180:183], v186
	ds_read_b128 v[208:211], v186 offset:1024
	ds_read_b128 v[212:215], v186 offset:2048
	ds_read_b128 v[216:219], v186 offset:3072
	ds_read_b128 v[220:223], v186 offset:4096
	ds_read_b128 v[224:227], v186 offset:5120
	ds_read_b128 v[228:231], v186 offset:6144
	ds_read_b128 v[232:235], v186 offset:7168
	global_load_lds_dwordx4 v[236:237], off
	v_lshl_add_u64 v[236:237], s[44:45], 0, v[164:165]
	s_mov_b32 m0, s69
	s_nop 0
	global_load_lds_dwordx4 v[236:237], off
	s_waitcnt vmcnt(8)
	s_waitcnt lgkmcnt(0)
	s_barrier
	s_waitcnt lgkmcnt(0)
	v_mfma_f32_16x16x32_bf16 v[124:127], v[128:131], v[180:183], v[124:127]
	v_mfma_f32_16x16x32_bf16 v[120:123], v[136:139], v[180:183], v[120:123]
	v_mfma_f32_16x16x32_bf16 v[108:111], v[128:131], v[212:215], v[108:111]
	v_mfma_f32_16x16x32_bf16 v[104:107], v[136:139], v[212:215], v[104:107]
	v_mfma_f32_16x16x32_bf16 v[92:95], v[128:131], v[220:223], v[92:95]
	v_mfma_f32_16x16x32_bf16 v[88:91], v[136:139], v[220:223], v[88:91]
	v_mfma_f32_16x16x32_bf16 v[76:79], v[128:131], v[228:231], v[76:79]
	v_mfma_f32_16x16x32_bf16 v[72:75], v[136:139], v[228:231], v[72:75]
	v_mfma_f32_16x16x32_bf16 v[124:127], v[132:135], v[208:211], v[124:127]
	v_mfma_f32_16x16x32_bf16 v[120:123], v[140:143], v[208:211], v[120:123]
	v_mfma_f32_16x16x32_bf16 v[108:111], v[132:135], v[216:219], v[108:111]
	v_mfma_f32_16x16x32_bf16 v[104:107], v[140:143], v[216:219], v[104:107]
	v_mfma_f32_16x16x32_bf16 v[92:95], v[132:135], v[224:227], v[92:95]
	v_mfma_f32_16x16x32_bf16 v[88:91], v[140:143], v[224:227], v[88:91]
	v_mfma_f32_16x16x32_bf16 v[76:79], v[132:135], v[232:235], v[76:79]
	v_mfma_f32_16x16x32_bf16 v[72:75], v[140:143], v[232:235], v[72:75]
	v_mfma_f32_16x16x32_bf16 v[116:119], v[144:147], v[180:183], v[116:119]
	v_mfma_f32_16x16x32_bf16 v[112:115], v[172:175], v[180:183], v[112:115]
	v_mfma_f32_16x16x32_bf16 v[100:103], v[144:147], v[212:215], v[100:103]
	v_mfma_f32_16x16x32_bf16 v[96:99], v[172:175], v[212:215], v[96:99]
	v_mfma_f32_16x16x32_bf16 v[84:87], v[144:147], v[220:223], v[84:87]
	v_mfma_f32_16x16x32_bf16 v[80:83], v[172:175], v[220:223], v[80:83]
	v_mfma_f32_16x16x32_bf16 v[68:71], v[144:147], v[228:231], v[68:71]
	v_mfma_f32_16x16x32_bf16 v[64:67], v[172:175], v[228:231], v[64:67]
	v_mfma_f32_16x16x32_bf16 v[116:119], v[148:151], v[208:211], v[116:119]
	v_mfma_f32_16x16x32_bf16 v[112:115], v[176:179], v[208:211], v[112:115]
	v_mfma_f32_16x16x32_bf16 v[100:103], v[148:151], v[216:219], v[100:103]
	v_mfma_f32_16x16x32_bf16 v[96:99], v[176:179], v[216:219], v[96:99]
	v_mfma_f32_16x16x32_bf16 v[84:87], v[148:151], v[224:227], v[84:87]
	v_mfma_f32_16x16x32_bf16 v[80:83], v[176:179], v[224:227], v[80:83]
	v_mfma_f32_16x16x32_bf16 v[68:71], v[148:151], v[232:235], v[68:71]
	v_mfma_f32_16x16x32_bf16 v[64:67], v[176:179], v[232:235], v[64:67]
	s_barrier
	s_mov_b32 m0, s51
	v_lshl_add_u64 v[236:237], s[46:47], 0, v[154:155]
	s_add_u32 s76, s46, 0x40000
	ds_read_b128 v[180:183], v186 offset:16384
	ds_read_b128 v[208:211], v186 offset:17408
	ds_read_b128 v[212:215], v186 offset:18432
	ds_read_b128 v[216:219], v186 offset:19456
	ds_read_b128 v[220:223], v186 offset:20480
	ds_read_b128 v[224:227], v186 offset:21504
	ds_read_b128 v[228:231], v186 offset:22528
	ds_read_b128 v[232:235], v186 offset:23552
	global_load_lds_dwordx4 v[236:237], off
	v_lshl_add_u64 v[238:239], s[46:47], 0, v[158:159]
	s_mov_b32 m0, s52
	s_addc_u32 s77, s47, 0
	global_load_lds_dwordx4 v[238:239], off
	v_lshl_add_u64 v[240:241], s[76:77], 0, v[154:155]
	s_mov_b32 m0, s53
	v_lshl_add_u64 v[242:243], s[48:49], 0, v[156:157]
	global_load_lds_dwordx4 v[240:241], off
	v_lshl_add_u64 v[240:241], s[76:77], 0, v[158:159]
	s_mov_b32 m0, s54
	s_nop 0
	global_load_lds_dwordx4 v[240:241], off
	v_lshl_add_u64 v[240:241], s[48:49], 0, v[152:153]
	s_mov_b32 m0, s50
	s_nop 0
	global_load_lds_dwordx4 v[240:241], off
	s_mov_b32 m0, s55
	s_nop 0
	global_load_lds_dwordx4 v[242:243], off
	s_waitcnt vmcnt(8)
	s_waitcnt lgkmcnt(0)
	s_barrier
	s_waitcnt lgkmcnt(0)
	v_mfma_f32_16x16x32_bf16 v[60:63], v[128:131], v[180:183], v[60:63]
	v_mfma_f32_16x16x32_bf16 v[56:59], v[136:139], v[180:183], v[56:59]
	v_mfma_f32_16x16x32_bf16 v[44:47], v[128:131], v[212:215], v[44:47]
	v_mfma_f32_16x16x32_bf16 v[40:43], v[136:139], v[212:215], v[40:43]
	v_mfma_f32_16x16x32_bf16 v[28:31], v[128:131], v[220:223], v[28:31]
	v_mfma_f32_16x16x32_bf16 v[24:27], v[136:139], v[220:223], v[24:27]
	v_mfma_f32_16x16x32_bf16 v[12:15], v[128:131], v[228:231], v[12:15]
	v_mfma_f32_16x16x32_bf16 v[8:11], v[136:139], v[228:231], v[8:11]
	v_mfma_f32_16x16x32_bf16 v[60:63], v[132:135], v[208:211], v[60:63]
	v_mfma_f32_16x16x32_bf16 v[56:59], v[140:143], v[208:211], v[56:59]
	v_mfma_f32_16x16x32_bf16 v[44:47], v[132:135], v[216:219], v[44:47]
	v_mfma_f32_16x16x32_bf16 v[40:43], v[140:143], v[216:219], v[40:43]
	v_mfma_f32_16x16x32_bf16 v[28:31], v[132:135], v[224:227], v[28:31]
	v_mfma_f32_16x16x32_bf16 v[24:27], v[140:143], v[224:227], v[24:27]
	v_mfma_f32_16x16x32_bf16 v[12:15], v[132:135], v[232:235], v[12:15]
	v_mfma_f32_16x16x32_bf16 v[8:11], v[140:143], v[232:235], v[8:11]
	v_mfma_f32_16x16x32_bf16 v[52:55], v[144:147], v[180:183], v[52:55]
	v_mfma_f32_16x16x32_bf16 v[48:51], v[172:175], v[180:183], v[48:51]
	v_mfma_f32_16x16x32_bf16 v[36:39], v[144:147], v[212:215], v[36:39]
	v_mfma_f32_16x16x32_bf16 v[32:35], v[172:175], v[212:215], v[32:35]
	v_mfma_f32_16x16x32_bf16 v[20:23], v[144:147], v[220:223], v[20:23]
	v_mfma_f32_16x16x32_bf16 v[16:19], v[172:175], v[220:223], v[16:19]
	v_mfma_f32_16x16x32_bf16 v[4:7], v[144:147], v[228:231], v[4:7]
	v_mfma_f32_16x16x32_bf16 v[0:3], v[172:175], v[228:231], v[0:3]
	v_mfma_f32_16x16x32_bf16 v[52:55], v[148:151], v[208:211], v[52:55]
	v_mfma_f32_16x16x32_bf16 v[48:51], v[176:179], v[208:211], v[48:51]
	v_mfma_f32_16x16x32_bf16 v[36:39], v[148:151], v[216:219], v[36:39]
	v_mfma_f32_16x16x32_bf16 v[32:35], v[176:179], v[216:219], v[32:35]
	v_mfma_f32_16x16x32_bf16 v[20:23], v[148:151], v[224:227], v[20:23]
	v_mfma_f32_16x16x32_bf16 v[16:19], v[176:179], v[224:227], v[16:19]
	v_mfma_f32_16x16x32_bf16 v[4:7], v[148:151], v[232:235], v[4:7]
	v_mfma_f32_16x16x32_bf16 v[0:3], v[176:179], v[232:235], v[0:3]
	s_barrier
; #define PG8_STAGE(bufoff, gbase, voff) do { _Pragma("unroll") for (int _i = 0; _i < 2; ++_i) \
;         __builtin_amdgcn_global_load_lds((const unsigned*)((const char*)(gbase) + (voff)[_i]), (PG8_LAS unsigned*)(lds + (bufoff) + ldsw + _i * 8192), 16, 0, 0); } while (0)
; #define PG8_LDA(dst, b, h) do { _Pragma("unroll") for (int m = 0; m < 4; ++m) _Pragma("unroll") for (int k = 0; k < 2; ++k) dst[m][k] = *(const PG8_LAS bf16x8*)(lds + PG8_SA(b, h) + aoff + m * 2048 + k * 1024); } while (0)
; #define PG8_LDB(dst, b, h) do { _Pragma("unroll") for (int n = 0; n < 2; ++n) _Pragma("unroll") for (int k = 0; k < 2; ++k) dst[n][k] = *(const PG8_LAS bf16x8*)(lds + PG8_SB(b, h) + boff + n * 2048 + k * 1024); } while (0)
; #define PG8_MMA(ai, bj, At, Bt) do { __builtin_amdgcn_s_setprio(1); _Pragma("unroll") for (int m = 0; m < 4; ++m) _Pragma("unroll") for (int n = 0; n < 2; ++n) _Pragma("unroll") for (int k = 0; k < 2; ++k) \
;         acc[ai][bj][m][n] = __builtin_amdgcn_mfma_f32_16x16x32_bf16(Bt[n][k], At[m][k], acc[ai][bj][m][n], 0, 0, 0); __builtin_amdgcn_s_setprio(0); } while (0)
; #define PG8_WAIT_V(n) asm volatile("s_waitcnt vmcnt(" #n ")" ::: "memory")
; #define PG8_WAIT_L(n) asm volatile("s_waitcnt lgkmcnt(" #n ")" ::: "memory")
; #define PG8_BAR __builtin_amdgcn_s_barrier()
; #define PG8_SCHED __builtin_amdgcn_sched_barrier(0)
; template <class Epi, class Sched, bool ALIGN_EPI = false, bool SP2 = false>
; __device__ __forceinline__ void gemm_phase(PG8_LAS unsigned char* lds, const Gemm g, const Sched& S, const Epi& E) {
;     ...
;         for (int t = 0; t < nt; t += 2) {
;             const bool last = (t == nt - 2);
;             const char* a1 = cA + (size_t)(t + 1) * kstep;
;             const char* a2 = last ? nA : cA + (size_t)(t + 2) * kstep; const char* b2 = last ? nB : cB + (size_t)(t + 2) * kstep;
;     ...
;             PG8_LDB(B0, 1, 0); PG8_LDB(B1, 1, 1); PG8_SCHED; PG8_LDA(At, 1, 0); PG8_STAGE(PG8_SA(0, 1), a2 + hstep, voffA);
;             PG8_WAIT_V(8); PG8_WAIT_L(0); PG8_BAR; PG8_MMA(0, 0, At, B0); PG8_MMA(0, 1, At, B1); PG8_BAR; PG8_SCHED;
;             PG8_LDA(At, 1, 1); PG8_STAGE(PG8_SB(1, 0), b3, voffB); PG8_STAGE(PG8_SB(1, 1), b3 + hstep, voffB); PG8_STAGE(PG8_SA(1, 0), a3, voffA);
;             PG8_WAIT_V(8); PG8_WAIT_L(0); PG8_BAR; PG8_MMA(1, 0, At, B0); PG8_MMA(1, 1, At, B1); PG8_BAR; PG8_SCHED;
	ds_read_b128 v[128:131], v196
	ds_read_b128 v[132:135], v197
	ds_read_b128 v[136:139], v198
	ds_read_b128 v[140:143], v199
	ds_read_b128 v[144:147], v200
	ds_read_b128 v[148:151], v201
	ds_read_b128 v[172:175], v202
	ds_read_b128 v[176:179], v203
	s_add_u32 s48, s48, 0x40000
	s_addc_u32 s49, s49, 0
	s_mov_b32 m0, s56
	v_lshl_add_u64 v[244:245], s[48:49], 0, v[152:153]
	ds_read_b128 v[180:183], v186 offset:32768
	ds_read_b128 v[208:211], v186 offset:33792
	ds_read_b128 v[212:215], v186 offset:34816
	ds_read_b128 v[216:219], v186 offset:35840
	ds_read_b128 v[220:223], v186 offset:36864
	ds_read_b128 v[224:227], v186 offset:37888
	ds_read_b128 v[228:231], v186 offset:38912
	ds_read_b128 v[232:235], v186 offset:39936
	global_load_lds_dwordx4 v[244:245], off
	v_lshl_add_u64 v[244:245], s[48:49], 0, v[156:157]
	s_mov_b32 m0, s57
	s_nop 0
	global_load_lds_dwordx4 v[244:245], off
	s_waitcnt vmcnt(8)
	s_waitcnt lgkmcnt(0)
	s_barrier
	s_waitcnt lgkmcnt(0)
	v_mfma_f32_16x16x32_bf16 v[124:127], v[128:131], v[180:183], v[124:127]
	v_mfma_f32_16x16x32_bf16 v[120:123], v[136:139], v[180:183], v[120:123]
	v_mfma_f32_16x16x32_bf16 v[108:111], v[128:131], v[212:215], v[108:111]
	v_mfma_f32_16x16x32_bf16 v[104:107], v[136:139], v[212:215], v[104:107]
	v_mfma_f32_16x16x32_bf16 v[92:95], v[128:131], v[220:223], v[92:95]
	v_mfma_f32_16x16x32_bf16 v[88:91], v[136:139], v[220:223], v[88:91]
	v_mfma_f32_16x16x32_bf16 v[76:79], v[128:131], v[228:231], v[76:79]
	v_mfma_f32_16x16x32_bf16 v[72:75], v[136:139], v[228:231], v[72:75]
	v_mfma_f32_16x16x32_bf16 v[124:127], v[132:135], v[208:211], v[124:127]
	v_mfma_f32_16x16x32_bf16 v[120:123], v[140:143], v[208:211], v[120:123]
	v_mfma_f32_16x16x32_bf16 v[108:111], v[132:135], v[216:219], v[108:111]
	v_mfma_f32_16x16x32_bf16 v[104:107], v[140:143], v[216:219], v[104:107]
	v_mfma_f32_16x16x32_bf16 v[92:95], v[132:135], v[224:227], v[92:95]
	v_mfma_f32_16x16x32_bf16 v[88:91], v[140:143], v[224:227], v[88:91]
	v_mfma_f32_16x16x32_bf16 v[76:79], v[132:135], v[232:235], v[76:79]
	v_mfma_f32_16x16x32_bf16 v[72:75], v[140:143], v[232:235], v[72:75]
	v_mfma_f32_16x16x32_bf16 v[116:119], v[144:147], v[180:183], v[116:119]
	v_mfma_f32_16x16x32_bf16 v[112:115], v[172:175], v[180:183], v[112:115]
	v_mfma_f32_16x16x32_bf16 v[100:103], v[144:147], v[212:215], v[100:103]
	v_mfma_f32_16x16x32_bf16 v[96:99], v[172:175], v[212:215], v[96:99]
	v_mfma_f32_16x16x32_bf16 v[84:87], v[144:147], v[220:223], v[84:87]
	v_mfma_f32_16x16x32_bf16 v[80:83], v[172:175], v[220:223], v[80:83]
	v_mfma_f32_16x16x32_bf16 v[68:71], v[144:147], v[228:231], v[68:71]
	v_mfma_f32_16x16x32_bf16 v[64:67], v[172:175], v[228:231], v[64:67]
	v_mfma_f32_16x16x32_bf16 v[116:119], v[148:151], v[208:211], v[116:119]
	v_mfma_f32_16x16x32_bf16 v[112:115], v[176:179], v[208:211], v[112:115]
	v_mfma_f32_16x16x32_bf16 v[100:103], v[148:151], v[216:219], v[100:103]
	v_mfma_f32_16x16x32_bf16 v[96:99], v[176:179], v[216:219], v[96:99]
	v_mfma_f32_16x16x32_bf16 v[84:87], v[148:151], v[224:227], v[84:87]
	v_mfma_f32_16x16x32_bf16 v[80:83], v[176:179], v[224:227], v[80:83]
	v_mfma_f32_16x16x32_bf16 v[68:71], v[148:151], v[232:235], v[68:71]
	v_mfma_f32_16x16x32_bf16 v[64:67], v[176:179], v[232:235], v[64:67]
	s_barrier
	s_mov_b32 m0, s59
	v_lshl_add_u64 v[236:237], v[236:237], 0, s[24:25]
	s_add_u32 s46, s46, 0x40080
	ds_read_b128 v[180:183], v186 offset:49152
	ds_read_b128 v[208:211], v186 offset:50176
	ds_read_b128 v[212:215], v186 offset:51200
	ds_read_b128 v[216:219], v186 offset:52224
	ds_read_b128 v[220:223], v186 offset:53248
	ds_read_b128 v[224:227], v186 offset:54272
	ds_read_b128 v[228:231], v186 offset:55296
	ds_read_b128 v[232:235], v186 offset:56320
	global_load_lds_dwordx4 v[236:237], off
	v_lshl_add_u64 v[236:237], v[238:239], 0, s[24:25]
	s_mov_b32 m0, s60
	s_addc_u32 s47, s47, 0
	global_load_lds_dwordx4 v[236:237], off
	v_lshl_add_u64 v[236:237], s[46:47], 0, v[154:155]
	s_mov_b32 m0, s63
	s_nop 0
	global_load_lds_dwordx4 v[236:237], off
	v_lshl_add_u64 v[236:237], s[46:47], 0, v[158:159]
	s_mov_b32 m0, s64
	s_nop 0
	global_load_lds_dwordx4 v[236:237], off
	v_lshl_add_u64 v[236:237], v[240:241], 0, s[24:25]
	s_mov_b32 m0, s61
	s_nop 0
	global_load_lds_dwordx4 v[236:237], off
	v_lshl_add_u64 v[236:237], v[242:243], 0, s[24:25]
	s_mov_b32 m0, s62
	s_nop 0
	global_load_lds_dwordx4 v[236:237], off
	s_waitcnt vmcnt(8)
	s_waitcnt lgkmcnt(0)
	s_barrier
	s_waitcnt lgkmcnt(0)
	v_mfma_f32_16x16x32_bf16 v[60:63], v[128:131], v[180:183], v[60:63]
	v_mfma_f32_16x16x32_bf16 v[56:59], v[136:139], v[180:183], v[56:59]
	v_mfma_f32_16x16x32_bf16 v[44:47], v[128:131], v[212:215], v[44:47]
	v_mfma_f32_16x16x32_bf16 v[40:43], v[136:139], v[212:215], v[40:43]
	v_mfma_f32_16x16x32_bf16 v[28:31], v[128:131], v[220:223], v[28:31]
	v_mfma_f32_16x16x32_bf16 v[24:27], v[136:139], v[220:223], v[24:27]
	v_mfma_f32_16x16x32_bf16 v[12:15], v[128:131], v[228:231], v[12:15]
	v_mfma_f32_16x16x32_bf16 v[8:11], v[136:139], v[228:231], v[8:11]
	v_mfma_f32_16x16x32_bf16 v[60:63], v[132:135], v[208:211], v[60:63]
	v_mfma_f32_16x16x32_bf16 v[56:59], v[140:143], v[208:211], v[56:59]
	v_mfma_f32_16x16x32_bf16 v[44:47], v[132:135], v[216:219], v[44:47]
	v_mfma_f32_16x16x32_bf16 v[40:43], v[140:143], v[216:219], v[40:43]
	v_mfma_f32_16x16x32_bf16 v[28:31], v[132:135], v[224:227], v[28:31]
	v_mfma_f32_16x16x32_bf16 v[24:27], v[140:143], v[224:227], v[24:27]
	v_mfma_f32_16x16x32_bf16 v[12:15], v[132:135], v[232:235], v[12:15]
	v_mfma_f32_16x16x32_bf16 v[8:11], v[140:143], v[232:235], v[8:11]
	v_mfma_f32_16x16x32_bf16 v[52:55], v[144:147], v[180:183], v[52:55]
	v_mfma_f32_16x16x32_bf16 v[48:51], v[172:175], v[180:183], v[48:51]
	v_mfma_f32_16x16x32_bf16 v[36:39], v[144:147], v[212:215], v[36:39]
	v_mfma_f32_16x16x32_bf16 v[32:35], v[172:175], v[212:215], v[32:35]
	v_mfma_f32_16x16x32_bf16 v[20:23], v[144:147], v[220:223], v[20:23]
	v_mfma_f32_16x16x32_bf16 v[16:19], v[172:175], v[220:223], v[16:19]
	v_mfma_f32_16x16x32_bf16 v[4:7], v[144:147], v[228:231], v[4:7]
	v_mfma_f32_16x16x32_bf16 v[0:3], v[172:175], v[228:231], v[0:3]
	v_mfma_f32_16x16x32_bf16 v[52:55], v[148:151], v[208:211], v[52:55]
	v_mfma_f32_16x16x32_bf16 v[48:51], v[176:179], v[208:211], v[48:51]
	v_mfma_f32_16x16x32_bf16 v[36:39], v[148:151], v[216:219], v[36:39]
	v_mfma_f32_16x16x32_bf16 v[32:35], v[176:179], v[216:219], v[32:35]
	v_mfma_f32_16x16x32_bf16 v[20:23], v[148:151], v[224:227], v[20:23]
	v_mfma_f32_16x16x32_bf16 v[16:19], v[176:179], v[224:227], v[16:19]
	v_mfma_f32_16x16x32_bf16 v[4:7], v[148:151], v[232:235], v[4:7]
	v_mfma_f32_16x16x32_bf16 v[0:3], v[176:179], v[232:235], v[0:3]
	s_add_i32 s74, s74, 2
	s_add_u32 s72, s72, 0x100
	s_addc_u32 s73, s73, 0
	s_add_u32 s44, s44, 0x100
	s_addc_u32 s45, s45, 0
	s_cmp_gt_u32 s74, 13
	s_barrier
	s_cbranch_scc0 .LBB0_760
	s_and_b64 vcc, exec, s[26:27]
	s_cbranch_vccz .LBB0_763
	s_barrier

; #define PG8_STAGE(bufoff, gbase, voff) do { _Pragma("unroll") for (int _i = 0; _i < 2; ++_i) \
;         __builtin_amdgcn_global_load_lds((const unsigned*)((const char*)(gbase) + (voff)[_i]), (PG8_LAS unsigned*)(lds + (bufoff) + ldsw + _i * 8192), 16, 0, 0); } while (0)
; #define PG8_LDA(dst, b, h) do { _Pragma("unroll") for (int m = 0; m < 4; ++m) _Pragma("unroll") for (int k = 0; k < 2; ++k) dst[m][k] = *(const PG8_LAS bf16x8*)(lds + PG8_SA(b, h) + aoff + m * 2048 + k * 1024); } while (0)
; #define PG8_LDB(dst, b, h) do { _Pragma("unroll") for (int n = 0; n < 2; ++n) _Pragma("unroll") for (int k = 0; k < 2; ++k) dst[n][k] = *(const PG8_LAS bf16x8*)(lds + PG8_SB(b, h) + boff + n * 2048 + k * 1024); } while (0)
; #define PG8_MMA(ai, bj, At, Bt) do { __builtin_amdgcn_s_setprio(1); _Pragma("unroll") for (int m = 0; m < 4; ++m) _Pragma("unroll") for (int n = 0; n < 2; ++n) _Pragma("unroll") for (int k = 0; k < 2; ++k) \
;         acc[ai][bj][m][n] = __builtin_amdgcn_mfma_f32_16x16x32_bf16(Bt[n][k], At[m][k], acc[ai][bj][m][n], 0, 0, 0); __builtin_amdgcn_s_setprio(0); } while (0)
; #define PG8_WAIT_V(n) asm volatile("s_waitcnt vmcnt(" #n ")" ::: "memory")
; #define PG8_WAIT_L(n) asm volatile("s_waitcnt lgkmcnt(" #n ")" ::: "memory")
; #define PG8_BAR __builtin_amdgcn_s_barrier()
; #define PG8_SCHED __builtin_amdgcn_sched_barrier(0)
; template <class Epi, class Sched, bool ALIGN_EPI = false, bool SP2 = false>
; __device__ __forceinline__ void gemm_phase(PG8_LAS unsigned char* lds, const Gemm g, const Sched& S, const Epi& E) {
;     ...
;             PG8_LDB(B0, 0, 0); PG8_LDB(B1, 0, 1); PG8_SCHED; PG8_LDA(At, 0, 0); PG8_STAGE(PG8_SA(1, 1), a1 + hstep, voffA);
;             PG8_WAIT_V(8); PG8_WAIT_L(0); PG8_BAR; PG8_MMA(0, 0, At, B0); PG8_MMA(0, 1, At, B1); PG8_BAR; PG8_SCHED;
;             PG8_LDA(At, 0, 1); PG8_STAGE(PG8_SB(0, 0), b2, voffB); PG8_STAGE(PG8_SB(0, 1), b2 + hstep, voffB); PG8_STAGE(PG8_SA(0, 0), a2, voffA);
;             PG8_WAIT_V(8); PG8_WAIT_L(0); PG8_BAR; PG8_MMA(1, 0, At, B0); PG8_MMA(1, 1, At, B1); PG8_BAR; PG8_SCHED;
.LBB0_1463:
	ds_read_b128 v[144:147], v151
	ds_read_b128 v[168:171], v152
	ds_read_b128 v[172:175], v153
	ds_read_b128 v[176:179], v154
	ds_read_b128 v[180:183], v155
	ds_read_b128 v[186:189], v156
	ds_read_b128 v[190:193], v157
	ds_read_b128 v[194:197], v158
	s_add_u32 s42, s36, 0xfffc0080
	s_addc_u32 s43, s37, -1
	s_cmp_eq_u32 s72, 12
	s_cselect_b32 s45, s27, s43
	s_cselect_b32 s44, s35, s42
	s_cselect_b32 s43, s25, s71
	s_cselect_b32 s42, s69, s70
	s_mov_b32 m0, s66
	v_lshl_add_u64 v[230:231], s[36:37], 0, v[138:139]
	ds_read_b128 v[198:201], v149
	ds_read_b128 v[202:205], v149 offset:1024
	ds_read_b128 v[206:209], v149 offset:2048
	ds_read_b128 v[210:213], v149 offset:3072
	ds_read_b128 v[214:217], v149 offset:4096
	ds_read_b128 v[218:221], v149 offset:5120
	ds_read_b128 v[222:225], v149 offset:6144
	ds_read_b128 v[226:229], v149 offset:7168
	global_load_lds_dwordx4 v[230:231], off
	v_lshl_add_u64 v[230:231], s[36:37], 0, v[136:137]
	s_mov_b32 m0, s67
	s_nop 0
	global_load_lds_dwordx4 v[230:231], off
	s_waitcnt vmcnt(8)
	s_waitcnt lgkmcnt(0)
	s_barrier
	s_waitcnt lgkmcnt(0)
	v_mfma_f32_16x16x32_bf16 v[124:127], v[144:147], v[198:201], v[124:127]
	v_mfma_f32_16x16x32_bf16 v[120:123], v[172:175], v[198:201], v[120:123]
	v_mfma_f32_16x16x32_bf16 v[108:111], v[144:147], v[206:209], v[108:111]
	v_mfma_f32_16x16x32_bf16 v[104:107], v[172:175], v[206:209], v[104:107]
	v_mfma_f32_16x16x32_bf16 v[92:95], v[144:147], v[214:217], v[92:95]
	v_mfma_f32_16x16x32_bf16 v[88:91], v[172:175], v[214:217], v[88:91]
	v_mfma_f32_16x16x32_bf16 v[76:79], v[144:147], v[222:225], v[76:79]
	v_mfma_f32_16x16x32_bf16 v[72:75], v[172:175], v[222:225], v[72:75]
	v_mfma_f32_16x16x32_bf16 v[124:127], v[168:171], v[202:205], v[124:127]
	v_mfma_f32_16x16x32_bf16 v[120:123], v[176:179], v[202:205], v[120:123]
	v_mfma_f32_16x16x32_bf16 v[108:111], v[168:171], v[210:213], v[108:111]
	v_mfma_f32_16x16x32_bf16 v[104:107], v[176:179], v[210:213], v[104:107]
	v_mfma_f32_16x16x32_bf16 v[92:95], v[168:171], v[218:221], v[92:95]
	v_mfma_f32_16x16x32_bf16 v[88:91], v[176:179], v[218:221], v[88:91]
	v_mfma_f32_16x16x32_bf16 v[76:79], v[168:171], v[226:229], v[76:79]
	v_mfma_f32_16x16x32_bf16 v[72:75], v[176:179], v[226:229], v[72:75]
	v_mfma_f32_16x16x32_bf16 v[116:119], v[180:183], v[198:201], v[116:119]
	v_mfma_f32_16x16x32_bf16 v[112:115], v[190:193], v[198:201], v[112:115]
	v_mfma_f32_16x16x32_bf16 v[100:103], v[180:183], v[206:209], v[100:103]
	v_mfma_f32_16x16x32_bf16 v[96:99], v[190:193], v[206:209], v[96:99]
	v_mfma_f32_16x16x32_bf16 v[84:87], v[180:183], v[214:217], v[84:87]
	v_mfma_f32_16x16x32_bf16 v[80:83], v[190:193], v[214:217], v[80:83]
	v_mfma_f32_16x16x32_bf16 v[68:71], v[180:183], v[222:225], v[68:71]
	v_mfma_f32_16x16x32_bf16 v[64:67], v[190:193], v[222:225], v[64:67]
	v_mfma_f32_16x16x32_bf16 v[116:119], v[186:189], v[202:205], v[116:119]
	v_mfma_f32_16x16x32_bf16 v[112:115], v[194:197], v[202:205], v[112:115]
	v_mfma_f32_16x16x32_bf16 v[100:103], v[186:189], v[210:213], v[100:103]
	v_mfma_f32_16x16x32_bf16 v[96:99], v[194:197], v[210:213], v[96:99]
	v_mfma_f32_16x16x32_bf16 v[84:87], v[186:189], v[218:221], v[84:87]
	v_mfma_f32_16x16x32_bf16 v[80:83], v[194:197], v[218:221], v[80:83]
	v_mfma_f32_16x16x32_bf16 v[68:71], v[186:189], v[226:229], v[68:71]
	v_mfma_f32_16x16x32_bf16 v[64:67], v[194:197], v[226:229], v[64:67]
	s_barrier
	s_mov_b32 m0, s50
	v_lshl_add_u64 v[230:231], s[42:43], 0, v[130:131]
	s_add_u32 s74, s42, 0x40000
	ds_read_b128 v[198:201], v149 offset:16384
	ds_read_b128 v[202:205], v149 offset:17408
	ds_read_b128 v[206:209], v149 offset:18432
	ds_read_b128 v[210:213], v149 offset:19456
	ds_read_b128 v[214:217], v149 offset:20480
	ds_read_b128 v[218:221], v149 offset:21504
	ds_read_b128 v[222:225], v149 offset:22528
	ds_read_b128 v[226:229], v149 offset:23552
	global_load_lds_dwordx4 v[230:231], off
	v_lshl_add_u64 v[232:233], s[42:43], 0, v[134:135]
	s_mov_b32 m0, s51
	s_addc_u32 s75, s43, 0
	global_load_lds_dwordx4 v[232:233], off
	v_lshl_add_u64 v[234:235], s[74:75], 0, v[130:131]
	s_mov_b32 m0, s52
	v_lshl_add_u64 v[236:237], s[44:45], 0, v[132:133]
	global_load_lds_dwordx4 v[234:235], off
	v_lshl_add_u64 v[234:235], s[74:75], 0, v[134:135]
	s_mov_b32 m0, s53
	s_nop 0
	global_load_lds_dwordx4 v[234:235], off
	v_lshl_add_u64 v[234:235], s[44:45], 0, v[128:129]
	s_mov_b32 m0, s49
	s_nop 0
	global_load_lds_dwordx4 v[234:235], off
	s_mov_b32 m0, s54
	s_nop 0
	global_load_lds_dwordx4 v[236:237], off
	s_waitcnt vmcnt(8)
	s_waitcnt lgkmcnt(0)
	s_barrier
	s_waitcnt lgkmcnt(0)
	v_mfma_f32_16x16x32_bf16 v[60:63], v[144:147], v[198:201], v[60:63]
	v_mfma_f32_16x16x32_bf16 v[56:59], v[172:175], v[198:201], v[56:59]
	v_mfma_f32_16x16x32_bf16 v[44:47], v[144:147], v[206:209], v[44:47]
	v_mfma_f32_16x16x32_bf16 v[40:43], v[172:175], v[206:209], v[40:43]
	v_mfma_f32_16x16x32_bf16 v[28:31], v[144:147], v[214:217], v[28:31]
	v_mfma_f32_16x16x32_bf16 v[24:27], v[172:175], v[214:217], v[24:27]
	v_mfma_f32_16x16x32_bf16 v[12:15], v[144:147], v[222:225], v[12:15]
	v_mfma_f32_16x16x32_bf16 v[8:11], v[172:175], v[222:225], v[8:11]
	v_mfma_f32_16x16x32_bf16 v[60:63], v[168:171], v[202:205], v[60:63]
	v_mfma_f32_16x16x32_bf16 v[56:59], v[176:179], v[202:205], v[56:59]
	v_mfma_f32_16x16x32_bf16 v[44:47], v[168:171], v[210:213], v[44:47]
	v_mfma_f32_16x16x32_bf16 v[40:43], v[176:179], v[210:213], v[40:43]
	v_mfma_f32_16x16x32_bf16 v[28:31], v[168:171], v[218:221], v[28:31]
	v_mfma_f32_16x16x32_bf16 v[24:27], v[176:179], v[218:221], v[24:27]
	v_mfma_f32_16x16x32_bf16 v[12:15], v[168:171], v[226:229], v[12:15]
	v_mfma_f32_16x16x32_bf16 v[8:11], v[176:179], v[226:229], v[8:11]
	v_mfma_f32_16x16x32_bf16 v[52:55], v[180:183], v[198:201], v[52:55]
	v_mfma_f32_16x16x32_bf16 v[48:51], v[190:193], v[198:201], v[48:51]
	v_mfma_f32_16x16x32_bf16 v[36:39], v[180:183], v[206:209], v[36:39]
	v_mfma_f32_16x16x32_bf16 v[32:35], v[190:193], v[206:209], v[32:35]
	v_mfma_f32_16x16x32_bf16 v[20:23], v[180:183], v[214:217], v[20:23]
	v_mfma_f32_16x16x32_bf16 v[16:19], v[190:193], v[214:217], v[16:19]
	v_mfma_f32_16x16x32_bf16 v[4:7], v[180:183], v[222:225], v[4:7]
	v_mfma_f32_16x16x32_bf16 v[0:3], v[190:193], v[222:225], v[0:3]
	v_mfma_f32_16x16x32_bf16 v[52:55], v[186:189], v[202:205], v[52:55]
	v_mfma_f32_16x16x32_bf16 v[48:51], v[194:197], v[202:205], v[48:51]
	v_mfma_f32_16x16x32_bf16 v[36:39], v[186:189], v[210:213], v[36:39]
	v_mfma_f32_16x16x32_bf16 v[32:35], v[194:197], v[210:213], v[32:35]
	v_mfma_f32_16x16x32_bf16 v[20:23], v[186:189], v[218:221], v[20:23]
	v_mfma_f32_16x16x32_bf16 v[16:19], v[194:197], v[218:221], v[16:19]
	v_mfma_f32_16x16x32_bf16 v[4:7], v[186:189], v[226:229], v[4:7]
	v_mfma_f32_16x16x32_bf16 v[0:3], v[194:197], v[226:229], v[0:3]
	s_barrier
; #define PG8_STAGE(bufoff, gbase, voff) do { _Pragma("unroll") for (int _i = 0; _i < 2; ++_i) \
;         __builtin_amdgcn_global_load_lds((const unsigned*)((const char*)(gbase) + (voff)[_i]), (PG8_LAS unsigned*)(lds + (bufoff) + ldsw + _i * 8192), 16, 0, 0); } while (0)
; #define PG8_LDA(dst, b, h) do { _Pragma("unroll") for (int m = 0; m < 4; ++m) _Pragma("unroll") for (int k = 0; k < 2; ++k) dst[m][k] = *(const PG8_LAS bf16x8*)(lds + PG8_SA(b, h) + aoff + m * 2048 + k * 1024); } while (0)
; #define PG8_LDB(dst, b, h) do { _Pragma("unroll") for (int n = 0; n < 2; ++n) _Pragma("unroll") for (int k = 0; k < 2; ++k) dst[n][k] = *(const PG8_LAS bf16x8*)(lds + PG8_SB(b, h) + boff + n * 2048 + k * 1024); } while (0)
; #define PG8_MMA(ai, bj, At, Bt) do { __builtin_amdgcn_s_setprio(1); _Pragma("unroll") for (int m = 0; m < 4; ++m) _Pragma("unroll") for (int n = 0; n < 2; ++n) _Pragma("unroll") for (int k = 0; k < 2; ++k) \
;         acc[ai][bj][m][n] = __builtin_amdgcn_mfma_f32_16x16x32_bf16(Bt[n][k], At[m][k], acc[ai][bj][m][n], 0, 0, 0); __builtin_amdgcn_s_setprio(0); } while (0)
; #define PG8_WAIT_V(n) asm volatile("s_waitcnt vmcnt(" #n ")" ::: "memory")
; #define PG8_WAIT_L(n) asm volatile("s_waitcnt lgkmcnt(" #n ")" ::: "memory")
; #define PG8_BAR __builtin_amdgcn_s_barrier()
; #define PG8_SCHED __builtin_amdgcn_sched_barrier(0)
; template <class Epi, class Sched, bool ALIGN_EPI = false, bool SP2 = false>
; __device__ __forceinline__ void gemm_phase(PG8_LAS unsigned char* lds, const Gemm g, const Sched& S, const Epi& E) {
;     ...
;         for (int t = 0; t < nt; t += 2) {
;             const bool last = (t == nt - 2);
;             const char* a1 = cA + (size_t)(t + 1) * kstep;
;             const char* a2 = last ? nA : cA + (size_t)(t + 2) * kstep; const char* b2 = last ? nB : cB + (size_t)(t + 2) * kstep;
;     ...
;             PG8_LDB(B0, 1, 0); PG8_LDB(B1, 1, 1); PG8_SCHED; PG8_LDA(At, 1, 0); PG8_STAGE(PG8_SA(0, 1), a2 + hstep, voffA);
;             PG8_WAIT_V(8); PG8_WAIT_L(0); PG8_BAR; PG8_MMA(0, 0, At, B0); PG8_MMA(0, 1, At, B1); PG8_BAR; PG8_SCHED;
;             PG8_LDA(At, 1, 1); PG8_STAGE(PG8_SB(1, 0), b3, voffB); PG8_STAGE(PG8_SB(1, 1), b3 + hstep, voffB); PG8_STAGE(PG8_SA(1, 0), a3, voffA);
;             PG8_WAIT_V(8); PG8_WAIT_L(0); PG8_BAR; PG8_MMA(1, 0, At, B0); PG8_MMA(1, 1, At, B1); PG8_BAR; PG8_SCHED;
	ds_read_b128 v[144:147], v159
	ds_read_b128 v[168:171], v160
	ds_read_b128 v[172:175], v161
	ds_read_b128 v[176:179], v162
	ds_read_b128 v[180:183], v163
	ds_read_b128 v[186:189], v164
	ds_read_b128 v[190:193], v165
	ds_read_b128 v[194:197], v166
	s_add_u32 s44, s44, 0x40000
	s_addc_u32 s45, s45, 0
	s_mov_b32 m0, s55
	v_lshl_add_u64 v[238:239], s[44:45], 0, v[128:129]
	ds_read_b128 v[198:201], v149 offset:32768
	ds_read_b128 v[202:205], v149 offset:33792
	ds_read_b128 v[206:209], v149 offset:34816
	ds_read_b128 v[210:213], v149 offset:35840
	ds_read_b128 v[214:217], v149 offset:36864
	ds_read_b128 v[218:221], v149 offset:37888
	ds_read_b128 v[222:225], v149 offset:38912
	ds_read_b128 v[226:229], v149 offset:39936
	global_load_lds_dwordx4 v[238:239], off
	v_lshl_add_u64 v[238:239], s[44:45], 0, v[132:133]
	s_mov_b32 m0, s56
	s_nop 0
	global_load_lds_dwordx4 v[238:239], off
	s_waitcnt vmcnt(8)
	s_waitcnt lgkmcnt(0)
	s_barrier
	s_waitcnt lgkmcnt(0)
	v_mfma_f32_16x16x32_bf16 v[124:127], v[144:147], v[198:201], v[124:127]
	v_mfma_f32_16x16x32_bf16 v[120:123], v[172:175], v[198:201], v[120:123]
	v_mfma_f32_16x16x32_bf16 v[108:111], v[144:147], v[206:209], v[108:111]
	v_mfma_f32_16x16x32_bf16 v[104:107], v[172:175], v[206:209], v[104:107]
	v_mfma_f32_16x16x32_bf16 v[92:95], v[144:147], v[214:217], v[92:95]
	v_mfma_f32_16x16x32_bf16 v[88:91], v[172:175], v[214:217], v[88:91]
	v_mfma_f32_16x16x32_bf16 v[76:79], v[144:147], v[222:225], v[76:79]
	v_mfma_f32_16x16x32_bf16 v[72:75], v[172:175], v[222:225], v[72:75]
	v_mfma_f32_16x16x32_bf16 v[124:127], v[168:171], v[202:205], v[124:127]
	v_mfma_f32_16x16x32_bf16 v[120:123], v[176:179], v[202:205], v[120:123]
	v_mfma_f32_16x16x32_bf16 v[108:111], v[168:171], v[210:213], v[108:111]
	v_mfma_f32_16x16x32_bf16 v[104:107], v[176:179], v[210:213], v[104:107]
	v_mfma_f32_16x16x32_bf16 v[92:95], v[168:171], v[218:221], v[92:95]
	v_mfma_f32_16x16x32_bf16 v[88:91], v[176:179], v[218:221], v[88:91]
	v_mfma_f32_16x16x32_bf16 v[76:79], v[168:171], v[226:229], v[76:79]
	v_mfma_f32_16x16x32_bf16 v[72:75], v[176:179], v[226:229], v[72:75]
	v_mfma_f32_16x16x32_bf16 v[116:119], v[180:183], v[198:201], v[116:119]
	v_mfma_f32_16x16x32_bf16 v[112:115], v[190:193], v[198:201], v[112:115]
	v_mfma_f32_16x16x32_bf16 v[100:103], v[180:183], v[206:209], v[100:103]
	v_mfma_f32_16x16x32_bf16 v[96:99], v[190:193], v[206:209], v[96:99]
	v_mfma_f32_16x16x32_bf16 v[84:87], v[180:183], v[214:217], v[84:87]
	v_mfma_f32_16x16x32_bf16 v[80:83], v[190:193], v[214:217], v[80:83]
	v_mfma_f32_16x16x32_bf16 v[68:71], v[180:183], v[222:225], v[68:71]
	v_mfma_f32_16x16x32_bf16 v[64:67], v[190:193], v[222:225], v[64:67]
	v_mfma_f32_16x16x32_bf16 v[116:119], v[186:189], v[202:205], v[116:119]
	v_mfma_f32_16x16x32_bf16 v[112:115], v[194:197], v[202:205], v[112:115]
	v_mfma_f32_16x16x32_bf16 v[100:103], v[186:189], v[210:213], v[100:103]
	v_mfma_f32_16x16x32_bf16 v[96:99], v[194:197], v[210:213], v[96:99]
	v_mfma_f32_16x16x32_bf16 v[84:87], v[186:189], v[218:221], v[84:87]
	v_mfma_f32_16x16x32_bf16 v[80:83], v[194:197], v[218:221], v[80:83]
	v_mfma_f32_16x16x32_bf16 v[68:71], v[186:189], v[226:229], v[68:71]
	v_mfma_f32_16x16x32_bf16 v[64:67], v[194:197], v[226:229], v[64:67]
	s_barrier
	s_mov_b32 m0, s58
	v_lshl_add_u64 v[230:231], v[230:231], 0, s[18:19]
	s_add_u32 s42, s42, 0x40080
	ds_read_b128 v[198:201], v149 offset:49152
	ds_read_b128 v[202:205], v149 offset:50176
	ds_read_b128 v[206:209], v149 offset:51200
	ds_read_b128 v[210:213], v149 offset:52224
	ds_read_b128 v[214:217], v149 offset:53248
	ds_read_b128 v[218:221], v149 offset:54272
	ds_read_b128 v[222:225], v149 offset:55296
	ds_read_b128 v[226:229], v149 offset:56320
	global_load_lds_dwordx4 v[230:231], off
	v_lshl_add_u64 v[230:231], v[232:233], 0, s[18:19]
	s_mov_b32 m0, s59
	s_addc_u32 s43, s43, 0
	global_load_lds_dwordx4 v[230:231], off
	v_lshl_add_u64 v[230:231], s[42:43], 0, v[130:131]
	s_mov_b32 m0, s62
	s_nop 0
	global_load_lds_dwordx4 v[230:231], off
	v_lshl_add_u64 v[230:231], s[42:43], 0, v[134:135]
	s_mov_b32 m0, s63
	s_nop 0
	global_load_lds_dwordx4 v[230:231], off
	v_lshl_add_u64 v[230:231], v[234:235], 0, s[18:19]
	s_mov_b32 m0, s60
	s_nop 0
	global_load_lds_dwordx4 v[230:231], off
	v_lshl_add_u64 v[230:231], v[236:237], 0, s[18:19]
	s_mov_b32 m0, s61
	s_nop 0
	global_load_lds_dwordx4 v[230:231], off
	s_waitcnt vmcnt(8)
	s_waitcnt lgkmcnt(0)
	s_barrier
	s_waitcnt lgkmcnt(0)
	v_mfma_f32_16x16x32_bf16 v[60:63], v[144:147], v[198:201], v[60:63]
	v_mfma_f32_16x16x32_bf16 v[56:59], v[172:175], v[198:201], v[56:59]
	v_mfma_f32_16x16x32_bf16 v[44:47], v[144:147], v[206:209], v[44:47]
	v_mfma_f32_16x16x32_bf16 v[40:43], v[172:175], v[206:209], v[40:43]
	v_mfma_f32_16x16x32_bf16 v[28:31], v[144:147], v[214:217], v[28:31]
	v_mfma_f32_16x16x32_bf16 v[24:27], v[172:175], v[214:217], v[24:27]
	v_mfma_f32_16x16x32_bf16 v[12:15], v[144:147], v[222:225], v[12:15]
	v_mfma_f32_16x16x32_bf16 v[8:11], v[172:175], v[222:225], v[8:11]
	v_mfma_f32_16x16x32_bf16 v[60:63], v[168:171], v[202:205], v[60:63]
	v_mfma_f32_16x16x32_bf16 v[56:59], v[176:179], v[202:205], v[56:59]
	v_mfma_f32_16x16x32_bf16 v[44:47], v[168:171], v[210:213], v[44:47]
	v_mfma_f32_16x16x32_bf16 v[40:43], v[176:179], v[210:213], v[40:43]
	v_mfma_f32_16x16x32_bf16 v[28:31], v[168:171], v[218:221], v[28:31]
	v_mfma_f32_16x16x32_bf16 v[24:27], v[176:179], v[218:221], v[24:27]
	v_mfma_f32_16x16x32_bf16 v[12:15], v[168:171], v[226:229], v[12:15]
	v_mfma_f32_16x16x32_bf16 v[8:11], v[176:179], v[226:229], v[8:11]
	v_mfma_f32_16x16x32_bf16 v[52:55], v[180:183], v[198:201], v[52:55]
	v_mfma_f32_16x16x32_bf16 v[48:51], v[190:193], v[198:201], v[48:51]
	v_mfma_f32_16x16x32_bf16 v[36:39], v[180:183], v[206:209], v[36:39]
	v_mfma_f32_16x16x32_bf16 v[32:35], v[190:193], v[206:209], v[32:35]
	v_mfma_f32_16x16x32_bf16 v[20:23], v[180:183], v[214:217], v[20:23]
	v_mfma_f32_16x16x32_bf16 v[16:19], v[190:193], v[214:217], v[16:19]
	v_mfma_f32_16x16x32_bf16 v[4:7], v[180:183], v[222:225], v[4:7]
	v_mfma_f32_16x16x32_bf16 v[0:3], v[190:193], v[222:225], v[0:3]
	v_mfma_f32_16x16x32_bf16 v[52:55], v[186:189], v[202:205], v[52:55]
	v_mfma_f32_16x16x32_bf16 v[48:51], v[194:197], v[202:205], v[48:51]
	v_mfma_f32_16x16x32_bf16 v[36:39], v[186:189], v[210:213], v[36:39]
	v_mfma_f32_16x16x32_bf16 v[32:35], v[194:197], v[210:213], v[32:35]
	v_mfma_f32_16x16x32_bf16 v[20:23], v[186:189], v[218:221], v[20:23]
	v_mfma_f32_16x16x32_bf16 v[16:19], v[194:197], v[218:221], v[16:19]
	v_mfma_f32_16x16x32_bf16 v[4:7], v[186:189], v[226:229], v[4:7]
	v_mfma_f32_16x16x32_bf16 v[0:3], v[194:197], v[226:229], v[0:3]
	s_add_i32 s72, s72, 2
	s_add_u32 s70, s70, 0x100
	s_addc_u32 s71, s71, 0
	s_add_u32 s36, s36, 0x100
	s_addc_u32 s37, s37, 0
	s_cmp_gt_u32 s72, 13
	s_barrier
	s_cbranch_scc0 .LBB0_1463
	s_and_b64 vcc, exec, s[20:21]
	s_cbranch_vccz .LBB0_1466
	s_barrier

; #define PG8_STAGE(bufoff, gbase, voff) do { _Pragma("unroll") for (int _i = 0; _i < 2; ++_i) \
;         __builtin_amdgcn_global_load_lds((const unsigned*)((const char*)(gbase) + (voff)[_i]), (PG8_LAS unsigned*)(lds + (bufoff) + ldsw + _i * 8192), 16, 0, 0); } while (0)
; #define PG8_LDA(dst, b, h) do { _Pragma("unroll") for (int m = 0; m < 4; ++m) _Pragma("unroll") for (int k = 0; k < 2; ++k) dst[m][k] = *(const PG8_LAS bf16x8*)(lds + PG8_SA(b, h) + aoff + m * 2048 + k * 1024); } while (0)
; #define PG8_LDB(dst, b, h) do { _Pragma("unroll") for (int n = 0; n < 2; ++n) _Pragma("unroll") for (int k = 0; k < 2; ++k) dst[n][k] = *(const PG8_LAS bf16x8*)(lds + PG8_SB(b, h) + boff + n * 2048 + k * 1024); } while (0)
; #define PG8_MMA(ai, bj, At, Bt) do { __builtin_amdgcn_s_setprio(1); _Pragma("unroll") for (int m = 0; m < 4; ++m) _Pragma("unroll") for (int n = 0; n < 2; ++n) _Pragma("unroll") for (int k = 0; k < 2; ++k) \
;         acc[ai][bj][m][n] = __builtin_amdgcn_mfma_f32_16x16x32_bf16(Bt[n][k], At[m][k], acc[ai][bj][m][n], 0, 0, 0); __builtin_amdgcn_s_setprio(0); } while (0)
; #define PG8_WAIT_V(n) asm volatile("s_waitcnt vmcnt(" #n ")" ::: "memory")
; #define PG8_WAIT_L(n) asm volatile("s_waitcnt lgkmcnt(" #n ")" ::: "memory")
; #define PG8_BAR __builtin_amdgcn_s_barrier()
; #define PG8_SCHED __builtin_amdgcn_sched_barrier(0)
; template <class Epi, class Sched, bool ALIGN_EPI = false, bool SP2 = false>
; __device__ __forceinline__ void gemm_phase(PG8_LAS unsigned char* lds, const Gemm g, const Sched& S, const Epi& E) {
;     ...
;             PG8_LDB(B0, 0, 0); PG8_LDB(B1, 0, 1); PG8_SCHED; PG8_LDA(At, 0, 0); PG8_STAGE(PG8_SA(1, 1), a1 + hstep, voffA);
;             PG8_WAIT_V(8); PG8_WAIT_L(0); PG8_BAR; PG8_MMA(0, 0, At, B0); PG8_MMA(0, 1, At, B1); PG8_BAR; PG8_SCHED;
;             PG8_LDA(At, 0, 1); PG8_STAGE(PG8_SB(0, 0), b2, voffB); PG8_STAGE(PG8_SB(0, 1), b2 + hstep, voffB); PG8_STAGE(PG8_SA(0, 0), a2, voffA);
;             PG8_WAIT_V(8); PG8_WAIT_L(0); PG8_BAR; PG8_MMA(1, 0, At, B0); PG8_MMA(1, 1, At, B1); PG8_BAR; PG8_SCHED;
.LBB0_1744:
	ds_read_b128 v[128:131], v161
	ds_read_b128 v[132:135], v162
	ds_read_b128 v[152:155], v163
	ds_read_b128 v[180:183], v164
	ds_read_b128 v[186:189], v165
	ds_read_b128 v[190:193], v166
	ds_read_b128 v[194:197], v167
	ds_read_b128 v[198:201], v168
	s_add_u32 s48, s12, 0xfffc0080
	s_addc_u32 s49, s13, -1
	s_cmp_eq_u32 s75, 12
	s_cselect_b32 s51, s9, s49
	s_cselect_b32 s50, s11, s48
	s_cselect_b32 s49, s34, s74
	s_cselect_b32 s48, s37, s43
	s_mov_b32 m0, s70
	v_lshl_add_u64 v[156:157], s[12:13], 0, v[146:147]
	ds_read_b128 v[202:205], v159
	ds_read_b128 v[206:209], v159 offset:1024
	ds_read_b128 v[210:213], v159 offset:2048
	ds_read_b128 v[214:217], v159 offset:3072
	ds_read_b128 v[218:221], v159 offset:4096
	ds_read_b128 v[222:225], v159 offset:5120
	ds_read_b128 v[226:229], v159 offset:6144
	ds_read_b128 v[230:233], v159 offset:7168
	global_load_lds_dwordx4 v[156:157], off
	v_lshl_add_u64 v[156:157], s[12:13], 0, v[144:145]
	s_mov_b32 m0, s71
	s_nop 0
	global_load_lds_dwordx4 v[156:157], off
	s_waitcnt vmcnt(8)
	s_waitcnt lgkmcnt(0)
	s_barrier
	s_waitcnt lgkmcnt(0)
	v_mfma_f32_16x16x32_bf16 v[124:127], v[128:131], v[202:205], v[124:127]
	v_mfma_f32_16x16x32_bf16 v[120:123], v[152:155], v[202:205], v[120:123]
	v_mfma_f32_16x16x32_bf16 v[108:111], v[128:131], v[210:213], v[108:111]
	v_mfma_f32_16x16x32_bf16 v[104:107], v[152:155], v[210:213], v[104:107]
	v_mfma_f32_16x16x32_bf16 v[92:95], v[128:131], v[218:221], v[92:95]
	v_mfma_f32_16x16x32_bf16 v[88:91], v[152:155], v[218:221], v[88:91]
	v_mfma_f32_16x16x32_bf16 v[76:79], v[128:131], v[226:229], v[76:79]
	v_mfma_f32_16x16x32_bf16 v[72:75], v[152:155], v[226:229], v[72:75]
	v_mfma_f32_16x16x32_bf16 v[124:127], v[132:135], v[206:209], v[124:127]
	v_mfma_f32_16x16x32_bf16 v[120:123], v[180:183], v[206:209], v[120:123]
	v_mfma_f32_16x16x32_bf16 v[108:111], v[132:135], v[214:217], v[108:111]
	v_mfma_f32_16x16x32_bf16 v[104:107], v[180:183], v[214:217], v[104:107]
	v_mfma_f32_16x16x32_bf16 v[92:95], v[132:135], v[222:225], v[92:95]
	v_mfma_f32_16x16x32_bf16 v[88:91], v[180:183], v[222:225], v[88:91]
	v_mfma_f32_16x16x32_bf16 v[76:79], v[132:135], v[230:233], v[76:79]
	v_mfma_f32_16x16x32_bf16 v[72:75], v[180:183], v[230:233], v[72:75]
	v_mfma_f32_16x16x32_bf16 v[116:119], v[186:189], v[202:205], v[116:119]
	v_mfma_f32_16x16x32_bf16 v[112:115], v[194:197], v[202:205], v[112:115]
	v_mfma_f32_16x16x32_bf16 v[100:103], v[186:189], v[210:213], v[100:103]
	v_mfma_f32_16x16x32_bf16 v[96:99], v[194:197], v[210:213], v[96:99]
	v_mfma_f32_16x16x32_bf16 v[84:87], v[186:189], v[218:221], v[84:87]
	v_mfma_f32_16x16x32_bf16 v[80:83], v[194:197], v[218:221], v[80:83]
	v_mfma_f32_16x16x32_bf16 v[68:71], v[186:189], v[226:229], v[68:71]
	v_mfma_f32_16x16x32_bf16 v[64:67], v[194:197], v[226:229], v[64:67]
	v_mfma_f32_16x16x32_bf16 v[116:119], v[190:193], v[206:209], v[116:119]
	v_mfma_f32_16x16x32_bf16 v[112:115], v[198:201], v[206:209], v[112:115]
	v_mfma_f32_16x16x32_bf16 v[100:103], v[190:193], v[214:217], v[100:103]
	v_mfma_f32_16x16x32_bf16 v[96:99], v[198:201], v[214:217], v[96:99]
	v_mfma_f32_16x16x32_bf16 v[84:87], v[190:193], v[222:225], v[84:87]
	v_mfma_f32_16x16x32_bf16 v[80:83], v[198:201], v[222:225], v[80:83]
	v_mfma_f32_16x16x32_bf16 v[68:71], v[190:193], v[230:233], v[68:71]
	v_mfma_f32_16x16x32_bf16 v[64:67], v[198:201], v[230:233], v[64:67]
	s_barrier
	s_mov_b32 m0, s54
	v_lshl_add_u64 v[156:157], s[48:49], 0, v[138:139]
	s_add_u32 s76, s48, 0x40000
	ds_read_b128 v[202:205], v159 offset:16384
	ds_read_b128 v[206:209], v159 offset:17408
	ds_read_b128 v[210:213], v159 offset:18432
	ds_read_b128 v[214:217], v159 offset:19456
	ds_read_b128 v[218:221], v159 offset:20480
	ds_read_b128 v[222:225], v159 offset:21504
	ds_read_b128 v[226:229], v159 offset:22528
	ds_read_b128 v[230:233], v159 offset:23552
	global_load_lds_dwordx4 v[156:157], off
	v_lshl_add_u64 v[234:235], s[48:49], 0, v[142:143]
	s_mov_b32 m0, s55
	s_addc_u32 s77, s49, 0
	global_load_lds_dwordx4 v[234:235], off
	v_lshl_add_u64 v[236:237], s[76:77], 0, v[138:139]
	s_mov_b32 m0, s56
	v_lshl_add_u64 v[238:239], s[50:51], 0, v[140:141]
	global_load_lds_dwordx4 v[236:237], off
	v_lshl_add_u64 v[236:237], s[76:77], 0, v[142:143]
	s_mov_b32 m0, s57
	s_nop 0
	global_load_lds_dwordx4 v[236:237], off
	v_lshl_add_u64 v[236:237], s[50:51], 0, v[136:137]
	s_mov_b32 m0, s53
	s_nop 0
	global_load_lds_dwordx4 v[236:237], off
	s_mov_b32 m0, s58
	s_nop 0
	global_load_lds_dwordx4 v[238:239], off
	s_waitcnt vmcnt(8)
	s_waitcnt lgkmcnt(0)
	s_barrier
	s_waitcnt lgkmcnt(0)
	v_mfma_f32_16x16x32_bf16 v[60:63], v[128:131], v[202:205], v[60:63]
	v_mfma_f32_16x16x32_bf16 v[56:59], v[152:155], v[202:205], v[56:59]
	v_mfma_f32_16x16x32_bf16 v[44:47], v[128:131], v[210:213], v[44:47]
	v_mfma_f32_16x16x32_bf16 v[40:43], v[152:155], v[210:213], v[40:43]
	v_mfma_f32_16x16x32_bf16 v[28:31], v[128:131], v[218:221], v[28:31]
	v_mfma_f32_16x16x32_bf16 v[24:27], v[152:155], v[218:221], v[24:27]
	v_mfma_f32_16x16x32_bf16 v[12:15], v[128:131], v[226:229], v[12:15]
	v_mfma_f32_16x16x32_bf16 v[8:11], v[152:155], v[226:229], v[8:11]
	v_mfma_f32_16x16x32_bf16 v[60:63], v[132:135], v[206:209], v[60:63]
	v_mfma_f32_16x16x32_bf16 v[56:59], v[180:183], v[206:209], v[56:59]
	v_mfma_f32_16x16x32_bf16 v[44:47], v[132:135], v[214:217], v[44:47]
	v_mfma_f32_16x16x32_bf16 v[40:43], v[180:183], v[214:217], v[40:43]
	v_mfma_f32_16x16x32_bf16 v[28:31], v[132:135], v[222:225], v[28:31]
	v_mfma_f32_16x16x32_bf16 v[24:27], v[180:183], v[222:225], v[24:27]
	v_mfma_f32_16x16x32_bf16 v[12:15], v[132:135], v[230:233], v[12:15]
	v_mfma_f32_16x16x32_bf16 v[8:11], v[180:183], v[230:233], v[8:11]
	v_mfma_f32_16x16x32_bf16 v[52:55], v[186:189], v[202:205], v[52:55]
	v_mfma_f32_16x16x32_bf16 v[48:51], v[194:197], v[202:205], v[48:51]
	v_mfma_f32_16x16x32_bf16 v[36:39], v[186:189], v[210:213], v[36:39]
	v_mfma_f32_16x16x32_bf16 v[32:35], v[194:197], v[210:213], v[32:35]
	v_mfma_f32_16x16x32_bf16 v[20:23], v[186:189], v[218:221], v[20:23]
	v_mfma_f32_16x16x32_bf16 v[16:19], v[194:197], v[218:221], v[16:19]
	v_mfma_f32_16x16x32_bf16 v[4:7], v[186:189], v[226:229], v[4:7]
	v_mfma_f32_16x16x32_bf16 v[0:3], v[194:197], v[226:229], v[0:3]
	v_mfma_f32_16x16x32_bf16 v[52:55], v[190:193], v[206:209], v[52:55]
	v_mfma_f32_16x16x32_bf16 v[48:51], v[198:201], v[206:209], v[48:51]
	v_mfma_f32_16x16x32_bf16 v[36:39], v[190:193], v[214:217], v[36:39]
	v_mfma_f32_16x16x32_bf16 v[32:35], v[198:201], v[214:217], v[32:35]
	v_mfma_f32_16x16x32_bf16 v[20:23], v[190:193], v[222:225], v[20:23]
	v_mfma_f32_16x16x32_bf16 v[16:19], v[198:201], v[222:225], v[16:19]
	v_mfma_f32_16x16x32_bf16 v[4:7], v[190:193], v[230:233], v[4:7]
	v_mfma_f32_16x16x32_bf16 v[0:3], v[198:201], v[230:233], v[0:3]
	s_barrier
; #define PG8_STAGE(bufoff, gbase, voff) do { _Pragma("unroll") for (int _i = 0; _i < 2; ++_i) \
;         __builtin_amdgcn_global_load_lds((const unsigned*)((const char*)(gbase) + (voff)[_i]), (PG8_LAS unsigned*)(lds + (bufoff) + ldsw + _i * 8192), 16, 0, 0); } while (0)
; #define PG8_LDA(dst, b, h) do { _Pragma("unroll") for (int m = 0; m < 4; ++m) _Pragma("unroll") for (int k = 0; k < 2; ++k) dst[m][k] = *(const PG8_LAS bf16x8*)(lds + PG8_SA(b, h) + aoff + m * 2048 + k * 1024); } while (0)
; #define PG8_LDB(dst, b, h) do { _Pragma("unroll") for (int n = 0; n < 2; ++n) _Pragma("unroll") for (int k = 0; k < 2; ++k) dst[n][k] = *(const PG8_LAS bf16x8*)(lds + PG8_SB(b, h) + boff + n * 2048 + k * 1024); } while (0)
; #define PG8_MMA(ai, bj, At, Bt) do { __builtin_amdgcn_s_setprio(1); _Pragma("unroll") for (int m = 0; m < 4; ++m) _Pragma("unroll") for (int n = 0; n < 2; ++n) _Pragma("unroll") for (int k = 0; k < 2; ++k) \
;         acc[ai][bj][m][n] = __builtin_amdgcn_mfma_f32_16x16x32_bf16(Bt[n][k], At[m][k], acc[ai][bj][m][n], 0, 0, 0); __builtin_amdgcn_s_setprio(0); } while (0)
; #define PG8_WAIT_V(n) asm volatile("s_waitcnt vmcnt(" #n ")" ::: "memory")
; #define PG8_WAIT_L(n) asm volatile("s_waitcnt lgkmcnt(" #n ")" ::: "memory")
; #define PG8_BAR __builtin_amdgcn_s_barrier()
; #define PG8_SCHED __builtin_amdgcn_sched_barrier(0)
; template <class Epi, class Sched, bool ALIGN_EPI = false, bool SP2 = false>
; __device__ __forceinline__ void gemm_phase(PG8_LAS unsigned char* lds, const Gemm g, const Sched& S, const Epi& E) {
;     ...
;         for (int t = 0; t < nt; t += 2) {
;             const bool last = (t == nt - 2);
;             const char* a1 = cA + (size_t)(t + 1) * kstep;
;             const char* a2 = last ? nA : cA + (size_t)(t + 2) * kstep; const char* b2 = last ? nB : cB + (size_t)(t + 2) * kstep;
;     ...
;             PG8_LDB(B0, 1, 0); PG8_LDB(B1, 1, 1); PG8_SCHED; PG8_LDA(At, 1, 0); PG8_STAGE(PG8_SA(0, 1), a2 + hstep, voffA);
;             PG8_WAIT_V(8); PG8_WAIT_L(0); PG8_BAR; PG8_MMA(0, 0, At, B0); PG8_MMA(0, 1, At, B1); PG8_BAR; PG8_SCHED;
;             PG8_LDA(At, 1, 1); PG8_STAGE(PG8_SB(1, 0), b3, voffB); PG8_STAGE(PG8_SB(1, 1), b3 + hstep, voffB); PG8_STAGE(PG8_SA(1, 0), a3, voffA);
;             PG8_WAIT_V(8); PG8_WAIT_L(0); PG8_BAR; PG8_MMA(1, 0, At, B0); PG8_MMA(1, 1, At, B1); PG8_BAR; PG8_SCHED;
	ds_read_b128 v[128:131], v169
	ds_read_b128 v[132:135], v170
	ds_read_b128 v[152:155], v171
	ds_read_b128 v[180:183], v172
	ds_read_b128 v[186:189], v173
	ds_read_b128 v[190:193], v174
	ds_read_b128 v[194:197], v175
	ds_read_b128 v[198:201], v176
	s_add_u32 s50, s50, 0x40000
	s_addc_u32 s51, s51, 0
	s_mov_b32 m0, s59
	v_lshl_add_u64 v[240:241], s[50:51], 0, v[136:137]
	ds_read_b128 v[202:205], v159 offset:32768
	ds_read_b128 v[206:209], v159 offset:33792
	ds_read_b128 v[210:213], v159 offset:34816
	ds_read_b128 v[214:217], v159 offset:35840
	ds_read_b128 v[218:221], v159 offset:36864
	ds_read_b128 v[222:225], v159 offset:37888
	ds_read_b128 v[226:229], v159 offset:38912
	ds_read_b128 v[230:233], v159 offset:39936
	global_load_lds_dwordx4 v[240:241], off
	v_lshl_add_u64 v[240:241], s[50:51], 0, v[140:141]
	s_mov_b32 m0, s60
	s_nop 0
	global_load_lds_dwordx4 v[240:241], off
	s_waitcnt vmcnt(8)
	s_waitcnt lgkmcnt(0)
	s_barrier
	s_waitcnt lgkmcnt(0)
	v_mfma_f32_16x16x32_bf16 v[124:127], v[128:131], v[202:205], v[124:127]
	v_mfma_f32_16x16x32_bf16 v[120:123], v[152:155], v[202:205], v[120:123]
	v_mfma_f32_16x16x32_bf16 v[108:111], v[128:131], v[210:213], v[108:111]
	v_mfma_f32_16x16x32_bf16 v[104:107], v[152:155], v[210:213], v[104:107]
	v_mfma_f32_16x16x32_bf16 v[92:95], v[128:131], v[218:221], v[92:95]
	v_mfma_f32_16x16x32_bf16 v[88:91], v[152:155], v[218:221], v[88:91]
	v_mfma_f32_16x16x32_bf16 v[76:79], v[128:131], v[226:229], v[76:79]
	v_mfma_f32_16x16x32_bf16 v[72:75], v[152:155], v[226:229], v[72:75]
	v_mfma_f32_16x16x32_bf16 v[124:127], v[132:135], v[206:209], v[124:127]
	v_mfma_f32_16x16x32_bf16 v[120:123], v[180:183], v[206:209], v[120:123]
	v_mfma_f32_16x16x32_bf16 v[108:111], v[132:135], v[214:217], v[108:111]
	v_mfma_f32_16x16x32_bf16 v[104:107], v[180:183], v[214:217], v[104:107]
	v_mfma_f32_16x16x32_bf16 v[92:95], v[132:135], v[222:225], v[92:95]
	v_mfma_f32_16x16x32_bf16 v[88:91], v[180:183], v[222:225], v[88:91]
	v_mfma_f32_16x16x32_bf16 v[76:79], v[132:135], v[230:233], v[76:79]
	v_mfma_f32_16x16x32_bf16 v[72:75], v[180:183], v[230:233], v[72:75]
	v_mfma_f32_16x16x32_bf16 v[116:119], v[186:189], v[202:205], v[116:119]
	v_mfma_f32_16x16x32_bf16 v[112:115], v[194:197], v[202:205], v[112:115]
	v_mfma_f32_16x16x32_bf16 v[100:103], v[186:189], v[210:213], v[100:103]
	v_mfma_f32_16x16x32_bf16 v[96:99], v[194:197], v[210:213], v[96:99]
	v_mfma_f32_16x16x32_bf16 v[84:87], v[186:189], v[218:221], v[84:87]
	v_mfma_f32_16x16x32_bf16 v[80:83], v[194:197], v[218:221], v[80:83]
	v_mfma_f32_16x16x32_bf16 v[68:71], v[186:189], v[226:229], v[68:71]
	v_mfma_f32_16x16x32_bf16 v[64:67], v[194:197], v[226:229], v[64:67]
	v_mfma_f32_16x16x32_bf16 v[116:119], v[190:193], v[206:209], v[116:119]
	v_mfma_f32_16x16x32_bf16 v[112:115], v[198:201], v[206:209], v[112:115]
	v_mfma_f32_16x16x32_bf16 v[100:103], v[190:193], v[214:217], v[100:103]
	v_mfma_f32_16x16x32_bf16 v[96:99], v[198:201], v[214:217], v[96:99]
	v_mfma_f32_16x16x32_bf16 v[84:87], v[190:193], v[222:225], v[84:87]
	v_mfma_f32_16x16x32_bf16 v[80:83], v[198:201], v[222:225], v[80:83]
	v_mfma_f32_16x16x32_bf16 v[68:71], v[190:193], v[230:233], v[68:71]
	v_mfma_f32_16x16x32_bf16 v[64:67], v[198:201], v[230:233], v[64:67]
	s_barrier
	s_mov_b32 m0, s62
	v_lshl_add_u64 v[156:157], v[156:157], 0, s[28:29]
	s_add_u32 s48, s48, 0x40080
	ds_read_b128 v[202:205], v159 offset:49152
	ds_read_b128 v[206:209], v159 offset:50176
	ds_read_b128 v[210:213], v159 offset:51200
	ds_read_b128 v[214:217], v159 offset:52224
	ds_read_b128 v[218:221], v159 offset:53248
	ds_read_b128 v[222:225], v159 offset:54272
	ds_read_b128 v[226:229], v159 offset:55296
	ds_read_b128 v[230:233], v159 offset:56320
	global_load_lds_dwordx4 v[156:157], off
	v_lshl_add_u64 v[156:157], v[234:235], 0, s[28:29]
	s_mov_b32 m0, s63
	s_addc_u32 s49, s49, 0
	global_load_lds_dwordx4 v[156:157], off
	v_lshl_add_u64 v[156:157], s[48:49], 0, v[138:139]
	s_mov_b32 m0, s66
	s_nop 0
	global_load_lds_dwordx4 v[156:157], off
	v_lshl_add_u64 v[156:157], s[48:49], 0, v[142:143]
	s_mov_b32 m0, s67
	s_nop 0
	global_load_lds_dwordx4 v[156:157], off
	v_lshl_add_u64 v[156:157], v[236:237], 0, s[28:29]
	s_mov_b32 m0, s64
	s_nop 0
	global_load_lds_dwordx4 v[156:157], off
	v_lshl_add_u64 v[156:157], v[238:239], 0, s[28:29]
	s_mov_b32 m0, s65
	s_nop 0
	global_load_lds_dwordx4 v[156:157], off
	s_waitcnt vmcnt(8)
	s_waitcnt lgkmcnt(0)
	s_barrier
	s_waitcnt lgkmcnt(0)
	v_mfma_f32_16x16x32_bf16 v[60:63], v[128:131], v[202:205], v[60:63]
	v_mfma_f32_16x16x32_bf16 v[56:59], v[152:155], v[202:205], v[56:59]
	v_mfma_f32_16x16x32_bf16 v[44:47], v[128:131], v[210:213], v[44:47]
	v_mfma_f32_16x16x32_bf16 v[40:43], v[152:155], v[210:213], v[40:43]
	v_mfma_f32_16x16x32_bf16 v[28:31], v[128:131], v[218:221], v[28:31]
	v_mfma_f32_16x16x32_bf16 v[24:27], v[152:155], v[218:221], v[24:27]
	v_mfma_f32_16x16x32_bf16 v[12:15], v[128:131], v[226:229], v[12:15]
	v_mfma_f32_16x16x32_bf16 v[8:11], v[152:155], v[226:229], v[8:11]
	v_mfma_f32_16x16x32_bf16 v[60:63], v[132:135], v[206:209], v[60:63]
	v_mfma_f32_16x16x32_bf16 v[56:59], v[180:183], v[206:209], v[56:59]
	v_mfma_f32_16x16x32_bf16 v[44:47], v[132:135], v[214:217], v[44:47]
	v_mfma_f32_16x16x32_bf16 v[40:43], v[180:183], v[214:217], v[40:43]
	v_mfma_f32_16x16x32_bf16 v[28:31], v[132:135], v[222:225], v[28:31]
	v_mfma_f32_16x16x32_bf16 v[24:27], v[180:183], v[222:225], v[24:27]
	v_mfma_f32_16x16x32_bf16 v[12:15], v[132:135], v[230:233], v[12:15]
	v_mfma_f32_16x16x32_bf16 v[8:11], v[180:183], v[230:233], v[8:11]
	v_mfma_f32_16x16x32_bf16 v[52:55], v[186:189], v[202:205], v[52:55]
	v_mfma_f32_16x16x32_bf16 v[48:51], v[194:197], v[202:205], v[48:51]
	v_mfma_f32_16x16x32_bf16 v[36:39], v[186:189], v[210:213], v[36:39]
	v_mfma_f32_16x16x32_bf16 v[32:35], v[194:197], v[210:213], v[32:35]
	v_mfma_f32_16x16x32_bf16 v[20:23], v[186:189], v[218:221], v[20:23]
	v_mfma_f32_16x16x32_bf16 v[16:19], v[194:197], v[218:221], v[16:19]
	v_mfma_f32_16x16x32_bf16 v[4:7], v[186:189], v[226:229], v[4:7]
	v_mfma_f32_16x16x32_bf16 v[0:3], v[194:197], v[226:229], v[0:3]
	v_mfma_f32_16x16x32_bf16 v[52:55], v[190:193], v[206:209], v[52:55]
	v_mfma_f32_16x16x32_bf16 v[48:51], v[198:201], v[206:209], v[48:51]
	v_mfma_f32_16x16x32_bf16 v[36:39], v[190:193], v[214:217], v[36:39]
	v_mfma_f32_16x16x32_bf16 v[32:35], v[198:201], v[214:217], v[32:35]
	v_mfma_f32_16x16x32_bf16 v[20:23], v[190:193], v[222:225], v[20:23]
	v_mfma_f32_16x16x32_bf16 v[16:19], v[198:201], v[222:225], v[16:19]
	v_mfma_f32_16x16x32_bf16 v[4:7], v[190:193], v[230:233], v[4:7]
	v_mfma_f32_16x16x32_bf16 v[0:3], v[198:201], v[230:233], v[0:3]
	s_add_i32 s75, s75, 2
	s_add_u32 s43, s43, 0x100
	s_addc_u32 s74, s74, 0
	s_add_u32 s12, s12, 0x100
	s_addc_u32 s13, s13, 0
	s_cmp_gt_u32 s75, 13
	s_barrier
	s_cbranch_scc0 .LBB0_1744
	s_and_b64 vcc, exec, s[30:31]
	s_cbranch_vccz .LBB0_1747
	s_barrier
